# v11: + system-scope (write-through) global stores so the grid-barrier release has less to flush
# speedup vs baseline: 1.0372x; 1.0035x over previous
.LBB0_14:
	v_ashrrev_i32_e32 v0, 12, v0
	v_add_u32_e32 v0, 1, v0
	v_cndmask_b32_e64 v0, v0, 0, s[8:9]
	s_load_dwordx2 s[8:9], s[0:1], 0xe8
	s_mul_i32 s10, s74, 9
	v_add_u32_e32 v0, s10, v0
	v_mov_b32_e32 v121, v1
	v_mov_b32_e32 v123, v1
	s_waitcnt lgkmcnt(0)
	v_lshl_add_u64 v[68:69], s[8:9], 0, v[70:71]
	s_load_dwordx2 s[8:9], s[0:1], 0x188
	s_mov_b64 s[24:25], -1
	s_waitcnt lgkmcnt(0)
	v_mov_b64_e32 v[70:71], s[8:9]
	v_mad_i64_i32 v[70:71], s[8:9], v0, s87, v[70:71]
	v_lshl_add_u64 v[70:71], s[22:23], 2, v[70:71]
	v_lshl_add_u64 v[70:71], v[70:71], 0, v[120:121]
	v_lshl_add_u64 v[70:71], v[70:71], 0, v[122:123]
	s_mov_b64 s[8:9], 0x2000
	v_lshl_add_u64 v[72:73], v[70:71], 0, s[8:9]
	s_movk_i32 s8, 0x2000
	v_add_co_u32_e32 v70, vcc, s8, v70
	s_nop 1
	v_addc_co_u32_e32 v71, vcc, 0, v71, vcc
	global_load_dword v0, v[70:71], off
	s_nop 0
	global_load_dword v72, v[72:73], off offset:64
	v_mov_b32_e32 v71, s23
	v_or_b32_e32 v70, s22, v86
	s_and_b64 vcc, exec, s[20:21]
	s_waitcnt vmcnt(0)
	v_mul_f32_e32 v62, v62, v0
	v_mul_f32_e32 v58, v58, v72
	ds_write2_b32 v136, v62, v58 offset1:16
	v_mul_f32_e32 v58, v63, v0
	v_mul_f32_e32 v59, v59, v72
	ds_write2_b32 v136, v58, v59 offset0:36 offset1:52
	v_mul_f32_e32 v58, v64, v0
	v_mul_f32_e32 v59, v60, v72
	ds_write2_b32 v136, v58, v59 offset0:72 offset1:88
	v_mul_f32_e32 v58, v65, v0
	v_mul_f32_e32 v59, v61, v72
	ds_write2_b32 v136, v58, v59 offset0:108 offset1:124
	v_mul_f32_e32 v54, v54, v0
	v_mul_f32_e32 v58, v50, v72
	v_add_u32_e32 v50, 0x800, v136
	ds_write2_b32 v50, v54, v58 offset0:64 offset1:80
	v_mul_f32_e32 v54, v55, v0
	v_mul_f32_e32 v51, v51, v72
	ds_write2_b32 v50, v54, v51 offset0:100 offset1:116
	v_mul_f32_e32 v51, v56, v0
	v_mul_f32_e32 v52, v52, v72
	ds_write2_b32 v50, v51, v52 offset0:136 offset1:152
	v_mul_f32_e32 v51, v57, v0
	v_mul_f32_e32 v52, v53, v72
	v_lshl_add_u64 v[56:57], v[70:71], 0, v[88:89]
	ds_write2_b32 v50, v51, v52 offset0:172 offset1:188
	v_lshlrev_b64 v[60:61], 2, v[56:57]
	s_waitcnt lgkmcnt(0)
	v_lshl_add_u64 v[56:57], v[66:67], 0, v[60:61]
	global_load_dwordx4 v[56:59], v[56:57], off
	ds_read_b128 v[52:55], v137
	v_mul_f32_e32 v46, v46, v0
	v_mul_f32_e32 v42, v42, v72
	v_mul_f32_e32 v38, v38, v0
	v_mul_f32_e32 v34, v34, v72
	v_mul_f32_e32 v43, v43, v72
	v_mul_f32_e32 v35, v35, v72
	v_mul_f32_e32 v30, v30, v0
	v_mul_f32_e32 v26, v26, v72
	v_mul_f32_e32 v22, v22, v0
	v_mul_f32_e32 v18, v18, v72
	v_mul_f32_e32 v27, v27, v72
	v_mul_f32_e32 v19, v19, v72
	v_mul_f32_e32 v14, v14, v0
	v_mul_f32_e32 v10, v10, v72
	v_mul_f32_e32 v6, v6, v0
	v_mul_f32_e32 v2, v2, v72
	v_mul_f32_e32 v11, v11, v72
	v_mul_f32_e32 v3, v3, v72
	s_waitcnt vmcnt(0) lgkmcnt(0)
	v_pk_fma_f32 v[54:55], v[58:59], s[98:99], v[54:55] op_sel_hi:[1,0,1]
	v_pk_fma_f32 v[52:53], v[56:57], s[98:99], v[52:53] op_sel_hi:[1,0,1]
	v_lshl_add_u64 v[56:57], v[68:69], 0, v[60:61]
	global_store_dwordx4 v[56:57], v[52:55], off sc0 sc1
	v_lshl_add_u64 v[56:57], v[70:71], 0, v[90:91]
	v_lshlrev_b64 v[60:61], 2, v[56:57]
	v_lshl_add_u64 v[56:57], v[66:67], 0, v[60:61]
	global_load_dwordx4 v[56:59], v[56:57], off
	ds_read_b128 v[52:55], v138
	s_waitcnt vmcnt(0) lgkmcnt(0)
	v_pk_fma_f32 v[54:55], v[58:59], s[98:99], v[54:55] op_sel_hi:[1,0,1]
	v_pk_fma_f32 v[52:53], v[56:57], s[98:99], v[52:53] op_sel_hi:[1,0,1]
	v_lshl_add_u64 v[56:57], v[68:69], 0, v[60:61]
	global_store_dwordx4 v[56:57], v[52:55], off sc0 sc1
	v_lshl_add_u64 v[56:57], v[70:71], 0, v[92:93]
	v_lshlrev_b64 v[60:61], 2, v[56:57]
	v_lshl_add_u64 v[56:57], v[66:67], 0, v[60:61]
	global_load_dwordx4 v[56:59], v[56:57], off
	ds_read_b128 v[52:55], v139
	s_waitcnt vmcnt(0) lgkmcnt(0)
	v_pk_fma_f32 v[54:55], v[58:59], s[98:99], v[54:55] op_sel_hi:[1,0,1]
	v_pk_fma_f32 v[52:53], v[56:57], s[98:99], v[52:53] op_sel_hi:[1,0,1]
	v_lshl_add_u64 v[56:57], v[68:69], 0, v[60:61]
	global_store_dwordx4 v[56:57], v[52:55], off sc0 sc1
	v_lshl_add_u64 v[56:57], v[70:71], 0, v[94:95]
	v_lshlrev_b64 v[60:61], 2, v[56:57]
	v_lshl_add_u64 v[56:57], v[66:67], 0, v[60:61]
	global_load_dwordx4 v[56:59], v[56:57], off
	ds_read_b128 v[52:55], v140
	s_waitcnt vmcnt(0) lgkmcnt(0)
	v_pk_fma_f32 v[54:55], v[58:59], s[98:99], v[54:55] op_sel_hi:[1,0,1]
	v_pk_fma_f32 v[52:53], v[56:57], s[98:99], v[52:53] op_sel_hi:[1,0,1]
	v_lshl_add_u64 v[56:57], v[68:69], 0, v[60:61]
	global_store_dwordx4 v[56:57], v[52:55], off sc0 sc1
	s_waitcnt lgkmcnt(0)
	ds_write2_b32 v136, v46, v42 offset1:16
	v_mul_f32_e32 v42, v47, v0
	ds_write2_b32 v50, v38, v34 offset0:64 offset1:80
	v_mul_f32_e32 v34, v39, v0
	ds_write2_b32 v136, v42, v43 offset0:36 offset1:52
	v_mul_f32_e32 v42, v48, v0
	v_mul_f32_e32 v43, v44, v72
	ds_write2_b32 v50, v34, v35 offset0:100 offset1:116
	v_mul_f32_e32 v34, v40, v0
	v_mul_f32_e32 v35, v36, v72
	ds_write2_b32 v136, v42, v43 offset0:72 offset1:88
	v_mul_f32_e32 v42, v49, v0
	v_mul_f32_e32 v43, v45, v72
	ds_write2_b32 v50, v34, v35 offset0:136 offset1:152
	v_mul_f32_e32 v34, v41, v0
	v_mul_f32_e32 v35, v37, v72
	v_lshl_add_u64 v[38:39], v[70:71], 0, v[96:97]
	ds_write2_b32 v136, v42, v43 offset0:108 offset1:124
	ds_write2_b32 v50, v34, v35 offset0:172 offset1:188
	v_lshlrev_b64 v[42:43], 2, v[38:39]
	s_waitcnt lgkmcnt(0)
	v_lshl_add_u64 v[38:39], v[66:67], 0, v[42:43]
	global_load_dwordx4 v[38:41], v[38:39], off
	ds_read_b128 v[34:37], v137
	s_waitcnt vmcnt(0) lgkmcnt(0)
	v_pk_fma_f32 v[36:37], v[40:41], s[98:99], v[36:37] op_sel_hi:[1,0,1]
	v_pk_fma_f32 v[34:35], v[38:39], s[98:99], v[34:35] op_sel_hi:[1,0,1]
	v_lshl_add_u64 v[38:39], v[68:69], 0, v[42:43]
	global_store_dwordx4 v[38:39], v[34:37], off sc0 sc1
	v_lshl_add_u64 v[38:39], v[70:71], 0, v[98:99]
	v_lshlrev_b64 v[42:43], 2, v[38:39]
	v_lshl_add_u64 v[38:39], v[66:67], 0, v[42:43]
	global_load_dwordx4 v[38:41], v[38:39], off
	ds_read_b128 v[34:37], v138
	s_waitcnt vmcnt(0) lgkmcnt(0)
	v_pk_fma_f32 v[36:37], v[40:41], s[98:99], v[36:37] op_sel_hi:[1,0,1]
	v_pk_fma_f32 v[34:35], v[38:39], s[98:99], v[34:35] op_sel_hi:[1,0,1]
	v_lshl_add_u64 v[38:39], v[68:69], 0, v[42:43]
	global_store_dwordx4 v[38:39], v[34:37], off sc0 sc1
	v_lshl_add_u64 v[38:39], v[70:71], 0, v[100:101]
	v_lshlrev_b64 v[42:43], 2, v[38:39]
	v_lshl_add_u64 v[38:39], v[66:67], 0, v[42:43]
	global_load_dwordx4 v[38:41], v[38:39], off
	ds_read_b128 v[34:37], v139
	s_waitcnt vmcnt(0) lgkmcnt(0)
	v_pk_fma_f32 v[36:37], v[40:41], s[98:99], v[36:37] op_sel_hi:[1,0,1]
	v_pk_fma_f32 v[34:35], v[38:39], s[98:99], v[34:35] op_sel_hi:[1,0,1]
	v_lshl_add_u64 v[38:39], v[68:69], 0, v[42:43]
	global_store_dwordx4 v[38:39], v[34:37], off sc0 sc1
	v_lshl_add_u64 v[38:39], v[70:71], 0, v[102:103]
	v_lshlrev_b64 v[42:43], 2, v[38:39]
	v_lshl_add_u64 v[38:39], v[66:67], 0, v[42:43]
	global_load_dwordx4 v[38:41], v[38:39], off
	ds_read_b128 v[34:37], v140
	s_waitcnt vmcnt(0) lgkmcnt(0)
	v_pk_fma_f32 v[36:37], v[40:41], s[98:99], v[36:37] op_sel_hi:[1,0,1]
	v_pk_fma_f32 v[34:35], v[38:39], s[98:99], v[34:35] op_sel_hi:[1,0,1]
	v_lshl_add_u64 v[38:39], v[68:69], 0, v[42:43]
	global_store_dwordx4 v[38:39], v[34:37], off sc0 sc1
	s_waitcnt lgkmcnt(0)
	ds_write2_b32 v136, v30, v26 offset1:16
	v_mul_f32_e32 v26, v31, v0
	ds_write2_b32 v50, v22, v18 offset0:64 offset1:80
	v_mul_f32_e32 v18, v23, v0
	ds_write2_b32 v136, v26, v27 offset0:36 offset1:52
	v_mul_f32_e32 v26, v32, v0
	v_mul_f32_e32 v27, v28, v72
	ds_write2_b32 v50, v18, v19 offset0:100 offset1:116
	v_mul_f32_e32 v18, v24, v0
	v_mul_f32_e32 v19, v20, v72
	ds_write2_b32 v136, v26, v27 offset0:72 offset1:88
	v_mul_f32_e32 v26, v33, v0
	v_mul_f32_e32 v27, v29, v72
	ds_write2_b32 v50, v18, v19 offset0:136 offset1:152
	v_mul_f32_e32 v18, v25, v0
	v_mul_f32_e32 v19, v21, v72
	v_lshl_add_u64 v[22:23], v[70:71], 0, v[104:105]
	ds_write2_b32 v136, v26, v27 offset0:108 offset1:124
	ds_write2_b32 v50, v18, v19 offset0:172 offset1:188
	v_lshlrev_b64 v[26:27], 2, v[22:23]
	s_waitcnt lgkmcnt(0)
	v_lshl_add_u64 v[22:23], v[66:67], 0, v[26:27]
	global_load_dwordx4 v[22:25], v[22:23], off
	ds_read_b128 v[18:21], v137
	s_waitcnt vmcnt(0) lgkmcnt(0)
	v_pk_fma_f32 v[20:21], v[24:25], s[98:99], v[20:21] op_sel_hi:[1,0,1]
	v_pk_fma_f32 v[18:19], v[22:23], s[98:99], v[18:19] op_sel_hi:[1,0,1]
	v_lshl_add_u64 v[22:23], v[68:69], 0, v[26:27]
	global_store_dwordx4 v[22:23], v[18:21], off sc0 sc1
	v_lshl_add_u64 v[22:23], v[70:71], 0, v[106:107]
	v_lshlrev_b64 v[26:27], 2, v[22:23]
	v_lshl_add_u64 v[22:23], v[66:67], 0, v[26:27]
	global_load_dwordx4 v[22:25], v[22:23], off
	ds_read_b128 v[18:21], v138
	s_waitcnt vmcnt(0) lgkmcnt(0)
	v_pk_fma_f32 v[20:21], v[24:25], s[98:99], v[20:21] op_sel_hi:[1,0,1]
	v_pk_fma_f32 v[18:19], v[22:23], s[98:99], v[18:19] op_sel_hi:[1,0,1]
	v_lshl_add_u64 v[22:23], v[68:69], 0, v[26:27]
	global_store_dwordx4 v[22:23], v[18:21], off sc0 sc1
	v_lshl_add_u64 v[22:23], v[70:71], 0, v[108:109]
	v_lshlrev_b64 v[26:27], 2, v[22:23]
	v_lshl_add_u64 v[22:23], v[66:67], 0, v[26:27]
	global_load_dwordx4 v[22:25], v[22:23], off
	ds_read_b128 v[18:21], v139
	s_waitcnt vmcnt(0) lgkmcnt(0)
	v_pk_fma_f32 v[20:21], v[24:25], s[98:99], v[20:21] op_sel_hi:[1,0,1]
	v_pk_fma_f32 v[18:19], v[22:23], s[98:99], v[18:19] op_sel_hi:[1,0,1]
	v_lshl_add_u64 v[22:23], v[68:69], 0, v[26:27]
	global_store_dwordx4 v[22:23], v[18:21], off sc0 sc1
	v_lshl_add_u64 v[22:23], v[70:71], 0, v[110:111]
	v_lshlrev_b64 v[26:27], 2, v[22:23]
	v_lshl_add_u64 v[22:23], v[66:67], 0, v[26:27]
	global_load_dwordx4 v[22:25], v[22:23], off
	ds_read_b128 v[18:21], v140
	s_waitcnt vmcnt(0) lgkmcnt(0)
	v_pk_fma_f32 v[20:21], v[24:25], s[98:99], v[20:21] op_sel_hi:[1,0,1]
	v_pk_fma_f32 v[18:19], v[22:23], s[98:99], v[18:19] op_sel_hi:[1,0,1]
	v_lshl_add_u64 v[22:23], v[68:69], 0, v[26:27]
	global_store_dwordx4 v[22:23], v[18:21], off sc0 sc1
	s_waitcnt lgkmcnt(0)
	ds_write2_b32 v136, v14, v10 offset1:16
	v_mul_f32_e32 v10, v15, v0
	ds_write2_b32 v50, v6, v2 offset0:64 offset1:80
	v_mul_f32_e32 v2, v7, v0
	ds_write2_b32 v136, v10, v11 offset0:36 offset1:52
	v_mul_f32_e32 v10, v16, v0
	v_mul_f32_e32 v11, v12, v72
	ds_write2_b32 v50, v2, v3 offset0:100 offset1:116
	v_mul_f32_e32 v2, v8, v0
	v_mul_f32_e32 v3, v4, v72
	ds_write2_b32 v136, v10, v11 offset0:72 offset1:88
	v_mul_f32_e32 v10, v17, v0
	v_mul_f32_e32 v11, v13, v72
	ds_write2_b32 v50, v2, v3 offset0:136 offset1:152
	v_mul_f32_e32 v0, v9, v0
	v_mul_f32_e32 v2, v5, v72
	v_lshl_add_u64 v[6:7], v[70:71], 0, v[112:113]
	ds_write2_b32 v136, v10, v11 offset0:108 offset1:124
	ds_write2_b32 v50, v0, v2 offset0:172 offset1:188
	v_lshlrev_b64 v[10:11], 2, v[6:7]
	s_waitcnt lgkmcnt(0)
	v_lshl_add_u64 v[6:7], v[66:67], 0, v[10:11]
	global_load_dwordx4 v[6:9], v[6:7], off
	ds_read_b128 v[2:5], v137
	s_waitcnt vmcnt(0) lgkmcnt(0)
	v_pk_fma_f32 v[4:5], v[8:9], s[98:99], v[4:5] op_sel_hi:[1,0,1]
	v_pk_fma_f32 v[2:3], v[6:7], s[98:99], v[2:3] op_sel_hi:[1,0,1]
	v_lshl_add_u64 v[6:7], v[68:69], 0, v[10:11]
	global_store_dwordx4 v[6:7], v[2:5], off sc0 sc1
	v_lshl_add_u64 v[6:7], v[70:71], 0, v[114:115]
	v_lshlrev_b64 v[10:11], 2, v[6:7]
	v_lshl_add_u64 v[6:7], v[66:67], 0, v[10:11]
	global_load_dwordx4 v[6:9], v[6:7], off
	ds_read_b128 v[2:5], v138
	s_waitcnt vmcnt(0) lgkmcnt(0)
	v_pk_fma_f32 v[4:5], v[8:9], s[98:99], v[4:5] op_sel_hi:[1,0,1]
	v_pk_fma_f32 v[2:3], v[6:7], s[98:99], v[2:3] op_sel_hi:[1,0,1]
	v_lshl_add_u64 v[6:7], v[68:69], 0, v[10:11]
	global_store_dwordx4 v[6:7], v[2:5], off sc0 sc1
	v_lshl_add_u64 v[6:7], v[70:71], 0, v[116:117]
	v_lshlrev_b64 v[10:11], 2, v[6:7]
	v_lshl_add_u64 v[6:7], v[66:67], 0, v[10:11]
	global_load_dwordx4 v[6:9], v[6:7], off
	ds_read_b128 v[2:5], v139
	s_waitcnt vmcnt(0) lgkmcnt(0)
	v_pk_fma_f32 v[4:5], v[8:9], s[98:99], v[4:5] op_sel_hi:[1,0,1]
	v_pk_fma_f32 v[2:3], v[6:7], s[98:99], v[2:3] op_sel_hi:[1,0,1]
	v_lshl_add_u64 v[6:7], v[68:69], 0, v[10:11]
	global_store_dwordx4 v[6:7], v[2:5], off sc0 sc1
	v_lshl_add_u64 v[6:7], v[70:71], 0, v[118:119]
	v_lshlrev_b64 v[10:11], 2, v[6:7]
	v_lshl_add_u64 v[6:7], v[66:67], 0, v[10:11]
	global_load_dwordx4 v[6:9], v[6:7], off
	ds_read_b128 v[2:5], v140
	s_waitcnt vmcnt(0) lgkmcnt(0)
	v_pk_fma_f32 v[4:5], v[8:9], s[98:99], v[4:5] op_sel_hi:[1,0,1]
	v_pk_fma_f32 v[2:3], v[6:7], s[98:99], v[2:3] op_sel_hi:[1,0,1]
	v_lshl_add_u64 v[6:7], v[68:69], 0, v[10:11]
	global_store_dwordx4 v[6:7], v[2:5], off sc0 sc1
	s_waitcnt lgkmcnt(0)
	s_cbranch_vccnz .LBB0_45

.LBB0_49:
	v_mov_b32_e32 v4, v226
	s_movk_i32 s6, 0x1400
	v_lshrrev_b32_e32 v0, 6, v4
	v_mul_lo_u32 v0, v0, s6
	v_add_u32_e32 v6, 0x18000, v0
	s_load_dwordx2 s[6:7], s[0:1], 0x150
	v_ashrrev_i32_e32 v0, 1, v4
	v_and_b32_e32 v0, 0xffffff80, v0
	v_add_u32_e32 v2, s59, v0
	v_ashrrev_i32_e32 v3, 31, v2
	v_lshlrev_b64 v[2:3], 11, v[2:3]
	s_waitcnt lgkmcnt(0)
	v_lshl_add_u64 v[2:3], s[6:7], 0, v[2:3]
	v_lshl_add_u64 v[2:3], s[24:25], 1, v[2:3]
	v_and_b32_e32 v0, 0xc0, v4
	v_lshl_add_u64 v[2:3], v[2:3], 0, v[0:1]
	v_lshrrev_b32_e32 v0, 2, v4
	v_and_b32_e32 v7, 12, v0
	v_lshlrev_b32_e32 v0, 4, v4
	v_and_b32_e32 v5, 15, v4
	v_and_b32_e32 v0, 48, v0
	v_lshl_or_b32 v5, v5, 1, v6
	v_or_b32_e32 v17, v6, v0
	v_lshl_add_u64 v[10:11], v[2:3], 0, v[0:1]
	v_bfe_u32 v0, v4, 2, 4
	s_movk_i32 s6, 0x50
	v_mad_u32_u24 v18, v0, s6, v17
	v_cvt_pk_bf16_f32 v0, v206, s0
	v_mad_u32_u24 v19, v7, s6, v5
	ds_write_b16 v19, v0
	v_cvt_pk_bf16_f32 v0, v207, s0
	ds_write_b16 v19, v0 offset:80
	v_cvt_pk_bf16_f32 v0, v212, s0
	ds_write_b16 v19, v0 offset:160
	v_cvt_pk_bf16_f32 v0, v213, s0
	ds_write_b16 v19, v0 offset:240
	v_cvt_pk_bf16_f32 v0, v210, s0
	ds_write_b16 v19, v0 offset:32
	v_cvt_pk_bf16_f32 v0, v211, s0
	ds_write_b16 v19, v0 offset:112
	v_cvt_pk_bf16_f32 v0, v208, s0
	ds_write_b16 v19, v0 offset:192
	v_cvt_pk_bf16_f32 v0, v209, s0
	ds_write_b16 v19, v0 offset:272
	v_cvt_pk_bf16_f32 v0, v204, s0
	ds_write_b16 v19, v0 offset:1280
	v_cvt_pk_bf16_f32 v0, v205, s0
	ds_write_b16 v19, v0 offset:1360
	v_cvt_pk_bf16_f32 v0, v202, s0
	ds_write_b16 v19, v0 offset:1440
	v_cvt_pk_bf16_f32 v0, v203, s0
	ds_write_b16 v19, v0 offset:1520
	v_cvt_pk_bf16_f32 v0, v200, s0
	ds_write_b16 v19, v0 offset:1312
	v_cvt_pk_bf16_f32 v0, v201, s0
	ds_write_b16 v19, v0 offset:1392
	v_cvt_pk_bf16_f32 v0, v198, s0
	ds_write_b16 v19, v0 offset:1472
	v_cvt_pk_bf16_f32 v0, v199, s0
	ds_write_b16 v19, v0 offset:1552
	v_cvt_pk_bf16_f32 v0, v196, s0
	ds_write_b16 v19, v0 offset:2560
	v_cvt_pk_bf16_f32 v0, v197, s0
	ds_write_b16 v19, v0 offset:2640
	v_cvt_pk_bf16_f32 v0, v194, s0
	ds_write_b16 v19, v0 offset:2720
	v_cvt_pk_bf16_f32 v0, v195, s0
	ds_write_b16 v19, v0 offset:2800
	v_cvt_pk_bf16_f32 v0, v192, s0
	ds_write_b16 v19, v0 offset:2592
	v_cvt_pk_bf16_f32 v0, v193, s0
	ds_write_b16 v19, v0 offset:2672
	v_cvt_pk_bf16_f32 v0, v190, s0
	ds_write_b16 v19, v0 offset:2752
	v_cvt_pk_bf16_f32 v0, v191, s0
	ds_write_b16 v19, v0 offset:2832
	v_cvt_pk_bf16_f32 v0, v188, s0
	ds_write_b16 v19, v0 offset:3840
	v_cvt_pk_bf16_f32 v0, v189, s0
	ds_write_b16 v19, v0 offset:3920
	v_cvt_pk_bf16_f32 v0, v186, s0
	ds_write_b16 v19, v0 offset:4000
	v_cvt_pk_bf16_f32 v0, v187, s0
	ds_write_b16 v19, v0 offset:4080
	v_cvt_pk_bf16_f32 v0, v184, s0
	ds_write_b16 v19, v0 offset:3872
	v_cvt_pk_bf16_f32 v0, v185, s0
	v_and_b32_e32 v16, 60, v4
	ds_write_b16 v19, v0 offset:3952
	v_cvt_pk_bf16_f32 v0, v182, s0
	ds_write_b16 v19, v0 offset:4032
	v_cvt_pk_bf16_f32 v0, v183, s0
	v_or_b32_e32 v14, 64, v16
	ds_write_b16 v19, v0 offset:4112
	v_lshrrev_b32_e32 v6, 2, v14
	s_waitcnt lgkmcnt(0)
	v_mad_u32_u24 v20, v6, s6, v17
	ds_read_b128 v[2:5], v18
	ds_read_b128 v[6:9], v20
	v_lshlrev_b32_e32 v0, 9, v16
	v_lshl_add_u64 v[12:13], v[10:11], 0, v[0:1]
	v_lshlrev_b32_e32 v0, 9, v14
	v_lshl_add_u64 v[14:15], v[10:11], 0, v[0:1]
	v_or_b32_e32 v0, 0x80, v16
	v_or_b32_e32 v22, 0xc0, v16
	s_waitcnt lgkmcnt(1)
	global_store_dwordx4 v[12:13], v[2:5], off sc0 sc1
	s_waitcnt lgkmcnt(0)
	global_store_dwordx4 v[14:15], v[6:9], off sc0 sc1
	v_lshrrev_b32_e32 v2, 2, v0
	s_nop 0
	v_lshrrev_b32_e32 v6, 2, v22
	v_mad_u32_u24 v21, v2, s6, v17
	v_mad_u32_u24 v23, v6, s6, v17
	ds_read_b128 v[2:5], v21
	ds_read_b128 v[6:9], v23
	v_lshlrev_b32_e32 v0, 9, v0
	v_lshl_add_u64 v[16:17], v[10:11], 0, v[0:1]
	v_lshlrev_b32_e32 v0, 9, v22
	v_lshl_add_u64 v[10:11], v[10:11], 0, v[0:1]
	s_waitcnt lgkmcnt(1)
	global_store_dwordx4 v[16:17], v[2:5], off sc0 sc1
	s_waitcnt lgkmcnt(0)
	global_store_dwordx4 v[10:11], v[6:9], off sc0 sc1
	v_cvt_pk_bf16_f32 v0, v180, s0
	s_waitcnt lgkmcnt(0)
	ds_write_b16 v19, v0
	v_cvt_pk_bf16_f32 v0, v181, s0
	ds_write_b16 v19, v0 offset:80
	v_cvt_pk_bf16_f32 v0, v178, s0
	ds_write_b16 v19, v0 offset:160
	v_cvt_pk_bf16_f32 v0, v179, s0
	ds_write_b16 v19, v0 offset:240
	v_cvt_pk_bf16_f32 v0, v176, s0
	ds_write_b16 v19, v0 offset:32
	v_cvt_pk_bf16_f32 v0, v177, s0
	ds_write_b16 v19, v0 offset:112
	v_cvt_pk_bf16_f32 v0, v174, s0
	ds_write_b16 v19, v0 offset:192
	v_cvt_pk_bf16_f32 v0, v175, s0
	ds_write_b16 v19, v0 offset:272
	v_cvt_pk_bf16_f32 v0, v172, s0
	ds_write_b16 v19, v0 offset:1280
	v_cvt_pk_bf16_f32 v0, v173, s0
	ds_write_b16 v19, v0 offset:1360
	v_cvt_pk_bf16_f32 v0, v170, s0
	ds_write_b16 v19, v0 offset:1440
	v_cvt_pk_bf16_f32 v0, v171, s0
	ds_write_b16 v19, v0 offset:1520
	v_cvt_pk_bf16_f32 v0, v168, s0
	ds_write_b16 v19, v0 offset:1312
	v_cvt_pk_bf16_f32 v0, v169, s0
	ds_write_b16 v19, v0 offset:1392
	v_cvt_pk_bf16_f32 v0, v166, s0
	ds_write_b16 v19, v0 offset:1472
	v_cvt_pk_bf16_f32 v0, v167, s0
	ds_write_b16 v19, v0 offset:1552
	v_cvt_pk_bf16_f32 v0, v164, s0
	ds_write_b16 v19, v0 offset:2560
	v_cvt_pk_bf16_f32 v0, v165, s0
	ds_write_b16 v19, v0 offset:2640
	v_cvt_pk_bf16_f32 v0, v162, s0
	ds_write_b16 v19, v0 offset:2720
	v_cvt_pk_bf16_f32 v0, v163, s0
	ds_write_b16 v19, v0 offset:2800
	v_cvt_pk_bf16_f32 v0, v160, s0
	ds_write_b16 v19, v0 offset:2592
	v_cvt_pk_bf16_f32 v0, v161, s0
	ds_write_b16 v19, v0 offset:2672
	v_cvt_pk_bf16_f32 v0, v158, s0
	ds_write_b16 v19, v0 offset:2752
	v_cvt_pk_bf16_f32 v0, v159, s0
	ds_write_b16 v19, v0 offset:2832
	v_cvt_pk_bf16_f32 v0, v156, s0
	ds_write_b16 v19, v0 offset:3840
	v_cvt_pk_bf16_f32 v0, v157, s0
	ds_write_b16 v19, v0 offset:3920
	v_cvt_pk_bf16_f32 v0, v154, s0
	ds_write_b16 v19, v0 offset:4000
	v_cvt_pk_bf16_f32 v0, v155, s0
	ds_write_b16 v19, v0 offset:4080
	v_cvt_pk_bf16_f32 v0, v152, s0
	ds_write_b16 v19, v0 offset:3872
	v_cvt_pk_bf16_f32 v0, v153, s0
	ds_write_b16 v19, v0 offset:3952
	v_cvt_pk_bf16_f32 v0, v150, s0
	ds_write_b16 v19, v0 offset:4032
	v_cvt_pk_bf16_f32 v0, v151, s0
	ds_write_b16 v19, v0 offset:4112
	s_waitcnt lgkmcnt(0)
	ds_read_b128 v[2:5], v18
	ds_read_b128 v[6:9], v20
	s_mov_b32 s6, 0x20000
	v_add_co_u32_e32 v12, vcc, s6, v12
	s_nop 1
	v_addc_co_u32_e32 v13, vcc, 0, v13, vcc
	s_waitcnt lgkmcnt(1)
	global_store_dwordx4 v[12:13], v[2:5], off sc0 sc1
	s_nop 1
	v_add_co_u32_e32 v2, vcc, s6, v14
	s_nop 1
	v_addc_co_u32_e32 v3, vcc, 0, v15, vcc
	s_waitcnt lgkmcnt(0)
	global_store_dwordx4 v[2:3], v[6:9], off sc0 sc1
	ds_read_b128 v[2:5], v21
	ds_read_b128 v[6:9], v23
	v_add_co_u32_e32 v12, vcc, 0x20000, v16
	s_nop 1
	v_addc_co_u32_e32 v13, vcc, 0, v17, vcc
	s_waitcnt lgkmcnt(1)
	global_store_dwordx4 v[12:13], v[2:5], off sc0 sc1
	s_nop 1
	v_add_co_u32_e32 v2, vcc, 0x20000, v10
	s_nop 1
	v_addc_co_u32_e32 v3, vcc, 0, v11, vcc
	s_waitcnt lgkmcnt(0)
	global_store_dwordx4 v[2:3], v[6:9], off sc0 sc1
	s_waitcnt lgkmcnt(0)
	s_and_b64 vcc, exec, s[22:23]
	s_cbranch_vccnz .LBB0_103

.LBB0_109:
	s_or_b64 exec, exec, s[4:5]
	v_ashrrev_i32_e32 v4, 4, v195
	v_add_u32_e32 v14, s35, v4
	v_ashrrev_i32_e32 v15, 31, v14
	v_lshlrev_b64 v[2:3], 13, v[14:15]
	v_lshlrev_b32_e32 v0, 4, v195
	v_lshl_add_u64 v[2:3], s[28:29], 0, v[2:3]
	s_lshl_b32 s94, s36, 8
	v_and_b32_e32 v0, 0xf0, v0
	v_lshl_add_u64 v[2:3], v[2:3], 0, s[94:95]
	v_lshl_add_u64 v[2:3], v[2:3], 0, v[0:1]
	v_add_co_u32_e32 v2, vcc, s86, v2
	s_waitcnt lgkmcnt(0)
	s_nop 0
	v_addc_co_u32_e32 v3, vcc, 0, v3, vcc
	s_barrier
	global_load_dwordx4 v[6:9], v[2:3], off
	v_add_u32_e32 v2, 0x200, v195
	v_ashrrev_i32_e32 v3, 4, v2
	v_or_b32_e32 v2, 0x10000, v0
	s_movk_i32 s6, 0x108
	s_load_dwordx2 s[2:3], s[16:17], 0x158
	v_mad_u64_u32 v[4:5], s[4:5], v4, s6, v[2:3]
	ds_read2_b64 v[10:13], v4 offset1:1
	v_add_u32_e32 v16, s35, v3
	v_ashrrev_i32_e32 v17, 31, v16
	v_lshlrev_b64 v[18:19], 13, v[16:17]
	s_waitcnt lgkmcnt(0)
	v_mov_b64_e32 v[4:5], s[2:3]
	v_lshl_add_u64 v[18:19], s[28:29], 0, v[18:19]
	v_mad_i64_i32 v[14:15], s[2:3], v14, s92, v[4:5]
	v_lshl_add_u64 v[18:19], v[18:19], 0, s[94:95]
	v_lshlrev_b32_e32 v20, 16, v10
	v_and_b32_e32 v21, 0xffff0000, v10
	v_lshlrev_b32_e32 v10, 16, v11
	v_and_b32_e32 v11, 0xffff0000, v11
	v_lshlrev_b32_e32 v22, 16, v12
	v_and_b32_e32 v23, 0xffff0000, v12
	v_lshlrev_b32_e32 v12, 16, v13
	v_and_b32_e32 v13, 0xffff0000, v13
	v_lshl_add_u64 v[14:15], v[14:15], 0, s[94:95]
	v_lshl_add_u64 v[18:19], v[18:19], 0, v[0:1]
	v_lshl_add_u64 v[14:15], v[14:15], 0, v[0:1]
	v_add_co_u32_e32 v18, vcc, s86, v18
	v_mad_i64_i32 v[16:17], s[2:3], v16, s92, v[4:5]
	s_nop 0
	v_addc_co_u32_e32 v19, vcc, 0, v19, vcc
	v_lshl_add_u64 v[16:17], v[16:17], 0, s[94:95]
	v_lshl_add_u64 v[16:17], v[16:17], 0, v[0:1]
	s_add_i32 s34, s34, s99
	s_cmpk_lt_i32 s34, 0x200
	s_waitcnt vmcnt(0)
	v_lshlrev_b32_e32 v24, 16, v6
	v_and_b32_e32 v25, 0xffff0000, v6
	v_lshlrev_b32_e32 v6, 16, v7
	v_and_b32_e32 v7, 0xffff0000, v7
	v_lshlrev_b32_e32 v26, 16, v8
	v_and_b32_e32 v27, 0xffff0000, v8
	v_lshlrev_b32_e32 v8, 16, v9
	v_and_b32_e32 v9, 0xffff0000, v9
	v_pk_mul_f32 v[20:21], v[20:21], v[24:25]
	v_pk_mul_f32 v[10:11], v[10:11], v[6:7]
	v_pk_mul_f32 v[22:23], v[22:23], v[26:27]
	v_pk_mul_f32 v[12:13], v[12:13], v[8:9]
	v_cvt_pk_bf16_f32 v6, v20, v21
	v_cvt_pk_bf16_f32 v7, v10, v11
	v_cvt_pk_bf16_f32 v8, v22, v23
	v_cvt_pk_bf16_f32 v9, v12, v13
	global_store_dwordx4 v[14:15], v[6:9], off offset:1024 sc0 sc1
	global_load_dwordx4 v[6:9], v[18:19], off
	v_add_u32_e32 v10, 0x400, v195
	v_ashrrev_i32_e32 v28, 4, v10
	v_mad_u64_u32 v[10:11], s[2:3], v3, s6, v[2:3]
	ds_read2_b64 v[10:13], v10 offset1:1
	v_add_u32_e32 v14, s35, v28
	v_ashrrev_i32_e32 v15, 31, v14
	v_lshlrev_b64 v[18:19], 13, v[14:15]
	v_lshl_add_u64 v[18:19], s[28:29], 0, v[18:19]
	v_lshl_add_u64 v[18:19], v[18:19], 0, s[94:95]
	s_waitcnt lgkmcnt(0)
	v_lshlrev_b32_e32 v20, 16, v10
	v_and_b32_e32 v21, 0xffff0000, v10
	v_lshlrev_b32_e32 v10, 16, v11
	v_and_b32_e32 v11, 0xffff0000, v11
	v_lshlrev_b32_e32 v22, 16, v12
	v_and_b32_e32 v23, 0xffff0000, v12
	v_lshlrev_b32_e32 v12, 16, v13
	v_and_b32_e32 v13, 0xffff0000, v13
	v_lshl_add_u64 v[18:19], v[18:19], 0, v[0:1]
	v_add_co_u32_e32 v18, vcc, s86, v18
	v_add_u32_e32 v3, 0x600, v195
	s_nop 0
	v_addc_co_u32_e32 v19, vcc, 0, v19, vcc
	v_ashrrev_i32_e32 v3, 4, v3
	v_mad_i64_i32 v[14:15], s[2:3], v14, s92, v[4:5]
	v_lshl_add_u64 v[14:15], v[14:15], 0, s[94:95]
	v_lshl_add_u64 v[14:15], v[14:15], 0, v[0:1]
	s_waitcnt vmcnt(0)
	v_lshlrev_b32_e32 v24, 16, v6
	v_and_b32_e32 v25, 0xffff0000, v6
	v_lshlrev_b32_e32 v6, 16, v7
	v_and_b32_e32 v7, 0xffff0000, v7
	v_lshlrev_b32_e32 v26, 16, v8
	v_and_b32_e32 v27, 0xffff0000, v8
	v_lshlrev_b32_e32 v8, 16, v9
	v_and_b32_e32 v9, 0xffff0000, v9
	v_pk_mul_f32 v[20:21], v[20:21], v[24:25]
	v_pk_mul_f32 v[10:11], v[10:11], v[6:7]
	v_pk_mul_f32 v[22:23], v[22:23], v[26:27]
	v_pk_mul_f32 v[12:13], v[12:13], v[8:9]
	v_cvt_pk_bf16_f32 v6, v20, v21
	v_cvt_pk_bf16_f32 v7, v10, v11
	v_cvt_pk_bf16_f32 v8, v22, v23
	v_cvt_pk_bf16_f32 v9, v12, v13
	global_store_dwordx4 v[16:17], v[6:9], off offset:1024 sc0 sc1
	global_load_dwordx4 v[6:9], v[18:19], off
	v_mad_u64_u32 v[10:11], s[2:3], v28, s6, v[2:3]
	ds_read2_b64 v[10:13], v10 offset1:1
	v_add_u32_e32 v16, s35, v3
	v_ashrrev_i32_e32 v17, 31, v16
	v_lshlrev_b64 v[18:19], 13, v[16:17]
	v_lshl_add_u64 v[18:19], s[28:29], 0, v[18:19]
	v_lshl_add_u64 v[18:19], v[18:19], 0, s[94:95]
	s_waitcnt lgkmcnt(0)
	v_lshlrev_b32_e32 v20, 16, v10
	v_and_b32_e32 v21, 0xffff0000, v10
	v_lshlrev_b32_e32 v10, 16, v11
	v_and_b32_e32 v11, 0xffff0000, v11
	v_lshlrev_b32_e32 v22, 16, v12
	v_and_b32_e32 v23, 0xffff0000, v12
	v_lshlrev_b32_e32 v12, 16, v13
	v_and_b32_e32 v13, 0xffff0000, v13
	v_lshl_add_u64 v[18:19], v[18:19], 0, v[0:1]
	v_add_co_u32_e32 v18, vcc, s86, v18
	v_mad_u64_u32 v[2:3], s[2:3], v3, s6, v[2:3]
	s_nop 0
	v_addc_co_u32_e32 v19, vcc, 0, v19, vcc
	s_waitcnt vmcnt(0)
	v_lshlrev_b32_e32 v24, 16, v6
	v_and_b32_e32 v25, 0xffff0000, v6
	v_lshlrev_b32_e32 v6, 16, v7
	v_and_b32_e32 v7, 0xffff0000, v7
	v_lshlrev_b32_e32 v26, 16, v8
	v_and_b32_e32 v27, 0xffff0000, v8
	v_lshlrev_b32_e32 v8, 16, v9
	v_and_b32_e32 v9, 0xffff0000, v9
	v_pk_mul_f32 v[20:21], v[20:21], v[24:25]
	v_pk_mul_f32 v[10:11], v[10:11], v[6:7]
	v_pk_mul_f32 v[22:23], v[22:23], v[26:27]
	v_pk_mul_f32 v[12:13], v[12:13], v[8:9]
	v_cvt_pk_bf16_f32 v6, v20, v21
	v_cvt_pk_bf16_f32 v7, v10, v11
	v_cvt_pk_bf16_f32 v8, v22, v23
	v_cvt_pk_bf16_f32 v9, v12, v13
	global_store_dwordx4 v[14:15], v[6:9], off offset:1024 sc0 sc1
	global_load_dwordx4 v[6:9], v[18:19], off
	ds_read2_b64 v[10:13], v2 offset1:1
	v_mad_i64_i32 v[2:3], s[2:3], v16, s92, v[4:5]
	v_lshl_add_u64 v[2:3], v[2:3], 0, s[94:95]
	v_lshl_add_u64 v[14:15], v[2:3], 0, v[0:1]
	s_waitcnt lgkmcnt(0)
	v_lshlrev_b32_e32 v2, 16, v10
	v_and_b32_e32 v3, 0xffff0000, v10
	v_lshlrev_b32_e32 v4, 16, v11
	v_and_b32_e32 v5, 0xffff0000, v11
	v_lshlrev_b32_e32 v10, 16, v12
	v_and_b32_e32 v11, 0xffff0000, v12
	v_lshlrev_b32_e32 v12, 16, v13
	v_and_b32_e32 v13, 0xffff0000, v13
	s_waitcnt vmcnt(0)
	v_lshlrev_b32_e32 v16, 16, v6
	v_and_b32_e32 v17, 0xffff0000, v6
	v_lshlrev_b32_e32 v6, 16, v7
	v_and_b32_e32 v7, 0xffff0000, v7
	v_lshlrev_b32_e32 v18, 16, v8
	v_and_b32_e32 v19, 0xffff0000, v8
	v_lshlrev_b32_e32 v8, 16, v9
	v_and_b32_e32 v9, 0xffff0000, v9
	v_pk_mul_f32 v[2:3], v[2:3], v[16:17]
	v_pk_mul_f32 v[4:5], v[4:5], v[6:7]
	v_pk_mul_f32 v[6:7], v[10:11], v[18:19]
	v_pk_mul_f32 v[8:9], v[12:13], v[8:9]
	v_cvt_pk_bf16_f32 v2, v2, v3
	v_cvt_pk_bf16_f32 v3, v4, v5
	v_cvt_pk_bf16_f32 v4, v6, v7
	v_cvt_pk_bf16_f32 v5, v8, v9
	global_store_dwordx4 v[14:15], v[2:5], off offset:1024 sc0 sc1
	s_cbranch_scc0 .LBB0_140

.LBB0_142:
	v_and_b32_e32 v34, 64, v228
	v_xor_b32_e32 v0, 32, v228
	v_add_u32_e32 v34, 64, v34
	v_cmp_lt_i32_e32 vcc, v0, v34
	s_waitcnt lgkmcnt(0)
	s_barrier
	v_cndmask_b32_e32 v0, v228, v0, vcc
	v_lshlrev_b32_e32 v0, 2, v0
	ds_bpermute_b32 v0, v0, v191
	s_waitcnt lgkmcnt(0)
	s_movk_i32 s8, 0x88
	s_add_i32 s2, s2, s99
	s_cmpk_lt_i32 s2, 0x200
	v_add_f32_e32 v0, v191, v0
	v_div_scale_f32 v34, s[6:7], v0, v0, 1.0
	v_rcp_f32_e32 v35, v34
	v_div_scale_f32 v36, vcc, 1.0, v0, 1.0
	s_movk_i32 s73, 0x60
	v_fma_f32 v37, -v34, v35, 1.0
	v_fmac_f32_e32 v35, v37, v35
	v_mul_f32_e32 v37, v36, v35
	v_fma_f32 v38, -v34, v37, v36
	v_fmac_f32_e32 v37, v38, v35
	v_fma_f32 v34, -v34, v37, v36
	v_div_fmas_f32 v34, v34, v35, v37
	v_div_fixup_f32 v0, v34, v0, 1.0
	v_pk_mul_f32 v[18:19], v[18:19], v[0:1] op_sel_hi:[1,0]
	v_pk_mul_f32 v[20:21], v[20:21], v[0:1] op_sel_hi:[1,0]
	v_cvt_pk_bf16_f32 v18, v18, v19
	v_cvt_pk_bf16_f32 v19, v20, v21
	v_lshrrev_b32_e32 v20, 2, v181
	v_pk_mul_f32 v[2:3], v[2:3], v[0:1] op_sel_hi:[1,0]
	v_pk_mul_f32 v[4:5], v[4:5], v[0:1] op_sel_hi:[1,0]
	v_mul_u32_u24_e32 v34, 0x88, v183
	v_and_b32_e32 v20, 8, v20
	v_cvt_pk_bf16_f32 v2, v2, v3
	v_cvt_pk_bf16_f32 v3, v4, v5
	v_pk_mul_f32 v[4:5], v[6:7], v[0:1] op_sel_hi:[1,0]
	v_pk_mul_f32 v[6:7], v[8:9], v[0:1] op_sel_hi:[1,0]
	v_add3_u32 v34, v145, v34, v20
	v_cvt_pk_bf16_f32 v4, v4, v5
	v_cvt_pk_bf16_f32 v5, v6, v7
	ds_write2_b64 v34, v[2:3], v[4:5] offset0:8 offset1:10
	v_pk_mul_f32 v[2:3], v[10:11], v[0:1] op_sel_hi:[1,0]
	v_pk_mul_f32 v[4:5], v[12:13], v[0:1] op_sel_hi:[1,0]
	v_pk_mul_f32 v[20:21], v[22:23], v[0:1] op_sel_hi:[1,0]
	v_pk_mul_f32 v[22:23], v[24:25], v[0:1] op_sel_hi:[1,0]
	v_cvt_pk_bf16_f32 v2, v2, v3
	v_cvt_pk_bf16_f32 v3, v4, v5
	v_pk_mul_f32 v[4:5], v[14:15], v[0:1] op_sel_hi:[1,0]
	v_pk_mul_f32 v[6:7], v[16:17], v[0:1] op_sel_hi:[1,0]
	v_lshrrev_b32_e32 v12, 3, v180
	v_cvt_pk_bf16_f32 v20, v20, v21
	v_cvt_pk_bf16_f32 v21, v22, v23
	v_cvt_pk_bf16_f32 v4, v4, v5
	v_cvt_pk_bf16_f32 v5, v6, v7
	v_or_b32_e32 v6, v182, v12
	ds_write2_b64 v34, v[18:19], v[20:21] offset1:2
	v_pk_mul_f32 v[18:19], v[26:27], v[0:1] op_sel_hi:[1,0]
	v_pk_mul_f32 v[20:21], v[28:29], v[0:1] op_sel_hi:[1,0]
	v_ashrrev_i32_e32 v7, 31, v6
	v_cvt_pk_bf16_f32 v18, v18, v19
	v_cvt_pk_bf16_f32 v19, v20, v21
	v_pk_mul_f32 v[20:21], v[30:31], v[0:1] op_sel_hi:[1,0]
	v_pk_mul_f32 v[22:23], v[32:33], v[0:1] op_sel_hi:[1,0]
	ds_write2_b64 v34, v[2:3], v[4:5] offset0:12 offset1:14
	v_lshlrev_b32_e32 v0, 4, v181
	v_lshlrev_b64 v[4:5], 13, v[6:7]
	v_and_b32_e32 v2, 0x70, v0
	v_lshl_add_u64 v[4:5], s[78:79], 0, v[4:5]
	v_lshlrev_b32_e32 v0, 1, v130
	v_lshl_add_u64 v[4:5], v[4:5], 0, v[0:1]
	v_mov_b32_e32 v3, v1
	v_lshl_add_u64 v[4:5], v[4:5], 0, v[2:3]
	v_add_co_u32_e32 v4, vcc, s86, v4
	v_cvt_pk_bf16_f32 v20, v20, v21
	v_cvt_pk_bf16_f32 v21, v22, v23
	v_addc_co_u32_e32 v5, vcc, 0, v5, vcc
	ds_write2_b64 v34, v[18:19], v[20:21] offset0:4 offset1:6
	s_waitcnt lgkmcnt(0)
	s_barrier
	global_load_dwordx4 v[8:11], v[4:5], off offset:3072
	v_add_u32_e32 v7, v145, v2
	v_mad_u32_u24 v30, v12, s8, v7
	ds_read2_b64 v[12:15], v30 offset1:1
	s_load_dwordx2 s[6:7], s[4:5], 0x158
	s_waitcnt lgkmcnt(0)
	v_lshlrev_b32_e32 v4, 16, v12
	v_and_b32_e32 v5, 0xffff0000, v12
	v_lshlrev_b32_e32 v12, 16, v13
	v_and_b32_e32 v13, 0xffff0000, v13
	v_lshlrev_b32_e32 v16, 16, v14
	v_and_b32_e32 v17, 0xffff0000, v14
	v_lshlrev_b32_e32 v14, 16, v15
	v_and_b32_e32 v15, 0xffff0000, v15
	s_waitcnt vmcnt(0)
	v_lshlrev_b32_e32 v18, 16, v8
	v_and_b32_e32 v19, 0xffff0000, v8
	v_lshlrev_b32_e32 v8, 16, v9
	v_and_b32_e32 v9, 0xffff0000, v9
	v_pk_mul_f32 v[4:5], v[4:5], v[18:19]
	v_pk_mul_f32 v[12:13], v[12:13], v[8:9]
	v_cvt_pk_bf16_f32 v8, v4, v5
	v_lshlrev_b32_e32 v4, 16, v11
	v_and_b32_e32 v5, 0xffff0000, v11
	v_pk_mul_f32 v[4:5], v[14:15], v[4:5]
	v_lshlrev_b32_e32 v20, 16, v10
	v_cvt_pk_bf16_f32 v11, v4, v5
	v_mov_b64_e32 v[4:5], s[6:7]
	v_and_b32_e32 v21, 0xffff0000, v10
	v_cvt_pk_bf16_f32 v9, v12, v13
	v_mad_i64_i32 v[12:13], s[6:7], v6, s92, v[4:5]
	v_pk_mul_f32 v[16:17], v[16:17], v[20:21]
	v_lshl_add_u64 v[12:13], v[12:13], 0, v[0:1]
	v_cvt_pk_bf16_f32 v10, v16, v17
	v_lshl_add_u64 v[12:13], v[12:13], 0, v[2:3]
	global_store_dwordx4 v[12:13], v[8:11], off offset:2048 sc0 sc1
	v_lshrrev_b32_e32 v12, 3, v179
	v_or_b32_e32 v16, v182, v12
	v_ashrrev_i32_e32 v17, 31, v16
	v_lshlrev_b64 v[8:9], 13, v[16:17]
	v_lshl_add_u64 v[8:9], s[78:79], 0, v[8:9]
	v_lshl_add_u64 v[8:9], v[8:9], 0, v[0:1]
	v_lshl_add_u64 v[8:9], v[8:9], 0, v[2:3]
	v_add_co_u32_e32 v8, vcc, s86, v8
	v_or_b32_e32 v18, 64, v6
	s_nop 0
	v_addc_co_u32_e32 v9, vcc, 0, v9, vcc
	global_load_dwordx4 v[8:11], v[8:9], off offset:3072
	v_ashrrev_i32_e32 v19, 31, v18
	v_mad_u32_u24 v7, v12, s8, v7
	v_lshlrev_b64 v[12:13], 13, v[18:19]
	v_lshl_add_u64 v[12:13], s[78:79], 0, v[12:13]
	v_lshl_add_u64 v[12:13], v[12:13], 0, v[0:1]
	v_lshl_add_u64 v[20:21], v[12:13], 0, v[2:3]
	ds_read2_b64 v[12:15], v7 offset1:1
	v_mad_i64_i32 v[16:17], s[6:7], v16, s92, v[4:5]
	v_lshl_add_u64 v[16:17], v[16:17], 0, v[0:1]
	v_add_co_u32_e32 v20, vcc, s86, v20
	s_waitcnt lgkmcnt(0)
	v_lshlrev_b32_e32 v22, 16, v12
	v_and_b32_e32 v23, 0xffff0000, v12
	v_lshlrev_b32_e32 v12, 16, v13
	v_and_b32_e32 v13, 0xffff0000, v13
	v_lshlrev_b32_e32 v24, 16, v14
	v_and_b32_e32 v25, 0xffff0000, v14
	v_lshlrev_b32_e32 v14, 16, v15
	v_and_b32_e32 v15, 0xffff0000, v15
	v_lshl_add_u64 v[16:17], v[16:17], 0, v[2:3]
	v_addc_co_u32_e32 v21, vcc, 0, v21, vcc
	v_mad_i64_i32 v[18:19], s[6:7], v18, s92, v[4:5]
	v_lshl_add_u64 v[18:19], v[18:19], 0, v[0:1]
	v_lshl_add_u64 v[18:19], v[18:19], 0, v[2:3]
	s_waitcnt vmcnt(0)
	v_lshlrev_b32_e32 v26, 16, v8
	v_and_b32_e32 v27, 0xffff0000, v8
	v_lshlrev_b32_e32 v8, 16, v9
	v_and_b32_e32 v9, 0xffff0000, v9
	v_lshlrev_b32_e32 v28, 16, v10
	v_and_b32_e32 v29, 0xffff0000, v10
	v_lshlrev_b32_e32 v10, 16, v11
	v_and_b32_e32 v11, 0xffff0000, v11
	v_pk_mul_f32 v[22:23], v[22:23], v[26:27]
	v_pk_mul_f32 v[12:13], v[12:13], v[8:9]
	v_pk_mul_f32 v[24:25], v[24:25], v[28:29]
	v_pk_mul_f32 v[14:15], v[14:15], v[10:11]
	v_cvt_pk_bf16_f32 v8, v22, v23
	v_cvt_pk_bf16_f32 v9, v12, v13
	v_cvt_pk_bf16_f32 v10, v24, v25
	v_cvt_pk_bf16_f32 v11, v14, v15
	global_store_dwordx4 v[16:17], v[8:11], off offset:2048 sc0 sc1
	global_load_dwordx4 v[8:11], v[20:21], off offset:3072
	v_or_b32_e32 v16, 0x60, v6
	v_ashrrev_i32_e32 v17, 31, v16
	v_add_u32_e32 v12, 0x2200, v30
	v_lshlrev_b64 v[6:7], 13, v[16:17]
	ds_read2_b64 v[12:15], v12 offset1:1
	v_lshl_add_u64 v[6:7], s[78:79], 0, v[6:7]
	v_lshl_add_u64 v[6:7], v[6:7], 0, v[0:1]
	v_lshl_add_u64 v[6:7], v[6:7], 0, v[2:3]
	v_add_co_u32_e32 v20, vcc, s86, v6
	s_waitcnt lgkmcnt(0)
	v_lshlrev_b32_e32 v6, 16, v12
	v_addc_co_u32_e32 v21, vcc, 0, v7, vcc
	v_and_b32_e32 v7, 0xffff0000, v12
	v_lshlrev_b32_e32 v12, 16, v13
	v_and_b32_e32 v13, 0xffff0000, v13
	v_lshlrev_b32_e32 v22, 16, v14
	v_and_b32_e32 v23, 0xffff0000, v14
	v_lshlrev_b32_e32 v14, 16, v15
	v_and_b32_e32 v15, 0xffff0000, v15
	v_mad_i64_i32 v[4:5], s[6:7], v16, s92, v[4:5]
	v_lshl_add_u64 v[4:5], v[4:5], 0, v[0:1]
	v_lshl_add_u64 v[16:17], v[4:5], 0, v[2:3]
	s_waitcnt vmcnt(0)
	v_lshlrev_b32_e32 v24, 16, v8
	v_and_b32_e32 v25, 0xffff0000, v8
	v_lshlrev_b32_e32 v8, 16, v9
	v_and_b32_e32 v9, 0xffff0000, v9
	v_lshlrev_b32_e32 v26, 16, v10
	v_and_b32_e32 v27, 0xffff0000, v10
	v_lshlrev_b32_e32 v10, 16, v11
	v_and_b32_e32 v11, 0xffff0000, v11
	v_pk_mul_f32 v[6:7], v[6:7], v[24:25]
	v_pk_mul_f32 v[8:9], v[12:13], v[8:9]
	v_pk_mul_f32 v[12:13], v[22:23], v[26:27]
	v_pk_mul_f32 v[10:11], v[14:15], v[10:11]
	v_cvt_pk_bf16_f32 v6, v6, v7
	v_cvt_pk_bf16_f32 v7, v8, v9
	v_cvt_pk_bf16_f32 v8, v12, v13
	v_cvt_pk_bf16_f32 v9, v10, v11
	global_store_dwordx4 v[18:19], v[6:9], off offset:2048 sc0 sc1
	global_load_dwordx4 v[6:9], v[20:21], off offset:3072
	v_add_u32_e32 v10, 0x3300, v30
	ds_read2_b64 v[10:13], v10 offset1:1
	s_waitcnt lgkmcnt(0)
	v_lshlrev_b32_e32 v14, 16, v10
	v_and_b32_e32 v15, 0xffff0000, v10
	v_lshlrev_b32_e32 v10, 16, v11
	v_and_b32_e32 v11, 0xffff0000, v11
	v_lshlrev_b32_e32 v18, 16, v12
	v_and_b32_e32 v19, 0xffff0000, v12
	v_lshlrev_b32_e32 v12, 16, v13
	v_and_b32_e32 v13, 0xffff0000, v13
	s_waitcnt vmcnt(0)
	v_lshlrev_b32_e32 v2, 16, v6
	v_and_b32_e32 v3, 0xffff0000, v6
	v_lshlrev_b32_e32 v4, 16, v7
	v_and_b32_e32 v5, 0xffff0000, v7
	v_lshlrev_b32_e32 v6, 16, v8
	v_and_b32_e32 v7, 0xffff0000, v8
	v_lshlrev_b32_e32 v8, 16, v9
	v_and_b32_e32 v9, 0xffff0000, v9
	v_pk_mul_f32 v[2:3], v[14:15], v[2:3]
	v_pk_mul_f32 v[4:5], v[10:11], v[4:5]
	v_pk_mul_f32 v[6:7], v[18:19], v[6:7]
	v_pk_mul_f32 v[8:9], v[12:13], v[8:9]
	v_cvt_pk_bf16_f32 v2, v2, v3
	v_cvt_pk_bf16_f32 v3, v4, v5
	v_cvt_pk_bf16_f32 v4, v6, v7
	v_cvt_pk_bf16_f32 v5, v8, v9
	global_store_dwordx4 v[16:17], v[2:5], off offset:2048 sc0 sc1
	s_cbranch_scc0 .LBB0_235

.LBB0_239:
	s_or_b64 exec, exec, s[4:5]
	v_ashrrev_i32_e32 v8, 4, v186
	v_add_u32_e32 v12, s27, v8
	v_ashrrev_i32_e32 v13, 31, v12
	v_lshlrev_b64 v[2:3], 13, v[12:13]
	v_lshl_add_u64 v[2:3], s[22:23], 0, v[2:3]
	s_lshl_b32 s94, s2, 8
	v_and_b32_e32 v0, 0xf0, v187
	v_lshl_add_u64 v[2:3], v[2:3], 0, s[94:95]
	v_lshl_add_u64 v[2:3], v[2:3], 0, v[0:1]
	v_add_co_u32_e32 v2, vcc, s86, v2
	s_waitcnt lgkmcnt(0)
	s_nop 0
	v_addc_co_u32_e32 v3, vcc, 0, v3, vcc
	s_barrier
	global_load_dwordx4 v[4:7], v[2:3], off
	v_add_u32_e32 v2, 0x200, v186
	v_or_b32_e32 v14, 0x10000, v0
	v_ashrrev_i32_e32 v15, 4, v2
	s_movk_i32 s6, 0x108
	s_load_dwordx2 s[2:3], s[12:13], 0x158
	v_mad_u64_u32 v[2:3], s[4:5], v8, s6, v[14:15]
	ds_read2_b64 v[8:11], v2 offset1:1
	v_add_u32_e32 v16, s27, v15
	v_ashrrev_i32_e32 v17, 31, v16
	v_lshlrev_b64 v[18:19], 13, v[16:17]
	s_waitcnt lgkmcnt(0)
	v_mov_b64_e32 v[2:3], s[2:3]
	v_lshl_add_u64 v[18:19], s[22:23], 0, v[18:19]
	v_mad_i64_i32 v[12:13], s[2:3], v12, s92, v[2:3]
	v_lshl_add_u64 v[18:19], v[18:19], 0, s[94:95]
	v_lshlrev_b32_e32 v20, 16, v8
	v_and_b32_e32 v21, 0xffff0000, v8
	v_lshlrev_b32_e32 v8, 16, v9
	v_and_b32_e32 v9, 0xffff0000, v9
	v_lshlrev_b32_e32 v22, 16, v10
	v_and_b32_e32 v23, 0xffff0000, v10
	v_lshlrev_b32_e32 v10, 16, v11
	v_and_b32_e32 v11, 0xffff0000, v11
	v_lshl_add_u64 v[12:13], v[12:13], 0, s[94:95]
	v_lshl_add_u64 v[18:19], v[18:19], 0, v[0:1]
	v_lshl_add_u64 v[12:13], v[12:13], 0, v[0:1]
	v_add_co_u32_e32 v18, vcc, s86, v18
	v_mad_i64_i32 v[16:17], s[2:3], v16, s92, v[2:3]
	s_nop 0
	v_addc_co_u32_e32 v19, vcc, 0, v19, vcc
	v_lshl_add_u64 v[16:17], v[16:17], 0, s[94:95]
	v_lshl_add_u64 v[16:17], v[16:17], 0, v[0:1]
	s_add_i32 s26, s26, s99
	s_cmpk_lt_i32 s26, 0x80
	s_waitcnt vmcnt(0)
	v_lshlrev_b32_e32 v24, 16, v4
	v_and_b32_e32 v25, 0xffff0000, v4
	v_lshlrev_b32_e32 v4, 16, v5
	v_and_b32_e32 v5, 0xffff0000, v5
	v_lshlrev_b32_e32 v26, 16, v6
	v_and_b32_e32 v27, 0xffff0000, v6
	v_lshlrev_b32_e32 v6, 16, v7
	v_and_b32_e32 v7, 0xffff0000, v7
	v_pk_mul_f32 v[20:21], v[20:21], v[24:25]
	v_pk_mul_f32 v[8:9], v[8:9], v[4:5]
	v_pk_mul_f32 v[22:23], v[22:23], v[26:27]
	v_pk_mul_f32 v[10:11], v[10:11], v[6:7]
	v_cvt_pk_bf16_f32 v4, v20, v21
	v_cvt_pk_bf16_f32 v5, v8, v9
	v_cvt_pk_bf16_f32 v6, v22, v23
	v_cvt_pk_bf16_f32 v7, v10, v11
	global_store_dwordx4 v[12:13], v[4:7], off offset:1024 sc0 sc1
	global_load_dwordx4 v[4:7], v[18:19], off
	v_add_u32_e32 v8, 0x400, v186
	v_ashrrev_i32_e32 v28, 4, v8
	v_mad_u64_u32 v[8:9], s[2:3], v15, s6, v[14:15]
	ds_read2_b64 v[8:11], v8 offset1:1
	v_add_u32_e32 v12, s27, v28
	v_ashrrev_i32_e32 v13, 31, v12
	v_lshlrev_b64 v[18:19], 13, v[12:13]
	v_lshl_add_u64 v[18:19], s[22:23], 0, v[18:19]
	v_lshl_add_u64 v[18:19], v[18:19], 0, s[94:95]
	s_waitcnt lgkmcnt(0)
	v_lshlrev_b32_e32 v20, 16, v8
	v_and_b32_e32 v21, 0xffff0000, v8
	v_lshlrev_b32_e32 v8, 16, v9
	v_and_b32_e32 v9, 0xffff0000, v9
	v_lshlrev_b32_e32 v22, 16, v10
	v_and_b32_e32 v23, 0xffff0000, v10
	v_lshlrev_b32_e32 v10, 16, v11
	v_and_b32_e32 v11, 0xffff0000, v11
	v_lshl_add_u64 v[18:19], v[18:19], 0, v[0:1]
	v_add_co_u32_e32 v18, vcc, s86, v18
	v_mad_i64_i32 v[12:13], s[2:3], v12, s92, v[2:3]
	s_nop 0
	v_addc_co_u32_e32 v19, vcc, 0, v19, vcc
	v_lshl_add_u64 v[12:13], v[12:13], 0, s[94:95]
	v_lshl_add_u64 v[12:13], v[12:13], 0, v[0:1]
	s_waitcnt vmcnt(0)
	v_lshlrev_b32_e32 v24, 16, v4
	v_and_b32_e32 v25, 0xffff0000, v4
	v_lshlrev_b32_e32 v4, 16, v5
	v_and_b32_e32 v5, 0xffff0000, v5
	v_lshlrev_b32_e32 v26, 16, v6
	v_and_b32_e32 v27, 0xffff0000, v6
	v_lshlrev_b32_e32 v6, 16, v7
	v_and_b32_e32 v7, 0xffff0000, v7
	v_pk_mul_f32 v[20:21], v[20:21], v[24:25]
	v_pk_mul_f32 v[8:9], v[8:9], v[4:5]
	v_pk_mul_f32 v[22:23], v[22:23], v[26:27]
	v_pk_mul_f32 v[10:11], v[10:11], v[6:7]
	v_cvt_pk_bf16_f32 v4, v20, v21
	v_cvt_pk_bf16_f32 v5, v8, v9
	v_cvt_pk_bf16_f32 v6, v22, v23
	v_cvt_pk_bf16_f32 v7, v10, v11
	global_store_dwordx4 v[16:17], v[4:7], off offset:1024 sc0 sc1
	global_load_dwordx4 v[4:7], v[18:19], off
	v_add_u32_e32 v8, 0x600, v186
	v_ashrrev_i32_e32 v15, 4, v8
	v_mad_u64_u32 v[8:9], s[2:3], v28, s6, v[14:15]
	ds_read2_b64 v[8:11], v8 offset1:1
	v_add_u32_e32 v16, s27, v15
	v_ashrrev_i32_e32 v17, 31, v16
	v_lshlrev_b64 v[18:19], 13, v[16:17]
	v_lshl_add_u64 v[18:19], s[22:23], 0, v[18:19]
	v_lshl_add_u64 v[18:19], v[18:19], 0, s[94:95]
	s_waitcnt lgkmcnt(0)
	v_lshlrev_b32_e32 v20, 16, v8
	v_and_b32_e32 v21, 0xffff0000, v8
	v_lshlrev_b32_e32 v8, 16, v9
	v_and_b32_e32 v9, 0xffff0000, v9
	v_lshlrev_b32_e32 v22, 16, v10
	v_and_b32_e32 v23, 0xffff0000, v10
	v_lshlrev_b32_e32 v10, 16, v11
	v_and_b32_e32 v11, 0xffff0000, v11
	v_lshl_add_u64 v[18:19], v[18:19], 0, v[0:1]
	v_add_co_u32_e32 v18, vcc, s86, v18
	v_mad_i64_i32 v[2:3], s[2:3], v16, s92, v[2:3]
	s_nop 0
	v_addc_co_u32_e32 v19, vcc, 0, v19, vcc
	v_lshl_add_u64 v[2:3], v[2:3], 0, s[94:95]
	v_lshl_add_u64 v[16:17], v[2:3], 0, v[0:1]
	s_waitcnt vmcnt(0)
	v_lshlrev_b32_e32 v24, 16, v4
	v_and_b32_e32 v25, 0xffff0000, v4
	v_lshlrev_b32_e32 v4, 16, v5
	v_and_b32_e32 v5, 0xffff0000, v5
	v_lshlrev_b32_e32 v26, 16, v6
	v_and_b32_e32 v27, 0xffff0000, v6
	v_lshlrev_b32_e32 v6, 16, v7
	v_and_b32_e32 v7, 0xffff0000, v7
	v_pk_mul_f32 v[20:21], v[20:21], v[24:25]
	v_pk_mul_f32 v[8:9], v[8:9], v[4:5]
	v_pk_mul_f32 v[22:23], v[22:23], v[26:27]
	v_pk_mul_f32 v[10:11], v[10:11], v[6:7]
	v_cvt_pk_bf16_f32 v4, v20, v21
	v_cvt_pk_bf16_f32 v5, v8, v9
	v_cvt_pk_bf16_f32 v6, v22, v23
	v_cvt_pk_bf16_f32 v7, v10, v11
	global_store_dwordx4 v[12:13], v[4:7], off offset:1024 sc0 sc1
	global_load_dwordx4 v[4:7], v[18:19], off
	v_mad_u64_u32 v[8:9], s[2:3], v15, s6, v[14:15]
	ds_read2_b64 v[8:11], v8 offset1:1
	s_waitcnt lgkmcnt(0)
	v_lshlrev_b32_e32 v12, 16, v8
	v_and_b32_e32 v13, 0xffff0000, v8
	v_lshlrev_b32_e32 v8, 16, v9
	v_and_b32_e32 v9, 0xffff0000, v9
	v_lshlrev_b32_e32 v14, 16, v10
	v_and_b32_e32 v15, 0xffff0000, v10
	v_lshlrev_b32_e32 v10, 16, v11
	v_and_b32_e32 v11, 0xffff0000, v11
	s_waitcnt vmcnt(0)
	v_lshlrev_b32_e32 v2, 16, v4
	v_and_b32_e32 v3, 0xffff0000, v4
	v_lshlrev_b32_e32 v4, 16, v5
	v_and_b32_e32 v5, 0xffff0000, v5
	v_lshlrev_b32_e32 v18, 16, v6
	v_and_b32_e32 v19, 0xffff0000, v6
	v_lshlrev_b32_e32 v6, 16, v7
	v_and_b32_e32 v7, 0xffff0000, v7
	v_pk_mul_f32 v[2:3], v[12:13], v[2:3]
	v_pk_mul_f32 v[4:5], v[8:9], v[4:5]
	v_pk_mul_f32 v[8:9], v[14:15], v[18:19]
	v_pk_mul_f32 v[6:7], v[10:11], v[6:7]
	v_cvt_pk_bf16_f32 v2, v2, v3
	v_cvt_pk_bf16_f32 v3, v4, v5
	v_cvt_pk_bf16_f32 v4, v8, v9
	v_cvt_pk_bf16_f32 v5, v6, v7
	global_store_dwordx4 v[16:17], v[2:5], off offset:1024 sc0 sc1
	s_cbranch_scc0 .LBB0_261

.LBB0_263:
	ds_bpermute_b32 v0, v160, v158
	s_movk_i32 s3, 0x88
	s_waitcnt lgkmcnt(0)
	s_barrier
	v_add_f32_e32 v0, v158, v0
	v_div_scale_f32 v34, s[6:7], v0, v0, 1.0
	v_rcp_f32_e32 v35, v34
	v_div_scale_f32 v36, vcc, 1.0, v0, 1.0
	s_lshl_b32 s94, s2, 1
	v_fma_f32 v37, -v34, v35, 1.0
	v_fmac_f32_e32 v35, v37, v35
	v_mul_f32_e32 v37, v36, v35
	v_fma_f32 v38, -v34, v37, v36
	v_fmac_f32_e32 v37, v38, v35
	v_fma_f32 v34, -v34, v37, v36
	v_div_fmas_f32 v34, v34, v35, v37
	v_div_fixup_f32 v0, v34, v0, 1.0
	v_lshrrev_b32_e32 v34, 2, v152
	v_pk_mul_f32 v[2:3], v[2:3], v[0:1] op_sel_hi:[1,0]
	v_pk_mul_f32 v[4:5], v[4:5], v[0:1] op_sel_hi:[1,0]
	v_and_b32_e32 v34, 8, v34
	v_cvt_pk_bf16_f32 v2, v2, v3
	v_cvt_pk_bf16_f32 v3, v4, v5
	v_pk_mul_f32 v[4:5], v[6:7], v[0:1] op_sel_hi:[1,0]
	v_pk_mul_f32 v[6:7], v[8:9], v[0:1] op_sel_hi:[1,0]
	v_mad_u32_u24 v34, v153, s3, v34
	v_cvt_pk_bf16_f32 v4, v4, v5
	v_cvt_pk_bf16_f32 v5, v6, v7
	ds_write2_b64 v34, v[2:3], v[4:5] offset1:2
	v_pk_mul_f32 v[2:3], v[10:11], v[0:1] op_sel_hi:[1,0]
	v_pk_mul_f32 v[4:5], v[12:13], v[0:1] op_sel_hi:[1,0]
	v_cvt_pk_bf16_f32 v2, v2, v3
	v_cvt_pk_bf16_f32 v3, v4, v5
	v_pk_mul_f32 v[4:5], v[14:15], v[0:1] op_sel_hi:[1,0]
	v_pk_mul_f32 v[6:7], v[16:17], v[0:1] op_sel_hi:[1,0]
	v_cvt_pk_bf16_f32 v4, v4, v5
	v_cvt_pk_bf16_f32 v5, v6, v7
	ds_write2_b64 v34, v[2:3], v[4:5] offset0:4 offset1:6
	v_pk_mul_f32 v[2:3], v[18:19], v[0:1] op_sel_hi:[1,0]
	v_pk_mul_f32 v[4:5], v[20:21], v[0:1] op_sel_hi:[1,0]
	v_cvt_pk_bf16_f32 v2, v2, v3
	v_cvt_pk_bf16_f32 v3, v4, v5
	v_pk_mul_f32 v[4:5], v[22:23], v[0:1] op_sel_hi:[1,0]
	v_pk_mul_f32 v[6:7], v[24:25], v[0:1] op_sel_hi:[1,0]
	v_cvt_pk_bf16_f32 v4, v4, v5
	v_cvt_pk_bf16_f32 v5, v6, v7
	ds_write2_b64 v34, v[2:3], v[4:5] offset0:8 offset1:10
	v_pk_mul_f32 v[2:3], v[26:27], v[0:1] op_sel_hi:[1,0]
	v_pk_mul_f32 v[4:5], v[28:29], v[0:1] op_sel_hi:[1,0]
	v_bfe_u32 v8, v152, 3, 6
	v_cvt_pk_bf16_f32 v2, v2, v3
	v_cvt_pk_bf16_f32 v3, v4, v5
	v_pk_mul_f32 v[4:5], v[30:31], v[0:1] op_sel_hi:[1,0]
	v_pk_mul_f32 v[6:7], v[32:33], v[0:1] op_sel_hi:[1,0]
	v_or_b32_e32 v12, s16, v8
	v_cvt_pk_bf16_f32 v4, v4, v5
	v_cvt_pk_bf16_f32 v5, v6, v7
	v_ashrrev_i32_e32 v13, 31, v12
	ds_write2_b64 v34, v[2:3], v[4:5] offset0:12 offset1:14
	v_lshlrev_b64 v[2:3], 13, v[12:13]
	v_lshlrev_b32_e32 v0, 4, v152
	v_lshl_add_u64 v[2:3], s[10:11], 0, v[2:3]
	v_and_b32_e32 v0, 0x70, v0
	v_lshl_add_u64 v[2:3], v[2:3], 0, s[94:95]
	v_lshl_add_u64 v[2:3], v[2:3], 0, v[0:1]
	v_add_co_u32_e32 v2, vcc, s86, v2
	s_waitcnt lgkmcnt(0)
	s_nop 0
	v_addc_co_u32_e32 v3, vcc, 0, v3, vcc
	s_barrier
	global_load_dwordx4 v[4:7], v[2:3], off offset:3072
	v_mad_u32_u24 v28, v8, s3, v0
	ds_read2_b64 v[8:11], v28 offset1:1
	s_load_dwordx2 s[2:3], s[4:5], 0x158
	s_add_i32 s14, s14, s99
	s_cmpk_lt_i32 s14, 0x80
	s_waitcnt lgkmcnt(0)
	v_lshlrev_b32_e32 v14, 16, v8
	v_and_b32_e32 v15, 0xffff0000, v8
	v_lshlrev_b32_e32 v8, 16, v9
	v_and_b32_e32 v9, 0xffff0000, v9
	v_mov_b64_e32 v[2:3], s[2:3]
	v_lshlrev_b32_e32 v16, 16, v10
	v_and_b32_e32 v17, 0xffff0000, v10
	v_lshlrev_b32_e32 v10, 16, v11
	v_and_b32_e32 v11, 0xffff0000, v11
	s_waitcnt vmcnt(0)
	v_lshlrev_b32_e32 v18, 16, v4
	v_and_b32_e32 v19, 0xffff0000, v4
	v_lshlrev_b32_e32 v4, 16, v5
	v_and_b32_e32 v5, 0xffff0000, v5
	v_pk_mul_f32 v[8:9], v[8:9], v[4:5]
	v_lshlrev_b32_e32 v20, 16, v6
	v_and_b32_e32 v21, 0xffff0000, v6
	v_lshlrev_b32_e32 v6, 16, v7
	v_and_b32_e32 v7, 0xffff0000, v7
	v_pk_mul_f32 v[14:15], v[14:15], v[18:19]
	v_cvt_pk_bf16_f32 v5, v8, v9
	v_mad_i64_i32 v[8:9], s[2:3], v12, s92, v[2:3]
	v_pk_mul_f32 v[16:17], v[16:17], v[20:21]
	v_pk_mul_f32 v[10:11], v[10:11], v[6:7]
	v_cvt_pk_bf16_f32 v4, v14, v15
	v_lshl_add_u64 v[8:9], v[8:9], 0, s[94:95]
	v_or_b32_e32 v14, 64, v12
	v_cvt_pk_bf16_f32 v6, v16, v17
	v_cvt_pk_bf16_f32 v7, v10, v11
	v_lshl_add_u64 v[8:9], v[8:9], 0, v[0:1]
	v_ashrrev_i32_e32 v15, 31, v14
	global_store_dwordx4 v[8:9], v[4:7], off offset:2048 sc0 sc1
	v_or_b32_e32 v16, 0x80, v12
	v_ashrrev_i32_e32 v17, 31, v16
	v_lshlrev_b64 v[4:5], 13, v[14:15]
	v_lshl_add_u64 v[4:5], s[10:11], 0, v[4:5]
	v_lshl_add_u64 v[4:5], v[4:5], 0, s[94:95]
	v_lshl_add_u64 v[4:5], v[4:5], 0, v[0:1]
	v_add_co_u32_e32 v4, vcc, s86, v4
	v_lshlrev_b64 v[8:9], 13, v[16:17]
	s_nop 0
	v_addc_co_u32_e32 v5, vcc, 0, v5, vcc
	global_load_dwordx4 v[4:7], v[4:5], off offset:3072
	v_lshl_add_u64 v[8:9], s[10:11], 0, v[8:9]
	v_add_u32_e32 v10, 0x2200, v28
	v_lshl_add_u64 v[8:9], v[8:9], 0, s[94:95]
	v_lshl_add_u64 v[18:19], v[8:9], 0, v[0:1]
	ds_read2_b64 v[8:11], v10 offset1:1
	v_mad_i64_i32 v[14:15], s[2:3], v14, s92, v[2:3]
	v_lshl_add_u64 v[14:15], v[14:15], 0, s[94:95]
	v_add_co_u32_e32 v18, vcc, s86, v18
	s_waitcnt lgkmcnt(0)
	v_lshlrev_b32_e32 v20, 16, v8
	v_and_b32_e32 v21, 0xffff0000, v8
	v_lshlrev_b32_e32 v8, 16, v9
	v_and_b32_e32 v9, 0xffff0000, v9
	v_lshlrev_b32_e32 v22, 16, v10
	v_and_b32_e32 v23, 0xffff0000, v10
	v_lshlrev_b32_e32 v10, 16, v11
	v_and_b32_e32 v11, 0xffff0000, v11
	v_lshl_add_u64 v[14:15], v[14:15], 0, v[0:1]
	v_addc_co_u32_e32 v19, vcc, 0, v19, vcc
	v_or_b32_e32 v12, 0xc0, v12
	v_ashrrev_i32_e32 v13, 31, v12
	v_mad_i64_i32 v[16:17], s[2:3], v16, s92, v[2:3]
	v_lshl_add_u64 v[16:17], v[16:17], 0, s[94:95]
	v_lshl_add_u64 v[16:17], v[16:17], 0, v[0:1]
	v_mad_i64_i32 v[2:3], s[2:3], v12, s92, v[2:3]
	v_lshl_add_u64 v[2:3], v[2:3], 0, s[94:95]
	s_waitcnt vmcnt(0)
	v_lshlrev_b32_e32 v24, 16, v4
	v_and_b32_e32 v25, 0xffff0000, v4
	v_lshlrev_b32_e32 v4, 16, v5
	v_and_b32_e32 v5, 0xffff0000, v5
	v_lshlrev_b32_e32 v26, 16, v6
	v_and_b32_e32 v27, 0xffff0000, v6
	v_lshlrev_b32_e32 v6, 16, v7
	v_and_b32_e32 v7, 0xffff0000, v7
	v_pk_mul_f32 v[20:21], v[20:21], v[24:25]
	v_pk_mul_f32 v[8:9], v[8:9], v[4:5]
	v_pk_mul_f32 v[22:23], v[22:23], v[26:27]
	v_pk_mul_f32 v[10:11], v[10:11], v[6:7]
	v_cvt_pk_bf16_f32 v4, v20, v21
	v_cvt_pk_bf16_f32 v5, v8, v9
	v_cvt_pk_bf16_f32 v6, v22, v23
	v_cvt_pk_bf16_f32 v7, v10, v11
	global_store_dwordx4 v[14:15], v[4:7], off offset:2048 sc0 sc1
	global_load_dwordx4 v[4:7], v[18:19], off offset:3072
	v_lshlrev_b64 v[8:9], 13, v[12:13]
	v_lshl_add_u64 v[8:9], s[10:11], 0, v[8:9]
	v_add_u32_e32 v10, 0x4400, v28
	v_lshl_add_u64 v[8:9], v[8:9], 0, s[94:95]
	v_lshl_add_u64 v[14:15], v[8:9], 0, v[0:1]
	ds_read2_b64 v[8:11], v10 offset1:1
	v_add_co_u32_e32 v14, vcc, s86, v14
	v_lshl_add_u64 v[12:13], v[2:3], 0, v[0:1]
	s_nop 0
	v_addc_co_u32_e32 v15, vcc, 0, v15, vcc
	s_waitcnt lgkmcnt(0)
	v_lshlrev_b32_e32 v18, 16, v8
	v_and_b32_e32 v19, 0xffff0000, v8
	v_lshlrev_b32_e32 v8, 16, v9
	v_and_b32_e32 v9, 0xffff0000, v9
	v_lshlrev_b32_e32 v20, 16, v10
	v_and_b32_e32 v21, 0xffff0000, v10
	v_lshlrev_b32_e32 v10, 16, v11
	v_and_b32_e32 v11, 0xffff0000, v11
	s_waitcnt vmcnt(0)
	v_lshlrev_b32_e32 v22, 16, v4
	v_and_b32_e32 v23, 0xffff0000, v4
	v_lshlrev_b32_e32 v4, 16, v5
	v_and_b32_e32 v5, 0xffff0000, v5
	v_lshlrev_b32_e32 v24, 16, v6
	v_and_b32_e32 v25, 0xffff0000, v6
	v_lshlrev_b32_e32 v6, 16, v7
	v_and_b32_e32 v7, 0xffff0000, v7
	v_pk_mul_f32 v[18:19], v[18:19], v[22:23]
	v_pk_mul_f32 v[8:9], v[8:9], v[4:5]
	v_pk_mul_f32 v[20:21], v[20:21], v[24:25]
	v_pk_mul_f32 v[10:11], v[10:11], v[6:7]
	v_cvt_pk_bf16_f32 v4, v18, v19
	v_cvt_pk_bf16_f32 v5, v8, v9
	v_cvt_pk_bf16_f32 v6, v20, v21
	v_cvt_pk_bf16_f32 v7, v10, v11
	global_store_dwordx4 v[16:17], v[4:7], off offset:2048 sc0 sc1
	global_load_dwordx4 v[4:7], v[14:15], off offset:3072
	v_add_u32_e32 v8, 0x6600, v28
	ds_read2_b64 v[8:11], v8 offset1:1
	s_waitcnt lgkmcnt(0)
	v_lshlrev_b32_e32 v14, 16, v8
	v_and_b32_e32 v15, 0xffff0000, v8
	v_lshlrev_b32_e32 v8, 16, v9
	v_and_b32_e32 v9, 0xffff0000, v9
	v_lshlrev_b32_e32 v16, 16, v10
	v_and_b32_e32 v17, 0xffff0000, v10
	v_lshlrev_b32_e32 v10, 16, v11
	v_and_b32_e32 v11, 0xffff0000, v11
	s_waitcnt vmcnt(0)
	v_lshlrev_b32_e32 v2, 16, v4
	v_and_b32_e32 v3, 0xffff0000, v4
	v_lshlrev_b32_e32 v4, 16, v5
	v_and_b32_e32 v5, 0xffff0000, v5
	v_lshlrev_b32_e32 v18, 16, v6
	v_and_b32_e32 v19, 0xffff0000, v6
	v_lshlrev_b32_e32 v6, 16, v7
	v_and_b32_e32 v7, 0xffff0000, v7
	v_pk_mul_f32 v[2:3], v[14:15], v[2:3]
	v_pk_mul_f32 v[4:5], v[8:9], v[4:5]
	v_pk_mul_f32 v[8:9], v[16:17], v[18:19]
	v_pk_mul_f32 v[6:7], v[10:11], v[6:7]
	v_cvt_pk_bf16_f32 v2, v2, v3
	v_cvt_pk_bf16_f32 v3, v4, v5
	v_cvt_pk_bf16_f32 v4, v8, v9
	v_cvt_pk_bf16_f32 v5, v6, v7
	global_store_dwordx4 v[12:13], v[2:5], off offset:2048 sc0 sc1
	s_cbranch_scc0 .LBB0_284

.LBB0_287:
	s_or_b64 exec, exec, s[4:5]
	v_lshlrev_b32_e32 v2, 4, v187
	v_and_b32_e32 v2, 0xf00, v2
	v_lshl_or_b32 v2, v184, 15, v2
	v_mov_b32_e32 v3, v1
	v_lshl_add_u64 v[2:3], v[48:49], 0, v[2:3]
	s_waitcnt lgkmcnt(0)
	s_barrier
	global_load_dwordx4 v[52:55], v[2:3], off
	s_movk_i32 s2, 0x2000
	v_add_co_u32_e32 v4, vcc, s2, v2
	s_movk_i32 s2, 0x4000
	s_nop 0
	v_addc_co_u32_e32 v5, vcc, 0, v3, vcc
	global_load_dwordx4 v[42:45], v[4:5], off offset:-4096
	global_load_dwordx4 v[38:41], v[4:5], off
	v_add_co_u32_e32 v4, vcc, s2, v2
	s_movk_i32 s2, 0x7000
	s_nop 0
	v_addc_co_u32_e32 v5, vcc, 0, v3, vcc
	global_load_dwordx4 v[34:37], v[4:5], off offset:-4096
	global_load_dwordx4 v[30:33], v[4:5], off
	v_add_co_u32_e32 v4, vcc, s91, v2
	v_and_b32_e32 v14, 15, v186
	s_nop 0
	v_addc_co_u32_e32 v5, vcc, 0, v3, vcc
	global_load_dwordx4 v[10:13], v[4:5], off offset:-4096
	global_load_dwordx4 v[6:9], v[4:5], off
	v_add_co_u32_e32 v2, vcc, s2, v2
	s_movk_i32 s2, 0xfc04
	s_nop 0
	v_addc_co_u32_e32 v3, vcc, 0, v3, vcc
	v_lshlrev_b32_e32 v57, 4, v14
	v_mad_i32_i24 v51, v185, s2, v28
	v_lshl_add_u32 v14, v14, 6, v182
	global_load_dwordx4 v[2:5], v[2:3], off
	ds_read_b32 v56, v51 offset:52224
	ds_read_b32 v58, v51 offset:52736
	ds_read_b128 v[26:29], v14 offset:16384
	ds_read_b128 v[22:25], v14 offset:16400
	ds_read_b128 v[18:21], v14 offset:16416
	ds_read_b128 v[14:17], v14 offset:16432
	v_lshlrev_b64 v[66:67], 7, v[46:47]
	s_waitcnt lgkmcnt(3)
	v_mov_b32_e32 v48, v26
	v_mov_b32_e32 v49, v28
	v_mov_b32_e32 v28, v27
	v_or_b32_e32 v68, s14, v184
	v_and_b32_e32 v50, 31, v186
	v_ashrrev_i32_e32 v69, 31, v68
	v_or_b32_e32 v66, v185, v66
	s_add_i32 s15, s15, s99
	s_cmp_ge_i32 s15, s6
	s_waitcnt vmcnt(7)
	v_lshlrev_b32_e32 v60, 16, v52
	v_and_b32_e32 v61, 0xffff0000, v52
	v_pk_add_f32 v[60:61], v[60:61], v[48:49] neg_lo:[0,1] neg_hi:[0,1]
	v_lshlrev_b32_e32 v52, 16, v53
	v_pk_mul_f32 v[26:27], v[60:61], v[28:29]
	v_and_b32_e32 v53, 0xffff0000, v53
	v_pk_fma_f32 v[60:61], v[56:57], v[26:27], v[58:59] op_sel_hi:[0,1,0]
	s_waitcnt lgkmcnt(2)
	v_mov_b32_e32 v26, v22
	v_mov_b32_e32 v27, v24
	v_pk_add_f32 v[52:53], v[52:53], v[26:27] neg_lo:[0,1] neg_hi:[0,1]
	v_mov_b32_e32 v24, v23
	v_pk_mul_f32 v[22:23], v[52:53], v[24:25]
	v_lshlrev_b32_e32 v52, 16, v54
	v_pk_fma_f32 v[62:63], v[56:57], v[22:23], v[58:59] op_sel_hi:[0,1,0]
	v_and_b32_e32 v53, 0xffff0000, v54
	s_waitcnt lgkmcnt(1)
	v_mov_b32_e32 v22, v18
	v_mov_b32_e32 v23, v20
	v_pk_add_f32 v[52:53], v[52:53], v[22:23] neg_lo:[0,1] neg_hi:[0,1]
	v_mov_b32_e32 v20, v19
	v_pk_mul_f32 v[18:19], v[52:53], v[20:21]
	v_lshlrev_b32_e32 v52, 16, v55
	v_pk_fma_f32 v[64:65], v[56:57], v[18:19], v[58:59] op_sel_hi:[0,1,0]
	v_and_b32_e32 v53, 0xffff0000, v55
	s_waitcnt lgkmcnt(0)
	v_mov_b32_e32 v18, v14
	v_mov_b32_e32 v19, v16
	v_pk_add_f32 v[52:53], v[52:53], v[18:19] neg_lo:[0,1] neg_hi:[0,1]
	v_mov_b32_e32 v16, v15
	v_pk_mul_f32 v[14:15], v[52:53], v[16:17]
	v_cvt_pk_bf16_f32 v52, v60, v61
	v_pk_fma_f32 v[14:15], v[56:57], v[14:15], v[58:59] op_sel_hi:[0,1,0]
	v_cvt_pk_bf16_f32 v55, v14, v15
	v_mul_u32_u24_e32 v14, 0x110, v185
	v_cvt_pk_bf16_f32 v53, v62, v63
	v_cvt_pk_bf16_f32 v54, v64, v65
	v_add3_u32 v15, v182, v57, v14
	ds_write_b128 v15, v[52:55] offset:17408
	ds_read_b32 v14, v51 offset:52288
	ds_read_b32 v46, v51 offset:52800
	s_waitcnt vmcnt(6)
	v_lshlrev_b32_e32 v52, 16, v42
	v_and_b32_e32 v53, 0xffff0000, v42
	v_lshlrev_b32_e32 v42, 16, v43
	v_and_b32_e32 v43, 0xffff0000, v43
	v_pk_add_f32 v[42:43], v[42:43], v[26:27] neg_lo:[0,1] neg_hi:[0,1]
	v_pk_add_f32 v[52:53], v[52:53], v[48:49] neg_lo:[0,1] neg_hi:[0,1]
	v_pk_mul_f32 v[42:43], v[42:43], v[24:25]
	v_pk_mul_f32 v[52:53], v[52:53], v[28:29]
	s_waitcnt lgkmcnt(0)
	v_pk_fma_f32 v[54:55], v[42:43], v[14:15], v[46:47] op_sel_hi:[1,0,0]
	v_lshlrev_b32_e32 v42, 16, v44
	v_and_b32_e32 v43, 0xffff0000, v44
	v_pk_add_f32 v[42:43], v[42:43], v[22:23] neg_lo:[0,1] neg_hi:[0,1]
	v_pk_fma_f32 v[52:53], v[52:53], v[14:15], v[46:47] op_sel_hi:[1,0,0]
	v_pk_mul_f32 v[42:43], v[42:43], v[20:21]
	s_nop 0
	v_pk_fma_f32 v[56:57], v[42:43], v[14:15], v[46:47] op_sel_hi:[1,0,0]
	v_lshlrev_b32_e32 v42, 16, v45
	v_and_b32_e32 v43, 0xffff0000, v45
	v_pk_add_f32 v[42:43], v[42:43], v[18:19] neg_lo:[0,1] neg_hi:[0,1]
	v_cvt_pk_bf16_f32 v44, v56, v57
	v_pk_mul_f32 v[42:43], v[42:43], v[16:17]
	s_nop 0
	v_pk_fma_f32 v[46:47], v[42:43], v[14:15], v[46:47] op_sel_hi:[1,0,0]
	v_cvt_pk_bf16_f32 v42, v52, v53
	v_cvt_pk_bf16_f32 v43, v54, v55
	v_cvt_pk_bf16_f32 v45, v46, v47
	ds_write_b128 v15, v[42:45] offset:21760
	ds_read_b32 v14, v51 offset:52352
	ds_read_b32 v42, v51 offset:52864
	s_waitcnt vmcnt(5)
	v_lshlrev_b32_e32 v44, 16, v38
	v_and_b32_e32 v45, 0xffff0000, v38
	v_lshlrev_b32_e32 v38, 16, v39
	v_and_b32_e32 v39, 0xffff0000, v39
	v_pk_add_f32 v[38:39], v[38:39], v[26:27] neg_lo:[0,1] neg_hi:[0,1]
	v_pk_add_f32 v[44:45], v[44:45], v[48:49] neg_lo:[0,1] neg_hi:[0,1]
	v_pk_mul_f32 v[38:39], v[38:39], v[24:25]
	v_pk_mul_f32 v[44:45], v[44:45], v[28:29]
	s_waitcnt lgkmcnt(0)
	v_pk_fma_f32 v[46:47], v[38:39], v[14:15], v[42:43] op_sel_hi:[1,0,0]
	v_lshlrev_b32_e32 v38, 16, v40
	v_and_b32_e32 v39, 0xffff0000, v40
	v_pk_add_f32 v[38:39], v[38:39], v[22:23] neg_lo:[0,1] neg_hi:[0,1]
	v_pk_fma_f32 v[44:45], v[44:45], v[14:15], v[42:43] op_sel_hi:[1,0,0]
	v_pk_mul_f32 v[38:39], v[38:39], v[20:21]
	s_nop 0
	v_pk_fma_f32 v[52:53], v[38:39], v[14:15], v[42:43] op_sel_hi:[1,0,0]
	v_lshlrev_b32_e32 v38, 16, v41
	v_and_b32_e32 v39, 0xffff0000, v41
	v_pk_add_f32 v[38:39], v[38:39], v[18:19] neg_lo:[0,1] neg_hi:[0,1]
	v_cvt_pk_bf16_f32 v40, v52, v53
	v_pk_mul_f32 v[38:39], v[38:39], v[16:17]
	s_nop 0
	v_pk_fma_f32 v[42:43], v[38:39], v[14:15], v[42:43] op_sel_hi:[1,0,0]
	v_cvt_pk_bf16_f32 v38, v44, v45
	v_cvt_pk_bf16_f32 v39, v46, v47
	v_cvt_pk_bf16_f32 v41, v42, v43
	ds_write_b128 v15, v[38:41] offset:26112
	ds_read_b32 v14, v51 offset:52416
	ds_read_b32 v38, v51 offset:52928
	s_waitcnt vmcnt(4)
	v_lshlrev_b32_e32 v40, 16, v34
	v_and_b32_e32 v41, 0xffff0000, v34
	v_lshlrev_b32_e32 v34, 16, v35
	v_and_b32_e32 v35, 0xffff0000, v35
	v_pk_add_f32 v[34:35], v[34:35], v[26:27] neg_lo:[0,1] neg_hi:[0,1]
	v_pk_add_f32 v[40:41], v[40:41], v[48:49] neg_lo:[0,1] neg_hi:[0,1]
	v_pk_mul_f32 v[34:35], v[34:35], v[24:25]
	v_pk_mul_f32 v[40:41], v[40:41], v[28:29]
	s_waitcnt lgkmcnt(0)
	v_pk_fma_f32 v[42:43], v[34:35], v[14:15], v[38:39] op_sel_hi:[1,0,0]
	v_lshlrev_b32_e32 v34, 16, v36
	v_and_b32_e32 v35, 0xffff0000, v36
	v_pk_add_f32 v[34:35], v[34:35], v[22:23] neg_lo:[0,1] neg_hi:[0,1]
	v_pk_fma_f32 v[40:41], v[40:41], v[14:15], v[38:39] op_sel_hi:[1,0,0]
	v_pk_mul_f32 v[34:35], v[34:35], v[20:21]
	s_nop 0
	v_pk_fma_f32 v[44:45], v[34:35], v[14:15], v[38:39] op_sel_hi:[1,0,0]
	v_lshlrev_b32_e32 v34, 16, v37
	v_and_b32_e32 v35, 0xffff0000, v37
	v_pk_add_f32 v[34:35], v[34:35], v[18:19] neg_lo:[0,1] neg_hi:[0,1]
	v_cvt_pk_bf16_f32 v36, v44, v45
	v_pk_mul_f32 v[34:35], v[34:35], v[16:17]
	s_nop 0
	v_pk_fma_f32 v[38:39], v[34:35], v[14:15], v[38:39] op_sel_hi:[1,0,0]
	v_cvt_pk_bf16_f32 v34, v40, v41
	v_cvt_pk_bf16_f32 v35, v42, v43
	v_cvt_pk_bf16_f32 v37, v38, v39
	ds_write_b128 v15, v[34:37] offset:30464
	ds_read_b32 v14, v51 offset:52480
	ds_read_b32 v34, v51 offset:52992
	s_waitcnt vmcnt(3)
	v_lshlrev_b32_e32 v36, 16, v30
	v_and_b32_e32 v37, 0xffff0000, v30
	v_lshlrev_b32_e32 v30, 16, v31
	v_and_b32_e32 v31, 0xffff0000, v31
	v_pk_add_f32 v[30:31], v[30:31], v[26:27] neg_lo:[0,1] neg_hi:[0,1]
	v_pk_add_f32 v[36:37], v[36:37], v[48:49] neg_lo:[0,1] neg_hi:[0,1]
	v_pk_mul_f32 v[30:31], v[30:31], v[24:25]
	v_pk_mul_f32 v[36:37], v[36:37], v[28:29]
	s_waitcnt lgkmcnt(0)
	v_pk_fma_f32 v[38:39], v[30:31], v[14:15], v[34:35] op_sel_hi:[1,0,0]
	v_lshlrev_b32_e32 v30, 16, v32
	v_and_b32_e32 v31, 0xffff0000, v32
	v_pk_add_f32 v[30:31], v[30:31], v[22:23] neg_lo:[0,1] neg_hi:[0,1]
	v_pk_fma_f32 v[36:37], v[36:37], v[14:15], v[34:35] op_sel_hi:[1,0,0]
	v_pk_mul_f32 v[30:31], v[30:31], v[20:21]
	s_nop 0
	v_pk_fma_f32 v[40:41], v[30:31], v[14:15], v[34:35] op_sel_hi:[1,0,0]
	v_lshlrev_b32_e32 v30, 16, v33
	v_and_b32_e32 v31, 0xffff0000, v33
	v_pk_add_f32 v[30:31], v[30:31], v[18:19] neg_lo:[0,1] neg_hi:[0,1]
	v_cvt_pk_bf16_f32 v32, v40, v41
	v_pk_mul_f32 v[30:31], v[30:31], v[16:17]
	s_nop 0
	v_pk_fma_f32 v[34:35], v[30:31], v[14:15], v[34:35] op_sel_hi:[1,0,0]
	v_cvt_pk_bf16_f32 v30, v36, v37
	v_cvt_pk_bf16_f32 v31, v38, v39
	v_cvt_pk_bf16_f32 v33, v34, v35
	ds_write_b128 v15, v[30:33] offset:34816
	ds_read_b32 v14, v51 offset:52544
	ds_read_b32 v30, v51 offset:53056
	s_waitcnt vmcnt(2)
	v_lshlrev_b32_e32 v32, 16, v10
	v_and_b32_e32 v33, 0xffff0000, v10
	v_lshlrev_b32_e32 v10, 16, v11
	v_and_b32_e32 v11, 0xffff0000, v11
	v_pk_add_f32 v[10:11], v[10:11], v[26:27] neg_lo:[0,1] neg_hi:[0,1]
	v_pk_add_f32 v[32:33], v[32:33], v[48:49] neg_lo:[0,1] neg_hi:[0,1]
	v_pk_mul_f32 v[10:11], v[10:11], v[24:25]
	v_pk_mul_f32 v[32:33], v[32:33], v[28:29]
	s_waitcnt lgkmcnt(0)
	v_pk_fma_f32 v[34:35], v[10:11], v[14:15], v[30:31] op_sel_hi:[1,0,0]
	v_lshlrev_b32_e32 v10, 16, v12
	v_and_b32_e32 v11, 0xffff0000, v12
	v_pk_add_f32 v[10:11], v[10:11], v[22:23] neg_lo:[0,1] neg_hi:[0,1]
	v_pk_fma_f32 v[32:33], v[32:33], v[14:15], v[30:31] op_sel_hi:[1,0,0]
	v_pk_mul_f32 v[10:11], v[10:11], v[20:21]
	s_nop 0
	v_pk_fma_f32 v[36:37], v[10:11], v[14:15], v[30:31] op_sel_hi:[1,0,0]
	v_lshlrev_b32_e32 v10, 16, v13
	v_and_b32_e32 v11, 0xffff0000, v13
	v_pk_add_f32 v[10:11], v[10:11], v[18:19] neg_lo:[0,1] neg_hi:[0,1]
	v_cvt_pk_bf16_f32 v12, v36, v37
	v_pk_mul_f32 v[10:11], v[10:11], v[16:17]
	s_nop 0
	v_pk_fma_f32 v[30:31], v[10:11], v[14:15], v[30:31] op_sel_hi:[1,0,0]
	v_cvt_pk_bf16_f32 v10, v32, v33
	v_cvt_pk_bf16_f32 v11, v34, v35
	v_cvt_pk_bf16_f32 v13, v30, v31
	ds_write_b128 v15, v[10:13] offset:39168
	ds_read_b32 v10, v51 offset:52608
	ds_read_b32 v12, v51 offset:53120
	s_waitcnt vmcnt(1)
	v_lshlrev_b32_e32 v30, 16, v6
	v_and_b32_e32 v31, 0xffff0000, v6
	v_lshlrev_b32_e32 v6, 16, v7
	v_and_b32_e32 v7, 0xffff0000, v7
	v_pk_add_f32 v[6:7], v[6:7], v[26:27] neg_lo:[0,1] neg_hi:[0,1]
	v_pk_add_f32 v[30:31], v[30:31], v[48:49] neg_lo:[0,1] neg_hi:[0,1]
	v_pk_mul_f32 v[6:7], v[6:7], v[24:25]
	v_pk_mul_f32 v[30:31], v[30:31], v[28:29]
	s_waitcnt lgkmcnt(0)
	v_pk_fma_f32 v[32:33], v[6:7], v[10:11], v[12:13] op_sel_hi:[1,0,0]
	v_lshlrev_b32_e32 v6, 16, v8
	v_and_b32_e32 v7, 0xffff0000, v8
	v_pk_add_f32 v[6:7], v[6:7], v[22:23] neg_lo:[0,1] neg_hi:[0,1]
	v_pk_fma_f32 v[30:31], v[30:31], v[10:11], v[12:13] op_sel_hi:[1,0,0]
	v_pk_mul_f32 v[6:7], v[6:7], v[20:21]
	s_nop 0
	v_pk_fma_f32 v[34:35], v[6:7], v[10:11], v[12:13] op_sel_hi:[1,0,0]
	v_lshlrev_b32_e32 v6, 16, v9
	v_and_b32_e32 v7, 0xffff0000, v9
	v_pk_add_f32 v[6:7], v[6:7], v[18:19] neg_lo:[0,1] neg_hi:[0,1]
	v_cvt_pk_bf16_f32 v8, v34, v35
	v_pk_mul_f32 v[6:7], v[6:7], v[16:17]
	s_nop 0
	v_pk_fma_f32 v[10:11], v[6:7], v[10:11], v[12:13] op_sel_hi:[1,0,0]
	v_cvt_pk_bf16_f32 v6, v30, v31
	v_cvt_pk_bf16_f32 v7, v32, v33
	v_cvt_pk_bf16_f32 v9, v10, v11
	ds_write_b128 v15, v[6:9] offset:43520
	ds_read_b32 v6, v51 offset:52672
	ds_read_b32 v8, v51 offset:53184
	s_waitcnt vmcnt(0)
	v_lshlrev_b32_e32 v10, 16, v2
	v_and_b32_e32 v11, 0xffff0000, v2
	v_lshlrev_b32_e32 v2, 16, v3
	v_and_b32_e32 v3, 0xffff0000, v3
	v_pk_add_f32 v[2:3], v[2:3], v[26:27] neg_lo:[0,1] neg_hi:[0,1]
	v_pk_add_f32 v[10:11], v[10:11], v[48:49] neg_lo:[0,1] neg_hi:[0,1]
	v_pk_mul_f32 v[2:3], v[2:3], v[24:25]
	v_pk_mul_f32 v[10:11], v[10:11], v[28:29]
	s_waitcnt lgkmcnt(0)
	v_pk_fma_f32 v[12:13], v[2:3], v[6:7], v[8:9] op_sel_hi:[1,0,0]
	v_lshlrev_b32_e32 v2, 16, v4
	v_and_b32_e32 v3, 0xffff0000, v4
	v_pk_add_f32 v[2:3], v[2:3], v[22:23] neg_lo:[0,1] neg_hi:[0,1]
	v_pk_fma_f32 v[10:11], v[10:11], v[6:7], v[8:9] op_sel_hi:[1,0,0]
	v_pk_mul_f32 v[2:3], v[2:3], v[20:21]
	s_nop 0
	v_pk_fma_f32 v[20:21], v[2:3], v[6:7], v[8:9] op_sel_hi:[1,0,0]
	v_lshlrev_b32_e32 v2, 16, v5
	v_and_b32_e32 v3, 0xffff0000, v5
	v_pk_add_f32 v[2:3], v[2:3], v[18:19] neg_lo:[0,1] neg_hi:[0,1]
	v_cvt_pk_bf16_f32 v4, v20, v21
	v_pk_mul_f32 v[2:3], v[2:3], v[16:17]
	s_nop 0
	v_pk_fma_f32 v[6:7], v[2:3], v[6:7], v[8:9] op_sel_hi:[1,0,0]
	v_cvt_pk_bf16_f32 v2, v10, v11
	v_cvt_pk_bf16_f32 v3, v12, v13
	v_cvt_pk_bf16_f32 v5, v6, v7
	ds_write_b128 v15, v[2:5] offset:47872
	s_waitcnt lgkmcnt(0)
	s_barrier
	s_load_dwordx2 s[2:3], s[12:13], 0x120
	v_lshrrev_b32_e32 v4, 1, v186
	v_lshlrev_b64 v[2:3], 15, v[68:69]
	v_and_or_b32 v69, v4, s73, v50
	v_lshlrev_b32_e32 v4, 8, v69
	s_waitcnt lgkmcnt(0)
	v_lshl_add_u64 v[2:3], s[2:3], 0, v[2:3]
	v_mov_b32_e32 v5, v1
	v_lshl_add_u64 v[2:3], v[2:3], 0, v[4:5]
	v_lshrrev_b32_e32 v4, 2, v186
	v_and_b32_e32 v70, 8, v4
	v_lshlrev_b32_e32 v6, 1, v70
	v_mov_b32_e32 v7, v1
	v_lshl_add_u64 v[80:81], v[2:3], 0, v[6:7]
	global_load_dwordx4 v[2:5], v[80:81], off
	v_mul_u32_u24_e32 v7, 0x88, v50
	v_lshlrev_b32_e32 v7, 1, v7
	v_add3_u32 v71, v182, v6, v7
	ds_read_b128 v[6:9], v71 offset:17408
	ds_read_b128 v[72:75], v71 offset:17440
	global_load_dwordx4 v[76:79], v[80:81], off offset:32
	s_waitcnt vmcnt(1) lgkmcnt(1)
	v_mfma_f32_32x32x16_bf16 v[50:65], v[6:9], v[2:5], 0
	ds_read_b128 v[6:9], v71 offset:26112
	s_load_dwordx2 s[4:5], s[12:13], 0x70
	s_waitcnt vmcnt(0) lgkmcnt(0)
	v_mfma_f32_32x32x16_bf16 v[50:65], v[72:75], v[76:79], v[50:65]
	ds_read_b128 v[72:75], v71 offset:26144
	v_mfma_f32_32x32x16_bf16 v[34:49], v[6:9], v[2:5], 0
	ds_read_b128 v[6:9], v71 offset:34816
	s_waitcnt lgkmcnt(1)
	v_mfma_f32_32x32x16_bf16 v[34:49], v[72:75], v[76:79], v[34:49]
	ds_read_b128 v[72:75], v71 offset:34848
	s_waitcnt lgkmcnt(1)
	v_mfma_f32_32x32x16_bf16 v[18:33], v[6:9], v[2:5], 0
	ds_read_b128 v[6:9], v71 offset:43520
	s_waitcnt lgkmcnt(1)
	v_mfma_f32_32x32x16_bf16 v[18:33], v[72:75], v[76:79], v[18:33]
	ds_read_b128 v[72:75], v71 offset:43552
	s_waitcnt lgkmcnt(1)
	v_mfma_f32_32x32x16_bf16 v[2:17], v[6:9], v[2:5], 0
	s_waitcnt lgkmcnt(0)
	v_mfma_f32_32x32x16_bf16 v[2:17], v[72:75], v[76:79], v[2:17]
	global_load_dwordx4 v[72:75], v[80:81], off offset:64
	ds_read_b128 v[76:79], v71 offset:17472
	s_waitcnt vmcnt(0) lgkmcnt(0)
	v_mfma_f32_32x32x16_bf16 v[50:65], v[76:79], v[72:75], v[50:65]
	ds_read_b128 v[76:79], v71 offset:26176
	s_waitcnt lgkmcnt(0)
	v_mfma_f32_32x32x16_bf16 v[34:49], v[76:79], v[72:75], v[34:49]
	ds_read_b128 v[76:79], v71 offset:34880
	s_waitcnt lgkmcnt(0)
	v_mfma_f32_32x32x16_bf16 v[18:33], v[76:79], v[72:75], v[18:33]
	ds_read_b128 v[76:79], v71 offset:43584
	s_waitcnt lgkmcnt(0)
	v_mfma_f32_32x32x16_bf16 v[2:17], v[76:79], v[72:75], v[2:17]
	global_load_dwordx4 v[72:75], v[80:81], off offset:96
	ds_read_b128 v[76:79], v71 offset:17504
	s_waitcnt vmcnt(0) lgkmcnt(0)
	v_mfma_f32_32x32x16_bf16 v[50:65], v[76:79], v[72:75], v[50:65]
	ds_read_b128 v[76:79], v71 offset:26208
	s_waitcnt lgkmcnt(0)
	v_mfma_f32_32x32x16_bf16 v[34:49], v[76:79], v[72:75], v[34:49]
	ds_read_b128 v[76:79], v71 offset:34912
	s_waitcnt lgkmcnt(0)
	v_mfma_f32_32x32x16_bf16 v[18:33], v[76:79], v[72:75], v[18:33]
	ds_read_b128 v[76:79], v71 offset:43616
	s_waitcnt lgkmcnt(0)
	v_mfma_f32_32x32x16_bf16 v[2:17], v[76:79], v[72:75], v[2:17]
	global_load_dwordx4 v[72:75], v[80:81], off offset:128
	ds_read_b128 v[76:79], v71 offset:17536
	s_waitcnt vmcnt(0) lgkmcnt(0)
	v_mfma_f32_32x32x16_bf16 v[50:65], v[76:79], v[72:75], v[50:65]
	ds_read_b128 v[76:79], v71 offset:26240
	s_waitcnt lgkmcnt(0)
	v_mfma_f32_32x32x16_bf16 v[34:49], v[76:79], v[72:75], v[34:49]
	ds_read_b128 v[76:79], v71 offset:34944
	s_waitcnt lgkmcnt(0)
	v_mfma_f32_32x32x16_bf16 v[18:33], v[76:79], v[72:75], v[18:33]
	ds_read_b128 v[76:79], v71 offset:43648
	s_waitcnt lgkmcnt(0)
	v_mfma_f32_32x32x16_bf16 v[2:17], v[76:79], v[72:75], v[2:17]
	global_load_dwordx4 v[72:75], v[80:81], off offset:160
	ds_read_b128 v[76:79], v71 offset:17568
	s_waitcnt vmcnt(0) lgkmcnt(0)
	v_mfma_f32_32x32x16_bf16 v[50:65], v[76:79], v[72:75], v[50:65]
	ds_read_b128 v[76:79], v71 offset:26272
	s_waitcnt lgkmcnt(0)
	v_mfma_f32_32x32x16_bf16 v[34:49], v[76:79], v[72:75], v[34:49]
	ds_read_b128 v[76:79], v71 offset:34976
	s_waitcnt lgkmcnt(0)
	v_mfma_f32_32x32x16_bf16 v[18:33], v[76:79], v[72:75], v[18:33]
	ds_read_b128 v[76:79], v71 offset:43680
	s_waitcnt lgkmcnt(0)
	v_mfma_f32_32x32x16_bf16 v[2:17], v[76:79], v[72:75], v[2:17]
	global_load_dwordx4 v[72:75], v[80:81], off offset:192
	ds_read_b128 v[76:79], v71 offset:17600
	s_waitcnt vmcnt(0) lgkmcnt(0)
	v_mfma_f32_32x32x16_bf16 v[50:65], v[76:79], v[72:75], v[50:65]
	ds_read_b128 v[76:79], v71 offset:26304
	s_waitcnt lgkmcnt(0)
	v_mfma_f32_32x32x16_bf16 v[34:49], v[76:79], v[72:75], v[34:49]
	ds_read_b128 v[76:79], v71 offset:35008
	s_waitcnt lgkmcnt(0)
	v_mfma_f32_32x32x16_bf16 v[18:33], v[76:79], v[72:75], v[18:33]
	ds_read_b128 v[76:79], v71 offset:43712
	s_waitcnt lgkmcnt(0)
	v_mfma_f32_32x32x16_bf16 v[2:17], v[76:79], v[72:75], v[2:17]
	global_load_dwordx4 v[72:75], v[80:81], off offset:224
	ds_read_b128 v[76:79], v71 offset:17632
	s_waitcnt vmcnt(0) lgkmcnt(0)
	v_mfma_f32_32x32x16_bf16 v[50:65], v[76:79], v[72:75], v[50:65]
	ds_read_b128 v[76:79], v71 offset:26336
	s_waitcnt lgkmcnt(0)
	v_mfma_f32_32x32x16_bf16 v[34:49], v[76:79], v[72:75], v[34:49]
	ds_read_b128 v[76:79], v71 offset:35040
	s_waitcnt lgkmcnt(0)
	v_mfma_f32_32x32x16_bf16 v[18:33], v[76:79], v[72:75], v[18:33]
	ds_read_b128 v[76:79], v71 offset:43744
	s_waitcnt lgkmcnt(0)
	v_mfma_f32_32x32x16_bf16 v[2:17], v[76:79], v[72:75], v[2:17]
	v_lshl_or_b32 v72, v68, 7, v69
	v_ashrrev_i32_e32 v73, 31, v72
	v_lshl_add_u64 v[72:73], v[72:73], 2, s[4:5]
	global_load_dword v68, v[72:73], off
	v_mul_u32_u24_e32 v69, 0x108, v69
	v_add3_u32 v69, v182, v69, v70
	s_barrier
	s_waitcnt vmcnt(0)
	v_pk_add_f32 v[50:51], v[50:51], v[68:69] op_sel_hi:[1,0]
	v_pk_add_f32 v[52:53], v[52:53], v[68:69] op_sel_hi:[1,0]
	v_pk_add_f32 v[34:35], v[34:35], v[68:69] op_sel_hi:[1,0]
	v_pk_add_f32 v[36:37], v[36:37], v[68:69] op_sel_hi:[1,0]
	v_pk_add_f32 v[18:19], v[18:19], v[68:69] op_sel_hi:[1,0]
	v_pk_add_f32 v[20:21], v[20:21], v[68:69] op_sel_hi:[1,0]
	v_pk_add_f32 v[2:3], v[2:3], v[68:69] op_sel_hi:[1,0]
	v_pk_add_f32 v[4:5], v[4:5], v[68:69] op_sel_hi:[1,0]
	v_cvt_pk_bf16_f32 v50, v50, v51
	v_cvt_pk_bf16_f32 v51, v52, v53
	v_pk_add_f32 v[52:53], v[54:55], v[68:69] op_sel_hi:[1,0]
	v_pk_add_f32 v[54:55], v[56:57], v[68:69] op_sel_hi:[1,0]
	v_cvt_pk_bf16_f32 v34, v34, v35
	v_cvt_pk_bf16_f32 v35, v36, v37
	v_pk_add_f32 v[36:37], v[38:39], v[68:69] op_sel_hi:[1,0]
	v_pk_add_f32 v[38:39], v[40:41], v[68:69] op_sel_hi:[1,0]
	v_cvt_pk_bf16_f32 v18, v18, v19
	v_cvt_pk_bf16_f32 v19, v20, v21
	v_pk_add_f32 v[20:21], v[22:23], v[68:69] op_sel_hi:[1,0]
	v_pk_add_f32 v[22:23], v[24:25], v[68:69] op_sel_hi:[1,0]
	v_cvt_pk_bf16_f32 v2, v2, v3
	v_cvt_pk_bf16_f32 v3, v4, v5
	v_pk_add_f32 v[4:5], v[6:7], v[68:69] op_sel_hi:[1,0]
	v_pk_add_f32 v[6:7], v[8:9], v[68:69] op_sel_hi:[1,0]
	v_cvt_pk_bf16_f32 v52, v52, v53
	v_cvt_pk_bf16_f32 v53, v54, v55
	v_add_u32_e32 v56, 0x4000, v69
	v_cvt_pk_bf16_f32 v36, v36, v37
	v_cvt_pk_bf16_f32 v37, v38, v39
	v_cvt_pk_bf16_f32 v20, v20, v21
	v_cvt_pk_bf16_f32 v21, v22, v23
	v_cvt_pk_bf16_f32 v4, v4, v5
	v_cvt_pk_bf16_f32 v5, v6, v7
	ds_write2_b64 v56, v[50:51], v[52:53] offset0:128 offset1:130
	v_pk_add_f32 v[50:51], v[58:59], v[68:69] op_sel_hi:[1,0]
	v_pk_add_f32 v[52:53], v[60:61], v[68:69] op_sel_hi:[1,0]
	ds_write2_b64 v56, v[34:35], v[36:37] offset0:136 offset1:138
	v_pk_add_f32 v[34:35], v[42:43], v[68:69] op_sel_hi:[1,0]
	v_pk_add_f32 v[36:37], v[44:45], v[68:69] op_sel_hi:[1,0]
	ds_write2_b64 v56, v[18:19], v[20:21] offset0:144 offset1:146
	v_pk_add_f32 v[18:19], v[26:27], v[68:69] op_sel_hi:[1,0]
	v_pk_add_f32 v[20:21], v[28:29], v[68:69] op_sel_hi:[1,0]
	ds_write2_b64 v56, v[2:3], v[4:5] offset0:152 offset1:154
	v_pk_add_f32 v[2:3], v[10:11], v[68:69] op_sel_hi:[1,0]
	v_pk_add_f32 v[4:5], v[12:13], v[68:69] op_sel_hi:[1,0]
	v_cvt_pk_bf16_f32 v50, v50, v51
	v_cvt_pk_bf16_f32 v51, v52, v53
	v_pk_add_f32 v[52:53], v[62:63], v[68:69] op_sel_hi:[1,0]
	v_pk_add_f32 v[54:55], v[64:65], v[68:69] op_sel_hi:[1,0]
	v_cvt_pk_bf16_f32 v34, v34, v35
	v_cvt_pk_bf16_f32 v35, v36, v37
	v_pk_add_f32 v[36:37], v[46:47], v[68:69] op_sel_hi:[1,0]
	v_pk_add_f32 v[38:39], v[48:49], v[68:69] op_sel_hi:[1,0]
	v_cvt_pk_bf16_f32 v18, v18, v19
	v_cvt_pk_bf16_f32 v19, v20, v21
	v_pk_add_f32 v[20:21], v[30:31], v[68:69] op_sel_hi:[1,0]
	v_pk_add_f32 v[22:23], v[32:33], v[68:69] op_sel_hi:[1,0]
	v_cvt_pk_bf16_f32 v2, v2, v3
	v_cvt_pk_bf16_f32 v3, v4, v5
	v_pk_add_f32 v[4:5], v[14:15], v[68:69] op_sel_hi:[1,0]
	v_pk_add_f32 v[6:7], v[16:17], v[68:69] op_sel_hi:[1,0]
	v_cvt_pk_bf16_f32 v52, v52, v53
	v_cvt_pk_bf16_f32 v53, v54, v55
	v_cvt_pk_bf16_f32 v36, v36, v37
	v_cvt_pk_bf16_f32 v37, v38, v39
	v_cvt_pk_bf16_f32 v20, v20, v21
	v_cvt_pk_bf16_f32 v21, v22, v23
	v_cvt_pk_bf16_f32 v4, v4, v5
	v_cvt_pk_bf16_f32 v5, v6, v7
	ds_write2_b64 v56, v[50:51], v[52:53] offset0:132 offset1:134
	ds_write2_b64 v56, v[34:35], v[36:37] offset0:140 offset1:142
	ds_write2_b64 v56, v[18:19], v[20:21] offset0:148 offset1:150
	ds_write2_b64 v56, v[2:3], v[4:5] offset0:156 offset1:158
	s_waitcnt lgkmcnt(0)
	s_barrier
	s_load_dwordx4 s[8:11], s[12:13], 0x150
	v_lshlrev_b32_e32 v8, 8, v184
	v_mov_b32_e32 v9, v1
	v_lshlrev_b64 v[10:11], 13, v[66:67]
	s_waitcnt lgkmcnt(0)
	v_lshl_add_u64 v[2:3], s[10:11], 0, v[8:9]
	v_lshl_add_u64 v[6:7], v[2:3], 0, v[0:1]
	v_mul_u32_u24_e32 v2, 0x108, v185
	v_lshl_add_u64 v[10:11], s[8:9], 0, v[10:11]
	v_add3_u32 v12, v182, v0, v2
	v_lshl_add_u64 v[10:11], v[10:11], 0, v[8:9]
	v_add_u32_e32 v2, 0x4400, v12
	v_lshl_add_u64 v[10:11], v[10:11], 0, v[0:1]
	ds_read2_b64 v[2:5], v2 offset1:1
	global_load_dwordx4 v[14:17], v[10:11], off
	global_load_dwordx4 v[18:21], v[10:11], off offset:1024
	s_waitcnt lgkmcnt(0)
	v_lshlrev_b32_e32 v22, 16, v2
	v_and_b32_e32 v23, 0xffff0000, v2
	s_waitcnt vmcnt(1)
	v_lshlrev_b32_e32 v10, 16, v14
	v_and_b32_e32 v11, 0xffff0000, v14
	v_pk_mul_f32 v[10:11], v[22:23], v[10:11]
	s_waitcnt vmcnt(0)
	v_lshlrev_b32_e32 v22, 16, v18
	v_and_b32_e32 v23, 0xffff0000, v18
	v_pk_mul_f32 v[10:11], v[10:11], v[22:23]
	v_lshlrev_b32_e32 v14, 16, v3
	v_cvt_pk_bf16_f32 v2, v10, v11
	v_lshlrev_b32_e32 v10, 16, v15
	v_and_b32_e32 v11, 0xffff0000, v15
	v_and_b32_e32 v15, 0xffff0000, v3
	v_pk_mul_f32 v[10:11], v[14:15], v[10:11]
	v_lshlrev_b32_e32 v14, 16, v19
	v_and_b32_e32 v15, 0xffff0000, v19
	v_pk_mul_f32 v[10:11], v[10:11], v[14:15]
	v_lshlrev_b32_e32 v14, 16, v4
	v_cvt_pk_bf16_f32 v3, v10, v11
	v_lshlrev_b32_e32 v10, 16, v16
	v_and_b32_e32 v11, 0xffff0000, v16
	v_and_b32_e32 v15, 0xffff0000, v4
	v_pk_mul_f32 v[10:11], v[14:15], v[10:11]
	v_lshlrev_b32_e32 v14, 16, v20
	v_and_b32_e32 v15, 0xffff0000, v20
	v_pk_mul_f32 v[10:11], v[10:11], v[14:15]
	v_lshlrev_b32_e32 v14, 16, v5
	v_cvt_pk_bf16_f32 v4, v10, v11
	v_lshlrev_b32_e32 v10, 16, v17
	v_and_b32_e32 v11, 0xffff0000, v17
	v_and_b32_e32 v15, 0xffff0000, v5
	v_pk_mul_f32 v[10:11], v[14:15], v[10:11]
	v_lshlrev_b32_e32 v14, 16, v21
	v_and_b32_e32 v15, 0xffff0000, v21
	v_pk_mul_f32 v[10:11], v[10:11], v[14:15]
	s_nop 0
	v_cvt_pk_bf16_f32 v5, v10, v11
	v_mad_u64_u32 v[10:11], s[2:3], v66, s92, v[6:7]
	v_mad_i32_i24 v11, v67, s92, v11
	global_store_dwordx4 v[10:11], v[2:5], off sc0 sc1
	v_or_b32_e32 v10, 16, v66
	v_mov_b32_e32 v11, v67
	v_lshlrev_b64 v[14:15], 13, v[10:11]
	v_lshl_add_u64 v[14:15], s[8:9], 0, v[14:15]
	v_lshl_add_u64 v[14:15], v[14:15], 0, v[8:9]
	v_add_u32_e32 v2, 0x5480, v12
	v_lshl_add_u64 v[18:19], v[14:15], 0, v[0:1]
	ds_read2_b64 v[2:5], v2 offset1:1
	global_load_dwordx4 v[14:17], v[18:19], off
	s_nop 0
	global_load_dwordx4 v[18:21], v[18:19], off offset:1024
	v_mad_u64_u32 v[10:11], s[2:3], v10, s92, v[6:7]
	v_mad_i32_i24 v11, v67, s92, v11
	s_waitcnt lgkmcnt(0)
	v_lshlrev_b32_e32 v24, 16, v2
	v_and_b32_e32 v25, 0xffff0000, v2
	s_waitcnt vmcnt(1)
	v_lshlrev_b32_e32 v22, 16, v14
	v_and_b32_e32 v23, 0xffff0000, v14
	v_pk_mul_f32 v[22:23], v[24:25], v[22:23]
	s_waitcnt vmcnt(0)
	v_lshlrev_b32_e32 v24, 16, v18
	v_and_b32_e32 v25, 0xffff0000, v18
	v_pk_mul_f32 v[22:23], v[22:23], v[24:25]
	v_lshlrev_b32_e32 v14, 16, v15
	v_cvt_pk_bf16_f32 v2, v22, v23
	v_and_b32_e32 v15, 0xffff0000, v15
	v_lshlrev_b32_e32 v22, 16, v3
	v_and_b32_e32 v23, 0xffff0000, v3
	v_pk_mul_f32 v[14:15], v[22:23], v[14:15]
	v_lshlrev_b32_e32 v18, 16, v19
	v_and_b32_e32 v19, 0xffff0000, v19
	v_pk_mul_f32 v[14:15], v[14:15], v[18:19]
	v_lshlrev_b32_e32 v18, 16, v4
	v_cvt_pk_bf16_f32 v3, v14, v15
	v_lshlrev_b32_e32 v14, 16, v16
	v_and_b32_e32 v15, 0xffff0000, v16
	v_and_b32_e32 v19, 0xffff0000, v4
	v_pk_mul_f32 v[14:15], v[18:19], v[14:15]
	v_lshlrev_b32_e32 v18, 16, v20
	v_and_b32_e32 v19, 0xffff0000, v20
	v_pk_mul_f32 v[14:15], v[14:15], v[18:19]
	v_lshlrev_b32_e32 v16, 16, v5
	v_cvt_pk_bf16_f32 v4, v14, v15
	v_lshlrev_b32_e32 v14, 16, v17
	v_and_b32_e32 v15, 0xffff0000, v17
	v_and_b32_e32 v17, 0xffff0000, v5
	v_pk_mul_f32 v[14:15], v[16:17], v[14:15]
	v_lshlrev_b32_e32 v16, 16, v21
	v_and_b32_e32 v17, 0xffff0000, v21
	v_pk_mul_f32 v[14:15], v[14:15], v[16:17]
	s_nop 0
	v_cvt_pk_bf16_f32 v5, v14, v15
	global_store_dwordx4 v[10:11], v[2:5], off sc0 sc1
	v_or_b32_e32 v10, 32, v66
	v_mov_b32_e32 v11, v67
	v_lshlrev_b64 v[14:15], 13, v[10:11]
	v_lshl_add_u64 v[14:15], s[8:9], 0, v[14:15]
	v_lshl_add_u64 v[14:15], v[14:15], 0, v[8:9]
	v_add_u32_e32 v2, 0x6500, v12
	v_lshl_add_u64 v[18:19], v[14:15], 0, v[0:1]
	ds_read2_b64 v[2:5], v2 offset1:1
	global_load_dwordx4 v[14:17], v[18:19], off
	s_nop 0
	global_load_dwordx4 v[18:21], v[18:19], off offset:1024
	v_mad_u64_u32 v[10:11], s[2:3], v10, s92, v[6:7]
	v_mad_i32_i24 v11, v67, s92, v11
	s_waitcnt lgkmcnt(0)
	v_lshlrev_b32_e32 v24, 16, v2
	v_and_b32_e32 v25, 0xffff0000, v2
	s_waitcnt vmcnt(1)
	v_lshlrev_b32_e32 v22, 16, v14
	v_and_b32_e32 v23, 0xffff0000, v14
	v_pk_mul_f32 v[22:23], v[24:25], v[22:23]
	s_waitcnt vmcnt(0)
	v_lshlrev_b32_e32 v24, 16, v18
	v_and_b32_e32 v25, 0xffff0000, v18
	v_pk_mul_f32 v[22:23], v[22:23], v[24:25]
	v_lshlrev_b32_e32 v14, 16, v15
	v_cvt_pk_bf16_f32 v2, v22, v23
	v_and_b32_e32 v15, 0xffff0000, v15
	v_lshlrev_b32_e32 v22, 16, v3
	v_and_b32_e32 v23, 0xffff0000, v3
	v_pk_mul_f32 v[14:15], v[22:23], v[14:15]
	v_lshlrev_b32_e32 v18, 16, v19
	v_and_b32_e32 v19, 0xffff0000, v19
	v_pk_mul_f32 v[14:15], v[14:15], v[18:19]
	v_lshlrev_b32_e32 v18, 16, v4
	v_cvt_pk_bf16_f32 v3, v14, v15
	v_lshlrev_b32_e32 v14, 16, v16
	v_and_b32_e32 v15, 0xffff0000, v16
	v_and_b32_e32 v19, 0xffff0000, v4
	v_pk_mul_f32 v[14:15], v[18:19], v[14:15]
	v_lshlrev_b32_e32 v18, 16, v20
	v_and_b32_e32 v19, 0xffff0000, v20
	v_pk_mul_f32 v[14:15], v[14:15], v[18:19]
	v_lshlrev_b32_e32 v16, 16, v5
	v_cvt_pk_bf16_f32 v4, v14, v15
	v_lshlrev_b32_e32 v14, 16, v17
	v_and_b32_e32 v15, 0xffff0000, v17
	v_and_b32_e32 v17, 0xffff0000, v5
	v_pk_mul_f32 v[14:15], v[16:17], v[14:15]
	v_lshlrev_b32_e32 v16, 16, v21
	v_and_b32_e32 v17, 0xffff0000, v21
	v_pk_mul_f32 v[14:15], v[14:15], v[16:17]
	s_nop 0
	v_cvt_pk_bf16_f32 v5, v14, v15
	global_store_dwordx4 v[10:11], v[2:5], off sc0 sc1
	v_or_b32_e32 v10, 48, v66
	v_mov_b32_e32 v11, v67
	v_lshlrev_b64 v[14:15], 13, v[10:11]
	v_lshl_add_u64 v[14:15], s[8:9], 0, v[14:15]
	v_lshl_add_u64 v[14:15], v[14:15], 0, v[8:9]
	v_add_u32_e32 v2, 0x7580, v12
	v_lshl_add_u64 v[18:19], v[14:15], 0, v[0:1]
	ds_read2_b64 v[2:5], v2 offset1:1
	global_load_dwordx4 v[14:17], v[18:19], off
	s_nop 0
	global_load_dwordx4 v[18:21], v[18:19], off offset:1024
	v_mad_u64_u32 v[10:11], s[2:3], v10, s92, v[6:7]
	v_mad_i32_i24 v11, v67, s92, v11
	s_waitcnt lgkmcnt(0)
	v_lshlrev_b32_e32 v24, 16, v2
	v_and_b32_e32 v25, 0xffff0000, v2
	s_waitcnt vmcnt(1)
	v_lshlrev_b32_e32 v22, 16, v14
	v_and_b32_e32 v23, 0xffff0000, v14
	v_pk_mul_f32 v[22:23], v[24:25], v[22:23]
	s_waitcnt vmcnt(0)
	v_lshlrev_b32_e32 v24, 16, v18
	v_and_b32_e32 v25, 0xffff0000, v18
	v_pk_mul_f32 v[22:23], v[22:23], v[24:25]
	v_lshlrev_b32_e32 v14, 16, v15
	v_cvt_pk_bf16_f32 v2, v22, v23
	v_and_b32_e32 v15, 0xffff0000, v15
	v_lshlrev_b32_e32 v22, 16, v3
	v_and_b32_e32 v23, 0xffff0000, v3
	v_pk_mul_f32 v[14:15], v[22:23], v[14:15]
	v_lshlrev_b32_e32 v18, 16, v19
	v_and_b32_e32 v19, 0xffff0000, v19
	v_pk_mul_f32 v[14:15], v[14:15], v[18:19]
	v_lshlrev_b32_e32 v18, 16, v4
	v_cvt_pk_bf16_f32 v3, v14, v15
	v_lshlrev_b32_e32 v14, 16, v16
	v_and_b32_e32 v15, 0xffff0000, v16
	v_and_b32_e32 v19, 0xffff0000, v4
	v_pk_mul_f32 v[14:15], v[18:19], v[14:15]
	v_lshlrev_b32_e32 v18, 16, v20
	v_and_b32_e32 v19, 0xffff0000, v20
	v_pk_mul_f32 v[14:15], v[14:15], v[18:19]
	v_lshlrev_b32_e32 v16, 16, v5
	v_cvt_pk_bf16_f32 v4, v14, v15
	v_lshlrev_b32_e32 v14, 16, v17
	v_and_b32_e32 v15, 0xffff0000, v17
	v_and_b32_e32 v17, 0xffff0000, v5
	v_pk_mul_f32 v[14:15], v[16:17], v[14:15]
	v_lshlrev_b32_e32 v16, 16, v21
	v_and_b32_e32 v17, 0xffff0000, v21
	v_pk_mul_f32 v[14:15], v[14:15], v[16:17]
	s_nop 0
	v_cvt_pk_bf16_f32 v5, v14, v15
	global_store_dwordx4 v[10:11], v[2:5], off sc0 sc1
	v_or_b32_e32 v10, 64, v66
	v_mov_b32_e32 v11, v67
	v_lshlrev_b64 v[14:15], 13, v[10:11]
	v_lshl_add_u64 v[14:15], s[8:9], 0, v[14:15]
	v_lshl_add_u64 v[14:15], v[14:15], 0, v[8:9]
	v_add_u32_e32 v2, 0x8600, v12
	v_lshl_add_u64 v[18:19], v[14:15], 0, v[0:1]
	ds_read2_b64 v[2:5], v2 offset1:1
	global_load_dwordx4 v[14:17], v[18:19], off
	s_nop 0
	global_load_dwordx4 v[18:21], v[18:19], off offset:1024
	v_mad_u64_u32 v[10:11], s[2:3], v10, s92, v[6:7]
	v_mad_i32_i24 v11, v67, s92, v11
	s_waitcnt lgkmcnt(0)
	v_lshlrev_b32_e32 v24, 16, v2
	v_and_b32_e32 v25, 0xffff0000, v2
	s_waitcnt vmcnt(1)
	v_lshlrev_b32_e32 v22, 16, v14
	v_and_b32_e32 v23, 0xffff0000, v14
	v_pk_mul_f32 v[22:23], v[24:25], v[22:23]
	s_waitcnt vmcnt(0)
	v_lshlrev_b32_e32 v24, 16, v18
	v_and_b32_e32 v25, 0xffff0000, v18
	v_pk_mul_f32 v[22:23], v[22:23], v[24:25]
	v_lshlrev_b32_e32 v14, 16, v15
	v_cvt_pk_bf16_f32 v2, v22, v23
	v_and_b32_e32 v15, 0xffff0000, v15
	v_lshlrev_b32_e32 v22, 16, v3
	v_and_b32_e32 v23, 0xffff0000, v3
	v_pk_mul_f32 v[14:15], v[22:23], v[14:15]
	v_lshlrev_b32_e32 v18, 16, v19
	v_and_b32_e32 v19, 0xffff0000, v19
	v_pk_mul_f32 v[14:15], v[14:15], v[18:19]
	v_lshlrev_b32_e32 v18, 16, v4
	v_cvt_pk_bf16_f32 v3, v14, v15
	v_lshlrev_b32_e32 v14, 16, v16
	v_and_b32_e32 v15, 0xffff0000, v16
	v_and_b32_e32 v19, 0xffff0000, v4
	v_pk_mul_f32 v[14:15], v[18:19], v[14:15]
	v_lshlrev_b32_e32 v18, 16, v20
	v_and_b32_e32 v19, 0xffff0000, v20
	v_pk_mul_f32 v[14:15], v[14:15], v[18:19]
	v_lshlrev_b32_e32 v16, 16, v5
	v_cvt_pk_bf16_f32 v4, v14, v15
	v_lshlrev_b32_e32 v14, 16, v17
	v_and_b32_e32 v15, 0xffff0000, v17
	v_and_b32_e32 v17, 0xffff0000, v5
	v_pk_mul_f32 v[14:15], v[16:17], v[14:15]
	v_lshlrev_b32_e32 v16, 16, v21
	v_and_b32_e32 v17, 0xffff0000, v21
	v_pk_mul_f32 v[14:15], v[14:15], v[16:17]
	s_nop 0
	v_cvt_pk_bf16_f32 v5, v14, v15
	global_store_dwordx4 v[10:11], v[2:5], off sc0 sc1
	s_nop 1
	v_or_b32_e32 v2, 0x50, v66
	v_mov_b32_e32 v3, v67
	v_add_u32_e32 v4, 0x9680, v12
	ds_read2_b64 v[14:17], v4 offset1:1
	v_lshlrev_b64 v[4:5], 13, v[2:3]
	v_lshl_add_u64 v[4:5], s[8:9], 0, v[4:5]
	v_lshl_add_u64 v[4:5], v[4:5], 0, v[8:9]
	v_lshl_add_u64 v[4:5], v[4:5], 0, v[0:1]
	global_load_dwordx4 v[18:21], v[4:5], off
	global_load_dwordx4 v[22:25], v[4:5], off offset:1024
	s_waitcnt lgkmcnt(0)
	v_lshlrev_b32_e32 v10, 16, v14
	v_and_b32_e32 v11, 0xffff0000, v14
	v_mad_u64_u32 v[2:3], s[2:3], v2, s92, v[6:7]
	v_mad_i32_i24 v3, v67, s92, v3
	s_waitcnt vmcnt(1)
	v_lshlrev_b32_e32 v4, 16, v18
	v_and_b32_e32 v5, 0xffff0000, v18
	v_pk_mul_f32 v[4:5], v[10:11], v[4:5]
	s_waitcnt vmcnt(0)
	v_lshlrev_b32_e32 v10, 16, v22
	v_and_b32_e32 v11, 0xffff0000, v22
	v_pk_mul_f32 v[4:5], v[4:5], v[10:11]
	v_lshlrev_b32_e32 v10, 16, v15
	v_cvt_pk_bf16_f32 v14, v4, v5
	v_lshlrev_b32_e32 v4, 16, v19
	v_and_b32_e32 v5, 0xffff0000, v19
	v_and_b32_e32 v11, 0xffff0000, v15
	v_pk_mul_f32 v[4:5], v[10:11], v[4:5]
	v_lshlrev_b32_e32 v10, 16, v23
	v_and_b32_e32 v11, 0xffff0000, v23
	v_pk_mul_f32 v[4:5], v[4:5], v[10:11]
	v_lshlrev_b32_e32 v10, 16, v16
	v_cvt_pk_bf16_f32 v15, v4, v5
	v_lshlrev_b32_e32 v4, 16, v20
	v_and_b32_e32 v5, 0xffff0000, v20
	v_and_b32_e32 v11, 0xffff0000, v16
	v_pk_mul_f32 v[4:5], v[10:11], v[4:5]
	v_lshlrev_b32_e32 v10, 16, v24
	v_and_b32_e32 v11, 0xffff0000, v24
	v_pk_mul_f32 v[4:5], v[4:5], v[10:11]
	v_lshlrev_b32_e32 v10, 16, v17
	v_cvt_pk_bf16_f32 v16, v4, v5
	v_lshlrev_b32_e32 v4, 16, v21
	v_and_b32_e32 v5, 0xffff0000, v21
	v_and_b32_e32 v11, 0xffff0000, v17
	v_pk_mul_f32 v[4:5], v[10:11], v[4:5]
	v_lshlrev_b32_e32 v10, 16, v25
	v_and_b32_e32 v11, 0xffff0000, v25
	v_pk_mul_f32 v[4:5], v[4:5], v[10:11]
	v_or_b32_e32 v10, 0x60, v66
	v_cvt_pk_bf16_f32 v17, v4, v5
	v_mov_b32_e32 v11, v67
	global_store_dwordx4 v[2:3], v[14:17], off sc0 sc1
	v_add_u32_e32 v2, 0xa700, v12
	ds_read2_b64 v[2:5], v2 offset1:1
	v_lshlrev_b64 v[14:15], 13, v[10:11]
	v_lshl_add_u64 v[14:15], s[8:9], 0, v[14:15]
	v_lshl_add_u64 v[14:15], v[14:15], 0, v[8:9]
	v_lshl_add_u64 v[18:19], v[14:15], 0, v[0:1]
	global_load_dwordx4 v[14:17], v[18:19], off
	s_nop 0
	global_load_dwordx4 v[18:21], v[18:19], off offset:1024
	s_waitcnt lgkmcnt(0)
	v_lshlrev_b32_e32 v24, 16, v2
	v_and_b32_e32 v25, 0xffff0000, v2
	v_mad_u64_u32 v[10:11], s[2:3], v10, s92, v[6:7]
	v_mad_i32_i24 v11, v67, s92, v11
	v_or_b32_e32 v66, 0x70, v66
	v_mad_u64_u32 v[6:7], s[2:3], v66, s92, v[6:7]
	v_readlane_b32 s2, v252, 17
	v_mad_i32_i24 v7, v67, s92, v7
	s_waitcnt vmcnt(1)
	v_lshlrev_b32_e32 v22, 16, v14
	v_and_b32_e32 v23, 0xffff0000, v14
	v_pk_mul_f32 v[22:23], v[24:25], v[22:23]
	s_waitcnt vmcnt(0)
	v_lshlrev_b32_e32 v24, 16, v18
	v_and_b32_e32 v25, 0xffff0000, v18
	v_pk_mul_f32 v[22:23], v[22:23], v[24:25]
	v_lshlrev_b32_e32 v14, 16, v15
	v_cvt_pk_bf16_f32 v2, v22, v23
	v_and_b32_e32 v15, 0xffff0000, v15
	v_lshlrev_b32_e32 v22, 16, v3
	v_and_b32_e32 v23, 0xffff0000, v3
	v_pk_mul_f32 v[14:15], v[22:23], v[14:15]
	v_lshlrev_b32_e32 v18, 16, v19
	v_and_b32_e32 v19, 0xffff0000, v19
	v_pk_mul_f32 v[14:15], v[14:15], v[18:19]
	v_lshlrev_b32_e32 v18, 16, v4
	v_cvt_pk_bf16_f32 v3, v14, v15
	v_lshlrev_b32_e32 v14, 16, v16
	v_and_b32_e32 v15, 0xffff0000, v16
	v_and_b32_e32 v19, 0xffff0000, v4
	v_pk_mul_f32 v[14:15], v[18:19], v[14:15]
	v_lshlrev_b32_e32 v18, 16, v20
	v_and_b32_e32 v19, 0xffff0000, v20
	v_pk_mul_f32 v[14:15], v[14:15], v[18:19]
	v_lshlrev_b32_e32 v16, 16, v5
	v_cvt_pk_bf16_f32 v4, v14, v15
	v_lshlrev_b32_e32 v14, 16, v17
	v_and_b32_e32 v15, 0xffff0000, v17
	v_and_b32_e32 v17, 0xffff0000, v5
	v_pk_mul_f32 v[14:15], v[16:17], v[14:15]
	v_lshlrev_b32_e32 v16, 16, v21
	v_and_b32_e32 v17, 0xffff0000, v21
	v_pk_mul_f32 v[14:15], v[14:15], v[16:17]
	v_add_u32_e32 v183, s2, v183
	v_cvt_pk_bf16_f32 v5, v14, v15
	global_store_dwordx4 v[10:11], v[2:5], off sc0 sc1
	v_lshlrev_b64 v[10:11], 13, v[66:67]
	v_lshl_add_u64 v[10:11], s[8:9], 0, v[10:11]
	v_lshl_add_u64 v[8:9], v[10:11], 0, v[8:9]
	v_add_u32_e32 v2, 0xb780, v12
	v_lshl_add_u64 v[12:13], v[8:9], 0, v[0:1]
	ds_read2_b64 v[2:5], v2 offset1:1
	global_load_dwordx4 v[8:11], v[12:13], off
	s_nop 0
	global_load_dwordx4 v[12:15], v[12:13], off offset:1024
	s_waitcnt lgkmcnt(0)
	v_lshlrev_b32_e32 v18, 16, v2
	v_and_b32_e32 v19, 0xffff0000, v2
	s_waitcnt vmcnt(1)
	v_lshlrev_b32_e32 v16, 16, v8
	v_and_b32_e32 v17, 0xffff0000, v8
	v_pk_mul_f32 v[16:17], v[18:19], v[16:17]
	s_waitcnt vmcnt(0)
	v_lshlrev_b32_e32 v18, 16, v12
	v_and_b32_e32 v19, 0xffff0000, v12
	v_pk_mul_f32 v[16:17], v[16:17], v[18:19]
	v_lshlrev_b32_e32 v8, 16, v9
	v_cvt_pk_bf16_f32 v2, v16, v17
	v_and_b32_e32 v9, 0xffff0000, v9
	v_lshlrev_b32_e32 v16, 16, v3
	v_and_b32_e32 v17, 0xffff0000, v3
	v_pk_mul_f32 v[8:9], v[16:17], v[8:9]
	v_lshlrev_b32_e32 v12, 16, v13
	v_and_b32_e32 v13, 0xffff0000, v13
	v_pk_mul_f32 v[8:9], v[8:9], v[12:13]
	v_lshlrev_b32_e32 v12, 16, v4
	v_cvt_pk_bf16_f32 v3, v8, v9
	v_lshlrev_b32_e32 v8, 16, v10
	v_and_b32_e32 v9, 0xffff0000, v10
	v_and_b32_e32 v13, 0xffff0000, v4
	v_pk_mul_f32 v[8:9], v[12:13], v[8:9]
	v_lshlrev_b32_e32 v12, 16, v14
	v_and_b32_e32 v13, 0xffff0000, v14
	v_pk_mul_f32 v[8:9], v[8:9], v[12:13]
	v_lshlrev_b32_e32 v10, 16, v5
	v_cvt_pk_bf16_f32 v4, v8, v9
	v_lshlrev_b32_e32 v8, 16, v11
	v_and_b32_e32 v9, 0xffff0000, v11
	v_and_b32_e32 v11, 0xffff0000, v5
	v_pk_mul_f32 v[8:9], v[10:11], v[8:9]
	v_lshlrev_b32_e32 v10, 16, v15
	v_and_b32_e32 v11, 0xffff0000, v15
	v_pk_mul_f32 v[8:9], v[8:9], v[10:11]
	s_nop 0
	v_cvt_pk_bf16_f32 v5, v8, v9
	global_store_dwordx4 v[6:7], v[2:5], off sc0 sc1
	s_cbranch_scc1 .LBB0_292

.LBB0_301:
	s_or_b64 exec, exec, s[10:11]
	s_waitcnt vmcnt(0)
	v_mov_b32_e32 v98, v81
	v_mov_b32_e32 v99, v82
	v_mov_b32_e32 v100, v80
	v_mov_b32_e32 v101, v83
	v_pk_add_f32 v[98:99], v[98:99], v[100:101]
	s_waitcnt vmcnt(2)
	v_mov_b32_e32 v100, v77
	v_mov_b32_e32 v101, v78
	v_mov_b32_e32 v102, v76
	v_mov_b32_e32 v103, v79
	v_pk_add_f32 v[100:101], v[100:101], v[102:103]
	v_add_f32_e32 v0, v98, v99
	v_pk_add_f32 v[100:101], v[100:101], v[100:101] op_sel:[0,1] op_sel_hi:[1,0]
	v_add_f32_e32 v98, 0, v0
	s_waitcnt vmcnt(1)
	v_add_f32_e32 v102, v72, v73
	v_add_f32_e32 v104, v74, v75
	s_waitcnt vmcnt(0)
	v_mov_b32_e32 v99, v68
	v_mov_b32_e32 v101, v69
	v_mov_b32_e32 v103, v70
	v_mov_b32_e32 v105, v71
	v_pk_add_f32 v[98:99], v[98:99], v[100:101]
	v_pk_add_f32 v[100:101], v[102:103], v[104:105]
	s_mov_b32 s10, 0x800000
	v_pk_add_f32 v[98:99], v[98:99], v[100:101]
	s_nop 0
	v_add_f32_e32 v0, v98, v99
	s_nop 1
	v_add_f32_dpp v0, v0, v0 quad_perm:[1,0,3,2] row_mask:0xf bank_mask:0xf
	s_nop 1
	v_add_f32_dpp v0, v0, v0 quad_perm:[2,3,0,1] row_mask:0xf bank_mask:0xf
	s_nop 1
	v_add_f32_dpp v0, v0, v0 row_half_mirror row_mask:0xf bank_mask:0xf
	s_nop 1
	v_add_f32_dpp v0, v0, v0 row_mirror row_mask:0xf bank_mask:0xf
	s_nop 1
	v_readlane_b32 s100, v0, 0
	v_readlane_b32 s101, v0, 16
	v_readlane_b32 vcc_lo, v0, 32
	v_readlane_b32 vcc_hi, v0, 48
	s_nop 1
	v_mov_b32_e32 v97, s100
	v_add_f32_e32 v97, s101, v97
	v_add_f32_e32 v97, vcc_lo, v97
	v_add_f32_e32 v97, vcc_hi, v97
	v_fmamk_f32 v81, v97, 0xba800000, v81
	v_fmamk_f32 v80, v97, 0xba800000, v80
	v_fmamk_f32 v83, v97, 0xba800000, v83
	v_fmac_f32_e32 v82, 0xba800000, v97
	v_pk_mul_f32 v[98:99], v[82:83], v[82:83]
	v_pk_mul_f32 v[100:101], v[80:81], v[80:81]
	v_fmamk_f32 v77, v97, 0xba800000, v77
	v_fmamk_f32 v76, v97, 0xba800000, v76
	v_fmamk_f32 v79, v97, 0xba800000, v79
	v_pk_mov_b32 v[102:103], v[100:101], v[98:99] op_sel:[1,0]
	v_mov_b32_e32 v101, v99
	v_fmac_f32_e32 v78, 0xba800000, v97
	v_pk_add_f32 v[98:99], v[102:103], v[100:101]
	v_pk_mul_f32 v[100:101], v[78:79], v[78:79]
	v_pk_mul_f32 v[102:103], v[76:77], v[76:77]
	v_fmamk_f32 v72, v97, 0xba800000, v72
	v_pk_mov_b32 v[104:105], v[102:103], v[100:101] op_sel:[1,0]
	v_mov_b32_e32 v103, v101
	v_fmamk_f32 v73, v97, 0xba800000, v73
	v_fmac_f32_e32 v74, 0xba800000, v97
	v_mul_f32_e32 v0, v72, v72
	v_pk_add_f32 v[100:101], v[104:105], v[102:103]
	v_fmamk_f32 v75, v97, 0xba800000, v75
	v_pk_fma_f32 v[102:103], v[72:73], v[72:73], v[0:1] op_sel_hi:[1,1,0]
	v_mul_f32_e32 v0, v74, v74
	v_pk_add_f32 v[98:99], v[98:99], v[98:99] op_sel_hi:[0,1]
	v_pk_add_f32 v[100:101], v[100:101], v[100:101] op_sel_hi:[0,1]
	v_pk_fma_f32 v[104:105], v[74:75], v[74:75], v[0:1] op_sel_hi:[1,1,0]
	v_fmamk_f32 v71, v97, 0xba800000, v71
	v_fmamk_f32 v70, v97, 0xba800000, v70
	v_fmamk_f32 v69, v97, 0xba800000, v69
	v_fmac_f32_e32 v68, 0xba800000, v97
	v_mul_f32_e32 v102, v68, v68
	v_mul_f32_e32 v104, v69, v69
	v_mul_f32_e32 v98, v70, v70
	v_mul_f32_e32 v100, v71, v71
	v_pk_add_f32 v[102:103], v[102:103], v[104:105]
	v_pk_add_f32 v[98:99], v[98:99], v[100:101]
	s_nop 0
	v_pk_add_f32 v[98:99], v[102:103], v[98:99]
	s_nop 0
	v_add_f32_e32 v0, v98, v99
	s_nop 1
	v_add_f32_dpp v0, v0, v0 quad_perm:[1,0,3,2] row_mask:0xf bank_mask:0xf
	s_nop 1
	v_add_f32_dpp v0, v0, v0 quad_perm:[2,3,0,1] row_mask:0xf bank_mask:0xf
	s_nop 1
	v_add_f32_dpp v0, v0, v0 row_half_mirror row_mask:0xf bank_mask:0xf
	s_nop 1
	v_add_f32_dpp v0, v0, v0 row_mirror row_mask:0xf bank_mask:0xf
	s_nop 1
	v_readlane_b32 s100, v0, 0
	v_readlane_b32 s101, v0, 16
	v_readlane_b32 vcc_lo, v0, 32
	v_readlane_b32 vcc_hi, v0, 48
	s_nop 1
	v_mov_b32_e32 v0, s100
	v_add_f32_e32 v0, s101, v0
	v_add_f32_e32 v0, vcc_lo, v0
	v_add_f32_e32 v0, vcc_hi, v0
	v_fmamk_f32 v0, v0, 0x3a800000, v227
	v_mul_f32_e32 v97, 0x4b800000, v0
	v_cmp_gt_f32_e32 vcc, s10, v0
	s_nop 1
	v_cndmask_b32_e32 v0, v0, v97, vcc
	v_rsq_f32_e32 v0, v0
	s_nop 0
	v_mul_f32_e32 v97, 0x45800000, v0
	v_cndmask_b32_e32 v0, v0, v97, vcc
	v_pk_mul_f32 v[80:81], v[80:81], v[0:1] op_sel_hi:[1,0]
	v_pk_mul_f32 v[82:83], v[82:83], v[0:1] op_sel_hi:[1,0]
	v_pk_mul_f32 v[76:77], v[76:77], v[0:1] op_sel_hi:[1,0]
	v_pk_mul_f32 v[78:79], v[78:79], v[0:1] op_sel_hi:[1,0]
	v_pk_mul_f32 v[72:73], v[72:73], v[0:1] op_sel_hi:[1,0]
	v_pk_mul_f32 v[74:75], v[74:75], v[0:1] op_sel_hi:[1,0]
	v_pk_mul_f32 v[68:69], v[68:69], v[0:1] op_sel_hi:[1,0]
	v_pk_mul_f32 v[70:71], v[70:71], v[0:1] op_sel_hi:[1,0]
	v_pk_fma_f32 v[82:83], v[6:7], v[82:83], v[14:15]
	v_pk_fma_f32 v[80:81], v[4:5], v[80:81], v[12:13]
	v_pk_fma_f32 v[78:79], v[10:11], v[78:79], v[18:19]
	v_pk_fma_f32 v[76:77], v[8:9], v[76:77], v[16:17]
	v_pk_fma_f32 v[74:75], v[22:23], v[74:75], v[30:31]
	v_pk_fma_f32 v[72:73], v[20:21], v[72:73], v[28:29]
	v_pk_fma_f32 v[70:71], v[26:27], v[70:71], v[34:35]
	v_pk_fma_f32 v[68:69], v[24:25], v[68:69], v[32:33]
	s_andn2_b64 vcc, exec, s[4:5]
	global_store_dwordx4 v[88:89], v[80:83], off sc0 sc1
	global_store_dwordx4 v[88:89], v[76:79], off offset:1024 sc0 sc1
	global_store_dwordx4 v[88:89], v[72:75], off offset:2048 sc0 sc1
	global_store_dwordx4 v[88:89], v[68:71], off offset:3072 sc0 sc1
	s_cbranch_vccnz .LBB0_298
	v_mov_b32_e32 v88, v81
	v_mov_b32_e32 v89, v82
	v_mov_b32_e32 v98, v80
	v_mov_b32_e32 v99, v83
	v_pk_add_f32 v[88:89], v[88:89], v[98:99]
	v_mov_b32_e32 v98, v77
	v_mov_b32_e32 v99, v78
	v_mov_b32_e32 v100, v76
	v_mov_b32_e32 v101, v79
	v_pk_add_f32 v[98:99], v[98:99], v[100:101]
	v_add_f32_e32 v0, v88, v89
	v_pk_add_f32 v[98:99], v[98:99], v[98:99] op_sel_hi:[0,1]
	v_add_f32_e32 v89, 0, v0
	v_add_f32_e32 v101, v72, v73
	v_add_f32_e32 v103, v74, v75
	v_mov_b32_e32 v100, v68
	v_mov_b32_e32 v102, v69
	v_mov_b32_e32 v98, v70
	v_mov_b32_e32 v88, v71
	v_pk_add_f32 v[100:101], v[100:101], v[102:103]
	v_pk_add_f32 v[88:89], v[98:99], v[88:89]
	v_lshlrev_b64 v[2:3], 10, v[2:3]
	v_pk_add_f32 v[88:89], v[100:101], v[88:89]
	s_nop 0
	v_add_f32_e32 v0, v88, v89
	s_nop 1
	v_add_f32_dpp v0, v0, v0 quad_perm:[1,0,3,2] row_mask:0xf bank_mask:0xf
	s_nop 1
	v_add_f32_dpp v0, v0, v0 quad_perm:[2,3,0,1] row_mask:0xf bank_mask:0xf
	s_nop 1
	v_add_f32_dpp v0, v0, v0 row_half_mirror row_mask:0xf bank_mask:0xf
	s_nop 1
	v_add_f32_dpp v0, v0, v0 row_mirror row_mask:0xf bank_mask:0xf
	s_nop 1
	v_readlane_b32 s100, v0, 0
	v_readlane_b32 s101, v0, 16
	v_readlane_b32 vcc_lo, v0, 32
	v_readlane_b32 vcc_hi, v0, 48
	s_nop 1
	v_mov_b32_e32 v97, s100
	v_add_f32_e32 v97, s101, v97
	v_add_f32_e32 v97, vcc_lo, v97
	v_add_f32_e32 v97, vcc_hi, v97
	v_fmamk_f32 v81, v97, 0xba800000, v81
	v_fmamk_f32 v80, v97, 0xba800000, v80
	v_fmamk_f32 v83, v97, 0xba800000, v83
	v_fmac_f32_e32 v82, 0xba800000, v97
	v_pk_mul_f32 v[88:89], v[82:83], v[82:83]
	v_pk_mul_f32 v[98:99], v[80:81], v[80:81]
	v_fmamk_f32 v77, v97, 0xba800000, v77
	v_pk_mov_b32 v[100:101], v[98:99], v[88:89] op_sel:[1,0]
	v_mov_b32_e32 v99, v89
	v_fmamk_f32 v76, v97, 0xba800000, v76
	v_fmamk_f32 v79, v97, 0xba800000, v79
	v_fmac_f32_e32 v78, 0xba800000, v97
	v_pk_add_f32 v[88:89], v[100:101], v[98:99]
	v_pk_mul_f32 v[98:99], v[78:79], v[78:79]
	v_pk_mul_f32 v[100:101], v[76:77], v[76:77]
	v_fmamk_f32 v72, v97, 0xba800000, v72
	v_pk_mov_b32 v[102:103], v[100:101], v[98:99] op_sel:[1,0]
	v_mov_b32_e32 v101, v99
	v_fmamk_f32 v73, v97, 0xba800000, v73
	v_fmac_f32_e32 v74, 0xba800000, v97
	v_mul_f32_e32 v0, v72, v72
	v_pk_add_f32 v[98:99], v[102:103], v[100:101]
	v_fmamk_f32 v75, v97, 0xba800000, v75
	v_pk_fma_f32 v[100:101], v[72:73], v[72:73], v[0:1] op_sel_hi:[1,1,0]
	v_mul_f32_e32 v0, v74, v74
	v_pk_add_f32 v[88:89], v[88:89], v[88:89] op_sel_hi:[0,1]
	v_pk_add_f32 v[98:99], v[98:99], v[98:99] op_sel_hi:[0,1]
	v_pk_fma_f32 v[102:103], v[74:75], v[74:75], v[0:1] op_sel_hi:[1,1,0]
	v_fmamk_f32 v71, v97, 0xba800000, v71
	v_fmamk_f32 v70, v97, 0xba800000, v70
	v_fmamk_f32 v69, v97, 0xba800000, v69
	v_fmac_f32_e32 v68, 0xba800000, v97
	v_mul_f32_e32 v100, v68, v68
	v_mul_f32_e32 v102, v69, v69
	v_mul_f32_e32 v88, v70, v70
	v_mul_f32_e32 v98, v71, v71
	v_pk_add_f32 v[100:101], v[100:101], v[102:103]
	v_pk_add_f32 v[88:89], v[88:89], v[98:99]
	v_pk_add_f32 v[98:99], v[50:51], 1.0 op_sel_hi:[1,0]
	v_pk_add_f32 v[88:89], v[100:101], v[88:89]
	v_pk_add_f32 v[100:101], v[48:49], 1.0 op_sel_hi:[1,0]
	v_add_f32_e32 v0, v88, v89
	s_nop 1
	v_add_f32_dpp v0, v0, v0 quad_perm:[1,0,3,2] row_mask:0xf bank_mask:0xf
	s_nop 1
	v_add_f32_dpp v0, v0, v0 quad_perm:[2,3,0,1] row_mask:0xf bank_mask:0xf
	s_nop 1
	v_add_f32_dpp v0, v0, v0 row_half_mirror row_mask:0xf bank_mask:0xf
	s_nop 1
	v_add_f32_dpp v0, v0, v0 row_mirror row_mask:0xf bank_mask:0xf
	s_nop 1
	v_readlane_b32 s100, v0, 0
	v_readlane_b32 s101, v0, 16
	v_readlane_b32 vcc_lo, v0, 32
	v_readlane_b32 vcc_hi, v0, 48
	s_nop 1
	v_mov_b32_e32 v0, s100
	v_add_f32_e32 v0, s101, v0
	v_add_f32_e32 v0, vcc_lo, v0
	v_add_f32_e32 v0, vcc_hi, v0
	v_fmamk_f32 v0, v0, 0x3a800000, v227
	v_cmp_gt_f32_e32 vcc, s10, v0
	v_mul_f32_e32 v88, 0x4b800000, v0
	s_load_dwordx2 s[10:11], s[0:1], 0x148
	v_cndmask_b32_e32 v0, v0, v88, vcc
	v_rsq_f32_e32 v0, v0
	s_waitcnt lgkmcnt(0)
	v_lshl_add_u64 v[2:3], v[2:3], 1, s[10:11]
	v_mul_f32_e32 v88, 0x45800000, v0
	v_cndmask_b32_e32 v88, v0, v88, vcc
	v_pk_mul_f32 v[80:81], v[80:81], v[88:89] op_sel_hi:[1,0]
	v_pk_mul_f32 v[82:83], v[82:83], v[88:89] op_sel_hi:[1,0]
	v_lshlrev_b32_e32 v0, 1, v84
	v_pk_fma_f32 v[82:83], v[98:99], v[82:83], v[38:39]
	v_pk_fma_f32 v[80:81], v[100:101], v[80:81], v[36:37]
	v_lshl_add_u64 v[2:3], v[2:3], 0, v[0:1]
	v_cvt_pk_bf16_f32 v80, v80, v81
	v_cvt_pk_bf16_f32 v81, v82, v83
	global_store_dwordx2 v[2:3], v[80:81], off sc0 sc1
	v_pk_mul_f32 v[76:77], v[76:77], v[88:89] op_sel_hi:[1,0]
	v_pk_mul_f32 v[78:79], v[78:79], v[88:89] op_sel_hi:[1,0]
	v_pk_add_f32 v[80:81], v[42:43], 1.0 op_sel_hi:[1,0]
	v_pk_add_f32 v[82:83], v[40:41], 1.0 op_sel_hi:[1,0]
	v_pk_fma_f32 v[78:79], v[80:81], v[78:79], v[54:55]
	v_pk_fma_f32 v[76:77], v[82:83], v[76:77], v[52:53]
	v_pk_mul_f32 v[72:73], v[72:73], v[88:89] op_sel_hi:[1,0]
	v_cvt_pk_bf16_f32 v76, v76, v77
	v_cvt_pk_bf16_f32 v77, v78, v79
	global_store_dwordx2 v[2:3], v[76:77], off offset:512 sc0 sc1
	v_pk_mul_f32 v[74:75], v[74:75], v[88:89] op_sel_hi:[1,0]
	v_pk_add_f32 v[76:77], v[46:47], 1.0 op_sel_hi:[1,0]
	v_pk_add_f32 v[78:79], v[44:45], 1.0 op_sel_hi:[1,0]
	v_pk_fma_f32 v[74:75], v[76:77], v[74:75], v[58:59]
	v_pk_fma_f32 v[72:73], v[78:79], v[72:73], v[56:57]
	v_pk_mul_f32 v[68:69], v[68:69], v[88:89] op_sel_hi:[1,0]
	v_cvt_pk_bf16_f32 v72, v72, v73
	v_cvt_pk_bf16_f32 v73, v74, v75
	global_store_dwordx2 v[2:3], v[72:73], off offset:1024 sc0 sc1
	v_pk_mul_f32 v[70:71], v[70:71], v[88:89] op_sel_hi:[1,0]
	v_pk_add_f32 v[72:73], v[66:67], 1.0 op_sel_hi:[1,0]
	v_pk_add_f32 v[74:75], v[64:65], 1.0 op_sel_hi:[1,0]
	v_pk_fma_f32 v[70:71], v[72:73], v[70:71], v[62:63]
	v_pk_fma_f32 v[68:69], v[74:75], v[68:69], v[60:61]
	s_nop 0
	v_cvt_pk_bf16_f32 v68, v68, v69
	v_cvt_pk_bf16_f32 v69, v70, v71
	global_store_dwordx2 v[2:3], v[68:69], off offset:1536 sc0 sc1
	s_branch .LBB0_298

.LBB0_308:
	s_cmpk_gt_i32 s2, 0xff
	s_mov_b64 s[4:5], -1
	s_cbranch_scc0 .LBB0_318
	s_cmpk_gt_u32 s2, 0x1ff
	s_cbranch_scc0 .LBB0_315
	s_cmpk_gt_u32 s2, 0x2ff
	s_cbranch_scc0 .LBB0_312
	s_add_i32 s4, s2, 0xfffffd00
	s_lshr_b32 s4, s4, 6
	s_add_i32 s15, s4, s6
	s_load_dwordx2 s[4:5], s[0:1], 0x30
	s_lshl_b32 s16, s15, 5
	s_waitcnt lgkmcnt(0)
	s_bfe_u32 s18, s2, 0x30003
	s_add_i32 s16, s16, s7
	s_or_b32 s16, s16, s18
	s_ashr_i32 s17, s16, 31
	s_lshl_b64 s[16:17], s[16:17], 17
	s_waitcnt lgkmcnt(0)
	s_add_u32 s16, s4, s16
	s_addc_u32 s17, s5, s17
	s_load_dwordx2 s[4:5], s[0:1], 0x140
	s_lshl_b32 s15, s15, 3
	s_or_b32 s94, s15, s18
	s_lshl_b64 s[18:19], s[94:95], 16
	v_mov_b32_e32 v12, v226
	s_waitcnt lgkmcnt(0)
	s_add_u32 s4, s4, s18
	s_addc_u32 s5, s5, s19
	s_and_b32 s15, s9, 0x1c0
	s_nop 0
	v_ashrrev_i32_e32 v10, 4, v12
	v_lshlrev_b32_e32 v0, 4, v12
	v_add_u32_e32 v8, s15, v10
	v_and_b32_e32 v0, 0xf0, v0
	v_ashrrev_i32_e32 v9, 31, v8
	v_lshl_add_u64 v[6:7], s[16:17], 0, v[0:1]
	v_lshlrev_b64 v[2:3], 8, v[8:9]
	v_lshl_add_u64 v[2:3], v[6:7], 0, v[2:3]
	s_barrier
	global_load_dwordx4 v[2:5], v[2:3], off
	s_movk_i32 s16, 0x104
	v_mad_u64_u32 v[10:11], s[16:17], v10, s16, v[0:1]
	v_add_u32_e32 v0, 0x2080, v10
	s_lshl_b32 s94, s15, 1
	s_waitcnt vmcnt(0)
	ds_write2_b32 v10, v2, v3 offset1:1
	ds_write2_b32 v10, v4, v5 offset0:2 offset1:3
	v_add_u32_e32 v2, 32, v8
	v_ashrrev_i32_e32 v3, 31, v2
	v_lshlrev_b64 v[2:3], 8, v[2:3]
	v_lshl_add_u64 v[2:3], v[6:7], 0, v[2:3]
	global_load_dwordx4 v[2:5], v[2:3], off
	v_ashrrev_i32_e32 v6, 3, v12
	s_waitcnt vmcnt(0)
	ds_write2_b32 v0, v2, v3 offset1:1
	v_add_u32_e32 v0, 0x2088, v10
	ds_write2_b32 v0, v4, v5 offset1:1
	v_lshlrev_b32_e32 v0, 3, v12
	v_and_b32_e32 v0, 56, v0
	v_mul_u32_u24_e32 v2, 0x104, v0
	v_lshl_add_u32 v7, v6, 2, v2
	s_waitcnt lgkmcnt(0)
	s_barrier
	ds_read2_b32 v[2:3], v7 offset1:65
	ds_read2_b32 v[4:5], v7 offset0:130 offset1:195
	v_add_u32_e32 v7, 0x400, v7
	ds_read2_b32 v[8:9], v7 offset0:4 offset1:69
	ds_read2_b32 v[10:11], v7 offset0:134 offset1:199
	v_ashrrev_i32_e32 v7, 31, v6
	v_lshlrev_b64 v[6:7], 10, v[6:7]
	v_lshl_add_u64 v[6:7], s[4:5], 0, v[6:7]
	v_lshl_add_u64 v[6:7], v[6:7], 0, s[94:95]
	v_lshlrev_b32_e32 v0, 1, v0
	s_waitcnt lgkmcnt(3)
	v_cvt_pk_bf16_f32 v2, v2, v3
	s_waitcnt lgkmcnt(2)
	v_cvt_pk_bf16_f32 v3, v4, v5
	s_waitcnt lgkmcnt(1)
	v_cvt_pk_bf16_f32 v4, v8, v9
	s_waitcnt lgkmcnt(0)
	v_cvt_pk_bf16_f32 v5, v10, v11
	v_lshl_add_u64 v[6:7], v[6:7], 0, v[0:1]
	global_store_dwordx4 v[6:7], v[2:5], off sc0 sc1
	s_mov_b64 s[4:5], 0
.LBB0_312:
	s_andn2_b64 vcc, exec, s[4:5]
	s_cbranch_vccnz .LBB0_314
	s_add_i32 s15, s2, 0xfffffe00
	s_lshr_b32 s15, s15, 4
	s_and_b32 s15, s15, 0xffffffc
	s_add_i32 s15, s15, s8
	s_load_dwordx2 s[4:5], s[0:1], 0x20
	s_add_i32 s16, s15, s74
	s_waitcnt lgkmcnt(0)
	s_bfe_u32 s18, s2, 0x20004
	s_lshl_b32 s16, s16, 2
	s_or_b32 s16, s16, s18
	s_ashr_i32 s17, s16, 31
	s_lshl_b64 s[16:17], s[16:17], 18
	s_waitcnt lgkmcnt(0)
	s_add_u32 s19, s4, s16
	s_addc_u32 s20, s5, s17
	s_load_dwordx2 s[4:5], s[0:1], 0x130
	s_or_b32 s94, s15, s18
	s_lshl_b64 s[16:17], s[94:95], 17
	v_mov_b32_e32 v12, v226
	s_waitcnt lgkmcnt(0)
	s_add_u32 s4, s4, s16
	s_addc_u32 s5, s5, s17
	s_and_b32 s18, s9, 64
	s_and_b32 s15, s11, 0x1c0
	v_ashrrev_i32_e32 v10, 4, v12
	s_lshl_b32 s16, s18, 2
	s_add_u32 s16, s19, s16
	v_lshlrev_b32_e32 v0, 4, v12
	v_add_u32_e32 v8, s15, v10
	s_addc_u32 s17, s20, 0
	v_and_b32_e32 v0, 0xf0, v0
	v_ashrrev_i32_e32 v9, 31, v8
	v_lshl_add_u64 v[6:7], s[16:17], 0, v[0:1]
	v_lshlrev_b64 v[2:3], 9, v[8:9]
	v_lshl_add_u64 v[2:3], v[6:7], 0, v[2:3]
	s_barrier
	global_load_dwordx4 v[2:5], v[2:3], off
	s_movk_i32 s16, 0x104
	v_mad_u64_u32 v[10:11], s[16:17], v10, s16, v[0:1]
	v_add_u32_e32 v0, 0x2080, v10
	s_lshl_b32 s94, s15, 1
	s_waitcnt vmcnt(0)
	ds_write2_b32 v10, v2, v3 offset1:1
	ds_write2_b32 v10, v4, v5 offset0:2 offset1:3
	v_add_u32_e32 v2, 32, v8
	v_ashrrev_i32_e32 v3, 31, v2
	v_lshlrev_b64 v[2:3], 9, v[2:3]
	v_lshl_add_u64 v[2:3], v[6:7], 0, v[2:3]
	global_load_dwordx4 v[2:5], v[2:3], off
	s_waitcnt vmcnt(0)
	ds_write2_b32 v0, v2, v3 offset1:1
	v_lshlrev_b32_e32 v2, 3, v12
	v_add_u32_e32 v0, 0x2088, v10
	v_and_b32_e32 v10, 56, v2
	ds_write2_b32 v0, v4, v5 offset1:1
	v_ashrrev_i32_e32 v0, 3, v12
	v_mul_u32_u24_e32 v2, 0x104, v10
	v_lshl_add_u32 v6, v0, 2, v2
	s_waitcnt lgkmcnt(0)
	s_barrier
	ds_read2_b32 v[2:3], v6 offset1:65
	ds_read2_b32 v[4:5], v6 offset0:130 offset1:195
	v_add_u32_e32 v8, 0x400, v6
	ds_read2_b32 v[6:7], v8 offset0:4 offset1:69
	ds_read2_b32 v[8:9], v8 offset0:134 offset1:199
	s_waitcnt lgkmcnt(3)
	v_cvt_pk_bf16_f32 v2, v2, v3
	s_waitcnt lgkmcnt(2)
	v_cvt_pk_bf16_f32 v3, v4, v5
	s_waitcnt lgkmcnt(1)
	v_cvt_pk_bf16_f32 v4, v6, v7
	v_add_u32_e32 v6, s18, v0
	v_ashrrev_i32_e32 v7, 31, v6
	v_lshlrev_b64 v[6:7], 10, v[6:7]
	v_lshl_add_u64 v[6:7], s[4:5], 0, v[6:7]
	v_lshl_add_u64 v[6:7], v[6:7], 0, s[94:95]
	v_lshlrev_b32_e32 v0, 1, v10
	s_waitcnt lgkmcnt(0)
	v_cvt_pk_bf16_f32 v5, v8, v9
	v_lshl_add_u64 v[6:7], v[6:7], 0, v[0:1]
	global_store_dwordx4 v[6:7], v[2:5], off sc0 sc1

.LBB0_315:
	s_andn2_b64 vcc, exec, s[4:5]
	s_cbranch_vccnz .LBB0_317
	s_add_i32 s4, s2, 0xffffff00
	s_lshr_b32 s4, s4, 6
	s_add_i32 s94, s4, s6
	s_load_dwordx2 s[4:5], s[0:1], 0x28
	s_lshl_b32 s16, s94, 2
	s_add_i32 s16, s16, s74
	s_ashr_i32 s17, s16, 31
	s_and_b32 s15, s13, 0x3f000
	s_lshl_b64 s[16:17], s[16:17], 20
	s_waitcnt lgkmcnt(0)
	s_add_u32 s4, s4, s16
	s_addc_u32 s5, s5, s17
	s_lshl_b32 s16, s15, 2
	v_mov_b32_e32 v0, v226
	s_add_u32 s4, s4, s16
	s_load_dwordx2 s[16:17], s[0:1], 0x138
	s_addc_u32 s5, s5, 0
	v_lshlrev_b32_e32 v10, 3, v0
	v_ashrrev_i32_e32 v11, 31, v10
	v_lshl_add_u64 v[6:7], v[10:11], 2, s[4:5]
	global_load_dwordx4 v[2:5], v[6:7], off offset:16
	s_nop 0
	global_load_dwordx4 v[6:9], v[6:7], off
	s_lshl_b64 s[18:19], s[94:95], 19
	s_waitcnt lgkmcnt(0)
	s_add_u32 s16, s16, s18
	s_addc_u32 s17, s17, s19
	s_lshl_b32 s15, s15, 1
	s_add_u32 s16, s16, s15
	s_addc_u32 s17, s17, 0
	s_waitcnt vmcnt(0)
	v_cvt_pk_bf16_f32 v6, v6, v7
	v_cvt_pk_bf16_f32 v7, v8, v9
	v_cvt_pk_bf16_f32 v8, v2, v3
	v_cvt_pk_bf16_f32 v9, v4, v5
	v_lshl_add_u64 v[2:3], v[10:11], 1, s[16:17]
	global_store_dwordx4 v[2:3], v[6:9], off sc0 sc1

.LBB0_318:
	s_andn2_b64 vcc, exec, s[4:5]
	s_cbranch_vccnz .LBB0_307
	s_ashr_i32 s4, s2, 6
	s_add_i32 s4, s4, s6
	s_load_dwordx2 s[16:17], s[0:1], 0x18
	s_load_dwordx2 s[20:21], s[0:1], 0x128
	s_lshl_b32 s5, s4, 2
	s_waitcnt lgkmcnt(0)
	s_add_i32 s18, s5, s74
	s_ashr_i32 s19, s18, 31
	s_and_b32 s15, s13, 0x3f000
	s_lshl_b64 s[18:19], s[18:19], 20
	s_waitcnt lgkmcnt(0)
	s_add_u32 s5, s16, s18
	s_addc_u32 s17, s17, s19
	s_lshl_b32 s16, s15, 2
	v_mov_b32_e32 v0, v226
	s_add_u32 s16, s5, s16
	s_addc_u32 s17, s17, 0
	v_lshlrev_b32_e32 v10, 3, v0
	v_ashrrev_i32_e32 v11, 31, v10
	v_lshl_add_u64 v[6:7], v[10:11], 2, s[16:17]
	global_load_dwordx4 v[2:5], v[6:7], off
	s_nop 0
	global_load_dwordx4 v[6:9], v[6:7], off offset:16
	s_ashr_i32 s5, s4, 31
	s_lshl_b64 s[4:5], s[4:5], 19
	s_add_u32 s4, s20, s4
	s_addc_u32 s5, s21, s5
	s_lshl_b32 s15, s15, 1
	s_add_u32 s4, s4, s15
	s_addc_u32 s5, s5, 0
	s_waitcnt vmcnt(0)
	v_cvt_pk_bf16_f32 v2, v2, v3
	v_cvt_pk_bf16_f32 v3, v4, v5
	s_waitcnt vmcnt(0)
	v_cvt_pk_bf16_f32 v4, v6, v7
	v_cvt_pk_bf16_f32 v5, v8, v9
	v_lshl_add_u64 v[6:7], v[10:11], 1, s[4:5]
	global_store_dwordx4 v[6:7], v[2:5], off sc0 sc1
	s_branch .LBB0_307

.LBB0_322:
	v_mov_b32_e32 v0, v226
	s_movk_i32 s2, 0x2400
	v_lshrrev_b32_e32 v0, 6, v0
	v_mul_lo_u32 v0, v0, s2
	v_add_u32_e32 v132, 0x10000, v0
	v_lshlrev_b32_e32 v0, 2, v162
	v_or_b32_e32 v133, v132, v0
	v_lshl_add_u64 v[130:131], v[130:131], 0, v[0:1]
	v_lshl_or_b32 v0, v163, 2, v132
	v_lshlrev_b32_e32 v134, 2, v234
	v_add_u32_e32 v135, v0, v134
	ds_write_b32 v135, v126
	ds_write_b32 v135, v127 offset:272
	ds_write_b32 v135, v128 offset:544
	v_lshlrev_b32_e32 v126, 2, v235
	v_add_u32_e32 v127, v0, v126
	ds_write_b32 v127, v129
	ds_write_b32 v135, v122 offset:64
	ds_write_b32 v135, v123 offset:336
	ds_write_b32 v135, v124 offset:608
	ds_write_b32 v127, v125 offset:64
	ds_write_b32 v135, v118 offset:128
	ds_write_b32 v135, v119 offset:400
	ds_write_b32 v135, v120 offset:672
	ds_write_b32 v127, v121 offset:128
	v_lshl_or_b32 v118, v219, 2, v132
	v_add_u32_e32 v119, v118, v134
	ds_write2_b32 v119, v114, v115 offset1:68
	ds_write_b32 v119, v116 offset:544
	v_add_u32_e32 v114, v118, v126
	ds_write_b32 v114, v117
	ds_write_b32 v135, v110 offset:4352
	ds_write_b32 v135, v111 offset:4624
	ds_write_b32 v135, v112 offset:4896
	v_lshlrev_b32_e32 v110, 2, v236
	v_add_u32_e32 v112, v0, v110
	ds_write_b32 v112, v113
	ds_write_b32 v135, v106 offset:4416
	ds_write_b32 v135, v107 offset:4688
	ds_write_b32 v135, v108 offset:4960
	ds_write_b32 v112, v109 offset:64
	ds_write_b32 v135, v102 offset:4480
	ds_write_b32 v135, v103 offset:4752
	ds_write_b32 v135, v104 offset:5024
	ds_write_b32 v112, v105 offset:128
	v_add_u32_e32 v113, 0x1000, v119
	v_add_u32_e32 v115, v118, v110
	ds_write2_b32 v113, v98, v99 offset0:64 offset1:132
	ds_write_b32 v119, v100 offset:4896
	ds_write_b32 v115, v101
	v_add_u32_e32 v133, v133, v233
	s_waitcnt lgkmcnt(0)
	ds_read_b128 v[98:101], v133
	ds_read_b128 v[102:105], v133 offset:1088
	v_mul_u32_u24_e32 v0, s3, v214
	v_lshlrev_b32_e32 v0, 2, v0
	v_lshl_add_u64 v[106:107], v[130:131], 0, v[0:1]
	s_waitcnt lgkmcnt(0)
	global_store_dwordx4 v[106:107], v[98:101], off sc0 sc1
	s_lshl_b32 s94, s3, 4
	ds_read_b128 v[98:101], v133 offset:2176
	v_lshl_add_u64 v[110:111], v[106:107], 0, s[94:95]
	ds_read_b128 v[106:109], v133 offset:3264
	s_lshl_b32 s2, s3, 2
	global_store_dwordx4 v[110:111], v[102:105], off sc0 sc1
	s_add_i32 s8, s2, s2
	s_add_i32 s8, s8, s8
	v_lshl_add_u64 v[102:103], v[110:111], 0, s[94:95]
	s_waitcnt lgkmcnt(0)
	global_store_dwordx4 v[102:103], v[98:101], off sc0 sc1
	v_mov_b32_e32 v0, s8
	s_nop 0
	v_lshl_add_u64 v[98:99], v[102:103], 0, s[94:95]
	global_store_dwordx4 v[98:99], v[106:109], off sc0 sc1
	ds_read_b128 v[98:101], v133 offset:4352
	ds_read_b128 v[102:105], v133 offset:5440
	v_mad_u32_u24 v108, s3, v214, v0
	v_lshlrev_b32_e32 v0, 2, v108
	v_add_u32_e32 v108, s2, v108
	v_lshl_add_u64 v[106:107], v[130:131], 0, v[0:1]
	v_lshlrev_b32_e32 v0, 2, v108
	s_waitcnt lgkmcnt(0)
	global_store_dwordx4 v[106:107], v[98:101], off sc0 sc1
	v_lshl_add_u64 v[106:107], v[130:131], 0, v[0:1]
	ds_read_b128 v[98:101], v133 offset:6528
	global_store_dwordx4 v[106:107], v[102:105], off sc0 sc1
	ds_read_b128 v[102:105], v133 offset:7616
	v_add_u32_e32 v0, s2, v108
	v_lshl_add_u64 v[106:107], v[0:1], 2, v[130:131]
	v_add_u32_e32 v0, s2, v0
	s_waitcnt lgkmcnt(0)
	global_store_dwordx4 v[106:107], v[98:101], off sc0 sc1
	s_nop 1
	v_lshl_add_u64 v[98:99], v[0:1], 2, v[130:131]
	global_store_dwordx4 v[98:99], v[102:105], off sc0 sc1
	s_waitcnt lgkmcnt(0)
	ds_write_b32 v135, v94
	ds_write_b32 v135, v95 offset:272
	ds_write_b32 v135, v96 offset:544
	ds_write_b32 v127, v97
	ds_write_b32 v135, v90 offset:64
	ds_write_b32 v135, v91 offset:336
	ds_write_b32 v135, v92 offset:608
	ds_write_b32 v127, v93 offset:64
	ds_write_b32 v135, v82 offset:128
	ds_write_b32 v135, v83 offset:400
	ds_write_b32 v135, v84 offset:672
	ds_write_b32 v127, v85 offset:128
	ds_write2_b32 v119, v86, v87 offset1:68
	ds_write_b32 v119, v88 offset:544
	ds_write_b32 v114, v89
	ds_write_b32 v135, v78 offset:4352
	ds_write_b32 v135, v79 offset:4624
	ds_write_b32 v135, v80 offset:4896
	ds_write_b32 v112, v81
	ds_write_b32 v135, v74 offset:4416
	ds_write_b32 v135, v75 offset:4688
	ds_write_b32 v135, v76 offset:4960
	ds_write_b32 v112, v77 offset:64
	ds_write_b32 v135, v70 offset:4480
	ds_write_b32 v135, v71 offset:4752
	ds_write_b32 v135, v72 offset:5024
	ds_write_b32 v112, v73 offset:128
	ds_write2_b32 v113, v66, v67 offset0:64 offset1:132
	ds_write_b32 v119, v68 offset:4896
	ds_write_b32 v115, v69
	s_waitcnt lgkmcnt(0)
	ds_read_b128 v[66:69], v133
	ds_read_b128 v[70:73], v133 offset:1088
	v_add_u32_e32 v0, s2, v0
	v_lshl_add_u64 v[74:75], v[0:1], 2, v[130:131]
	v_add_u32_e32 v0, s2, v0
	s_waitcnt lgkmcnt(0)
	global_store_dwordx4 v[74:75], v[66:69], off sc0 sc1
	v_lshl_add_u64 v[74:75], v[0:1], 2, v[130:131]
	ds_read_b128 v[66:69], v133 offset:2176
	global_store_dwordx4 v[74:75], v[70:73], off sc0 sc1
	ds_read_b128 v[70:73], v133 offset:3264
	v_add_u32_e32 v0, s2, v0
	v_lshl_add_u64 v[74:75], v[0:1], 2, v[130:131]
	v_add_u32_e32 v0, s2, v0
	s_waitcnt lgkmcnt(0)
	global_store_dwordx4 v[74:75], v[66:69], off sc0 sc1
	v_lshl_add_u64 v[74:75], v[0:1], 2, v[130:131]
	ds_read_b128 v[66:69], v133 offset:4352
	global_store_dwordx4 v[74:75], v[70:73], off sc0 sc1
	ds_read_b128 v[70:73], v133 offset:5440
	v_add_u32_e32 v0, s2, v0
	v_lshl_add_u64 v[74:75], v[0:1], 2, v[130:131]
	v_add_u32_e32 v0, s2, v0
	s_waitcnt lgkmcnt(0)
	global_store_dwordx4 v[74:75], v[66:69], off sc0 sc1
	v_lshl_add_u64 v[74:75], v[0:1], 2, v[130:131]
	ds_read_b128 v[66:69], v133 offset:6528
	global_store_dwordx4 v[74:75], v[70:73], off sc0 sc1
	ds_read_b128 v[70:73], v133 offset:7616
	v_add_u32_e32 v0, s2, v0
	v_lshl_add_u64 v[74:75], v[0:1], 2, v[130:131]
	v_add_u32_e32 v0, s2, v0
	s_waitcnt lgkmcnt(0)
	global_store_dwordx4 v[74:75], v[66:69], off sc0 sc1
	s_nop 1
	v_lshl_add_u64 v[66:67], v[0:1], 2, v[130:131]
	global_store_dwordx4 v[66:67], v[70:73], off sc0 sc1
	s_waitcnt lgkmcnt(0)
	ds_write_b32 v135, v58
	ds_write_b32 v135, v59 offset:272
	ds_write_b32 v135, v60 offset:544
	ds_write_b32 v127, v61
	ds_write_b32 v135, v54 offset:64
	ds_write_b32 v135, v55 offset:336
	ds_write_b32 v135, v56 offset:608
	ds_write_b32 v127, v57 offset:64
	ds_write_b32 v135, v46 offset:128
	ds_write_b32 v135, v47 offset:400
	ds_write_b32 v135, v48 offset:672
	ds_write_b32 v127, v49 offset:128
	ds_write2_b32 v119, v50, v51 offset1:68
	ds_write_b32 v119, v52 offset:544
	ds_write_b32 v114, v53
	ds_write_b32 v135, v42 offset:4352
	ds_write_b32 v135, v43 offset:4624
	ds_write_b32 v135, v44 offset:4896
	ds_write_b32 v112, v45
	ds_write_b32 v135, v38 offset:4416
	ds_write_b32 v135, v39 offset:4688
	ds_write_b32 v135, v40 offset:4960
	ds_write_b32 v112, v41 offset:64
	ds_write_b32 v135, v34 offset:4480
	ds_write_b32 v135, v35 offset:4752
	ds_write_b32 v135, v36 offset:5024
	ds_write_b32 v112, v37 offset:128
	ds_write2_b32 v113, v30, v31 offset0:64 offset1:132
	ds_write_b32 v119, v32 offset:4896
	ds_write_b32 v115, v33
	s_waitcnt lgkmcnt(0)
	ds_read_b128 v[30:33], v133
	ds_read_b128 v[34:37], v133 offset:1088
	v_add_u32_e32 v0, s2, v0
	v_lshl_add_u64 v[38:39], v[0:1], 2, v[130:131]
	v_add_u32_e32 v0, s2, v0
	s_waitcnt lgkmcnt(0)
	global_store_dwordx4 v[38:39], v[30:33], off sc0 sc1
	v_lshl_add_u64 v[38:39], v[0:1], 2, v[130:131]
	ds_read_b128 v[30:33], v133 offset:2176
	global_store_dwordx4 v[38:39], v[34:37], off sc0 sc1
	ds_read_b128 v[34:37], v133 offset:3264
	v_add_u32_e32 v0, s2, v0
	v_lshl_add_u64 v[38:39], v[0:1], 2, v[130:131]
	v_add_u32_e32 v0, s2, v0
	s_waitcnt lgkmcnt(0)
	global_store_dwordx4 v[38:39], v[30:33], off sc0 sc1
	v_lshl_add_u64 v[38:39], v[0:1], 2, v[130:131]
	ds_read_b128 v[30:33], v133 offset:4352
	global_store_dwordx4 v[38:39], v[34:37], off sc0 sc1
	ds_read_b128 v[34:37], v133 offset:5440
	v_add_u32_e32 v0, s2, v0
	v_lshl_add_u64 v[38:39], v[0:1], 2, v[130:131]
	v_add_u32_e32 v0, s2, v0
	s_waitcnt lgkmcnt(0)
	global_store_dwordx4 v[38:39], v[30:33], off sc0 sc1
	v_lshl_add_u64 v[38:39], v[0:1], 2, v[130:131]
	ds_read_b128 v[30:33], v133 offset:6528
	global_store_dwordx4 v[38:39], v[34:37], off sc0 sc1
	ds_read_b128 v[34:37], v133 offset:7616
	v_add_u32_e32 v0, s2, v0
	v_lshl_add_u64 v[38:39], v[0:1], 2, v[130:131]
	v_add_u32_e32 v0, s2, v0
	s_waitcnt lgkmcnt(0)
	global_store_dwordx4 v[38:39], v[30:33], off sc0 sc1
	s_nop 1
	v_lshl_add_u64 v[30:31], v[0:1], 2, v[130:131]
	global_store_dwordx4 v[30:31], v[34:37], off sc0 sc1
	s_waitcnt lgkmcnt(0)
	ds_write_b32 v135, v22
	ds_write_b32 v135, v23 offset:272
	ds_write_b32 v135, v24 offset:544
	ds_write_b32 v127, v25
	ds_write_b32 v135, v18 offset:64
	ds_write_b32 v135, v19 offset:336
	ds_write_b32 v135, v20 offset:608
	ds_write_b32 v127, v21 offset:64
	ds_write_b32 v135, v10 offset:128
	ds_write_b32 v135, v11 offset:400
	ds_write_b32 v135, v12 offset:672
	ds_write_b32 v127, v13 offset:128
	ds_write2_b32 v119, v14, v15 offset1:68
	ds_write_b32 v119, v16 offset:544
	ds_write_b32 v114, v17
	ds_write_b32 v135, v6 offset:4352
	ds_write_b32 v135, v7 offset:4624
	ds_write_b32 v135, v8 offset:4896
	ds_write_b32 v112, v9
	ds_write_b32 v135, v2 offset:4416
	ds_write_b32 v135, v3 offset:4688
	ds_write_b32 v135, v4 offset:4960
	ds_write_b32 v112, v5 offset:64
	ds_write_b32 v135, v26 offset:4480
	ds_write_b32 v135, v27 offset:4752
	ds_write_b32 v135, v28 offset:5024
	ds_write_b32 v112, v29 offset:128
	ds_write2_b32 v113, v62, v63 offset0:64 offset1:132
	ds_write_b32 v119, v64 offset:4896
	ds_write_b32 v115, v65
	s_waitcnt lgkmcnt(0)
	ds_read_b128 v[2:5], v133
	ds_read_b128 v[6:9], v133 offset:1088
	v_add_u32_e32 v0, s2, v0
	v_lshl_add_u64 v[10:11], v[0:1], 2, v[130:131]
	v_add_u32_e32 v0, s2, v0
	s_waitcnt lgkmcnt(0)
	global_store_dwordx4 v[10:11], v[2:5], off sc0 sc1
	v_lshl_add_u64 v[10:11], v[0:1], 2, v[130:131]
	ds_read_b128 v[2:5], v133 offset:2176
	global_store_dwordx4 v[10:11], v[6:9], off sc0 sc1
	ds_read_b128 v[6:9], v133 offset:3264
	v_add_u32_e32 v0, s2, v0
	v_lshl_add_u64 v[10:11], v[0:1], 2, v[130:131]
	v_add_u32_e32 v0, s2, v0
	s_waitcnt lgkmcnt(0)
	global_store_dwordx4 v[10:11], v[2:5], off sc0 sc1
	v_lshl_add_u64 v[10:11], v[0:1], 2, v[130:131]
	ds_read_b128 v[2:5], v133 offset:4352
	global_store_dwordx4 v[10:11], v[6:9], off sc0 sc1
	ds_read_b128 v[6:9], v133 offset:5440
	v_add_u32_e32 v0, s2, v0
	v_lshl_add_u64 v[10:11], v[0:1], 2, v[130:131]
	v_add_u32_e32 v0, s2, v0
	s_waitcnt lgkmcnt(0)
	global_store_dwordx4 v[10:11], v[2:5], off sc0 sc1
	v_lshl_add_u64 v[10:11], v[0:1], 2, v[130:131]
	ds_read_b128 v[2:5], v133 offset:6528
	global_store_dwordx4 v[10:11], v[6:9], off sc0 sc1
	ds_read_b128 v[6:9], v133 offset:7616
	v_add_u32_e32 v0, s2, v0
	v_lshl_add_u64 v[10:11], v[0:1], 2, v[130:131]
	v_add_u32_e32 v0, s2, v0
	s_waitcnt lgkmcnt(0)
	global_store_dwordx4 v[10:11], v[2:5], off sc0 sc1
	s_nop 1
	v_lshl_add_u64 v[2:3], v[0:1], 2, v[130:131]
	global_store_dwordx4 v[2:3], v[6:9], off sc0 sc1
	s_waitcnt lgkmcnt(0)

.LBB0_400:
	s_or_b64 exec, exec, s[4:5]
	s_load_dwordx2 s[4:5], s[0:1], 0x150
	v_ashrrev_i32_e32 v133, 31, v132
	v_lshlrev_b64 v[138:139], 13, v[132:133]
	v_lshlrev_b32_e32 v140, 1, v160
	v_or_b32_e32 v0, s2, v155
	s_waitcnt lgkmcnt(0)
	v_lshl_add_u64 v[138:139], s[4:5], 0, v[138:139]
	v_add_u32_e32 v142, v136, v140
	v_lshl_add_u64 v[136:137], v[0:1], 1, v[138:139]
	v_mov_b32_e32 v141, v1
	s_waitcnt lgkmcnt(0)
	v_add_u32_e32 v0, v142, v238
	v_lshl_add_u64 v[148:149], v[136:137], 0, v[140:141]
	ds_read_b128 v[136:139], v0
	ds_read_b128 v[198:201], v0 offset:3456
	v_mov_b32_e32 v167, v1
	v_lshl_add_u64 v[150:151], v[148:149], 0, v[166:167]
	v_mov_b32_e32 v169, v1
	s_waitcnt lgkmcnt(0)
	global_store_dwordx4 v[150:151], v[136:139], off sc0 sc1
	ds_read_b128 v[136:139], v0 offset:1152
	v_lshl_add_u64 v[142:143], v[148:149], 0, v[168:169]
	v_mov_b32_e32 v171, v1
	v_lshl_add_u64 v[146:147], v[148:149], 0, v[170:171]
	v_mov_b32_e32 v173, v1
	s_waitcnt lgkmcnt(0)
	global_store_dwordx4 v[142:143], v[136:139], off sc0 sc1
	ds_read_b128 v[136:139], v0 offset:2304
	v_mov_b32_e32 v175, v1
	v_lshl_add_u64 v[144:145], v[148:149], 0, v[174:175]
	v_mov_b32_e32 v177, v1
	v_mov_b32_e32 v179, v1
	s_waitcnt lgkmcnt(0)
	global_store_dwordx4 v[146:147], v[136:139], off sc0 sc1
	v_lshl_add_u64 v[140:141], v[148:149], 0, v[178:179]
	v_mov_b32_e32 v181, v1
	v_lshl_add_u64 v[138:139], v[148:149], 0, v[172:173]
	global_store_dwordx4 v[138:139], v[198:201], off sc0 sc1
	ds_read_b128 v[198:201], v0 offset:4608
	v_lshl_add_u64 v[136:137], v[148:149], 0, v[176:177]
	v_lshl_add_u64 v[148:149], v[148:149], 0, v[180:181]
	v_or_b32_e32 v133, v153, v237
	s_waitcnt lgkmcnt(0)
	global_store_dwordx4 v[144:145], v[198:201], off sc0 sc1
	ds_read_b128 v[198:201], v0 offset:5760
	s_waitcnt lgkmcnt(0)
	global_store_dwordx4 v[136:137], v[198:201], off sc0 sc1
	ds_read_b128 v[198:201], v0 offset:6912
	s_waitcnt lgkmcnt(0)
	global_store_dwordx4 v[140:141], v[198:201], off sc0 sc1
	ds_read_b128 v[198:201], v0 offset:8064
	s_waitcnt lgkmcnt(0)
	global_store_dwordx4 v[148:149], v[198:201], off sc0 sc1
	s_waitcnt lgkmcnt(0)
	s_and_saveexec_b64 s[2:3], s[10:11]
	s_xor_b64 s[4:5], exec, s[2:3]
	s_cbranch_execnz .LBB0_420
	s_andn2_saveexec_b64 s[4:5], s[4:5]
	s_cbranch_execnz .LBB0_421

.LBB0_409:
	s_or_b64 exec, exec, s[4:5]
	s_waitcnt lgkmcnt(0)
	ds_read_b128 v[198:201], v0
	v_add_co_u32_e32 v150, vcc, 0x80000, v150
	s_nop 1
	v_addc_co_u32_e32 v151, vcc, 0, v151, vcc
	s_waitcnt lgkmcnt(0)
	global_store_dwordx4 v[150:151], v[198:201], off sc0 sc1
	ds_read_b128 v[198:201], v0 offset:1152
	v_add_co_u32_e32 v142, vcc, 0x80000, v142
	s_nop 1
	v_addc_co_u32_e32 v143, vcc, 0, v143, vcc
	s_waitcnt lgkmcnt(0)
	global_store_dwordx4 v[142:143], v[198:201], off sc0 sc1
	ds_read_b128 v[198:201], v0 offset:2304
	v_add_co_u32_e32 v142, vcc, 0x80000, v146
	s_nop 1
	v_addc_co_u32_e32 v143, vcc, 0, v147, vcc
	s_waitcnt lgkmcnt(0)
	global_store_dwordx4 v[142:143], v[198:201], off sc0 sc1
	ds_read_b128 v[198:201], v0 offset:3456
	v_add_co_u32_e32 v138, vcc, 0x80000, v138
	s_nop 1
	v_addc_co_u32_e32 v139, vcc, 0, v139, vcc
	s_waitcnt lgkmcnt(0)
	global_store_dwordx4 v[138:139], v[198:201], off sc0 sc1
	v_add_co_u32_e32 v138, vcc, 0x80000, v144
	ds_read_b128 v[198:201], v0 offset:4608
	s_nop 0
	v_addc_co_u32_e32 v139, vcc, 0, v145, vcc
	ds_read_b128 v[142:145], v0 offset:5760
	v_add_co_u32_e32 v136, vcc, 0x80000, v136
	s_waitcnt lgkmcnt(0)
	global_store_dwordx4 v[138:139], v[198:201], off sc0 sc1
	v_addc_co_u32_e32 v137, vcc, 0, v137, vcc
	global_store_dwordx4 v[136:137], v[142:145], off sc0 sc1
	ds_read_b128 v[136:139], v0 offset:6912
	v_add_co_u32_e32 v140, vcc, 0x80000, v140
	s_nop 1
	v_addc_co_u32_e32 v141, vcc, 0, v141, vcc
	s_waitcnt lgkmcnt(0)
	global_store_dwordx4 v[140:141], v[136:139], off sc0 sc1
	ds_read_b128 v[136:139], v0 offset:8064
	v_add_co_u32_e32 v140, vcc, 0x80000, v148
	s_nop 1
	v_addc_co_u32_e32 v141, vcc, 0, v149, vcc
	s_waitcnt lgkmcnt(0)
	global_store_dwordx4 v[140:141], v[136:139], off sc0 sc1
	s_waitcnt lgkmcnt(0)
	s_and_saveexec_b64 s[4:5], s[8:9]
	s_cbranch_execz .LBB0_433
	s_cmp_lt_i32 s36, 8
	s_cbranch_scc1 .LBB0_427
	s_mov_b64 s[18:19], 0
	s_cmp_eq_u32 s36, 8
	s_mov_b64 s[10:11], 0
	s_cbranch_scc0 .LBB0_428
	s_load_dwordx2 s[2:3], s[0:1], 0xe8
	v_lshl_add_u32 v136, v154, 2, s74
	v_ashrrev_i32_e32 v137, 31, v136
	v_lshlrev_b32_e32 v0, 2, v152
	v_and_b32_e32 v0, 0x700, v0
	v_lshlrev_b64 v[136:137], 19, v[136:137]
	v_add_lshl_u32 v0, v153, v0, 8
	s_waitcnt lgkmcnt(0)
	v_lshl_add_u64 v[136:137], s[2:3], 0, v[136:137]
	v_lshl_add_u64 v[136:137], v[136:137], 0, v[0:1]
	s_mov_b64 s[2:3], 0xd000000
	v_lshl_add_u64 v[136:137], v[136:137], 0, s[2:3]
	s_mov_b64 s[10:11], -1
	s_branch .LBB0_428

.LBB0_431:
	s_and_b64 vcc, exec, s[10:11]
	s_cbranch_vccz .LBB0_433
	v_mov_b32_e32 v0, v226
	s_movk_i32 s2, 0x2400
	v_lshrrev_b32_e32 v0, 6, v0
	v_mul_lo_u32 v0, v0, s2
	v_add_u32_e32 v131, 0x10000, v0
	v_lshlrev_b32_e32 v0, 2, v162
	v_or_b32_e32 v133, v131, v0
	v_lshl_add_u64 v[142:143], v[136:137], 0, v[0:1]
	v_add_u32_e32 v0, v133, v233
	v_lshl_or_b32 v133, v163, 2, v131
	v_lshlrev_b32_e32 v136, 2, v234
	v_lshl_or_b32 v131, v219, 2, v131
	v_add_u32_e32 v146, v133, v136
	v_lshlrev_b32_e32 v137, 2, v235
	v_add_u32_e32 v148, v131, v136
	v_lshlrev_b32_e32 v136, 2, v236
	v_add_u32_e32 v147, v133, v137
	v_add_u32_e32 v149, v131, v137
	v_add_u32_e32 v133, v133, v136
	v_add_u32_e32 v150, 0x1000, v148
	v_add_u32_e32 v131, v131, v136
	ds_write_b32 v146, v126
	ds_write_b32 v146, v127 offset:272
	ds_write_b32 v146, v128 offset:544
	ds_write_b32 v147, v129
	ds_write_b32 v146, v122 offset:64
	ds_write_b32 v146, v123 offset:336
	ds_write_b32 v146, v124 offset:608
	ds_write_b32 v147, v125 offset:64
	ds_write_b32 v146, v118 offset:128
	ds_write_b32 v146, v119 offset:400
	ds_write_b32 v146, v120 offset:672
	ds_write_b32 v147, v121 offset:128
	ds_write2_b32 v148, v114, v115 offset1:68
	ds_write_b32 v148, v116 offset:544
	ds_write_b32 v149, v117
	ds_write_b32 v146, v110 offset:4352
	ds_write_b32 v146, v111 offset:4624
	ds_write_b32 v146, v112 offset:4896
	ds_write_b32 v133, v113
	ds_write_b32 v146, v106 offset:4416
	ds_write_b32 v146, v107 offset:4688
	ds_write_b32 v146, v108 offset:4960
	ds_write_b32 v133, v109 offset:64
	ds_write_b32 v146, v102 offset:4480
	ds_write_b32 v146, v103 offset:4752
	ds_write_b32 v146, v104 offset:5024
	ds_write_b32 v133, v105 offset:128
	ds_write2_b32 v150, v98, v99 offset0:64 offset1:132
	ds_write_b32 v148, v100 offset:4896
	ds_write_b32 v131, v101
	s_waitcnt lgkmcnt(0)
	ds_read_b128 v[138:141], v0
	v_mov_b32_e32 v183, v1
	v_lshl_add_u64 v[136:137], v[142:143], 0, v[182:183]
	v_mov_b32_e32 v185, v1
	v_lshl_add_u64 v[144:145], v[142:143], 0, v[184:185]
	s_waitcnt lgkmcnt(0)
	global_store_dwordx4 v[136:137], v[138:141], off sc0 sc1
	ds_read_b128 v[138:141], v0 offset:1088
	v_mov_b32_e32 v187, v1
	v_mov_b32_e32 v189, v1
	v_mov_b32_e32 v191, v1
	v_mov_b32_e32 v193, v1
	s_waitcnt lgkmcnt(0)
	global_store_dwordx4 v[144:145], v[138:141], off sc0 sc1
	ds_read_b128 v[138:141], v0 offset:2176
	v_lshl_add_u64 v[144:145], v[142:143], 0, v[186:187]
	v_mov_b32_e32 v195, v1
	v_mov_b32_e32 v197, v1
	s_movk_i32 s2, 0x2000
	s_waitcnt lgkmcnt(0)
	global_store_dwordx4 v[144:145], v[138:141], off sc0 sc1
	ds_read_b128 v[138:141], v0 offset:3264
	v_lshl_add_u64 v[144:145], v[142:143], 0, v[188:189]
	s_waitcnt lgkmcnt(0)
	global_store_dwordx4 v[144:145], v[138:141], off sc0 sc1
	ds_read_b128 v[138:141], v0 offset:4352
	v_lshl_add_u64 v[144:145], v[142:143], 0, v[190:191]
	s_waitcnt lgkmcnt(0)
	global_store_dwordx4 v[144:145], v[138:141], off sc0 sc1
	ds_read_b128 v[138:141], v0 offset:5440
	v_lshl_add_u64 v[144:145], v[142:143], 0, v[192:193]
	s_waitcnt lgkmcnt(0)
	global_store_dwordx4 v[144:145], v[138:141], off sc0 sc1
	ds_read_b128 v[138:141], v0 offset:6528
	v_lshl_add_u64 v[144:145], v[142:143], 0, v[194:195]
	v_lshl_add_u64 v[142:143], v[142:143], 0, v[196:197]
	s_waitcnt lgkmcnt(0)
	global_store_dwordx4 v[144:145], v[138:141], off sc0 sc1
	ds_read_b128 v[138:141], v0 offset:7616
	s_waitcnt lgkmcnt(0)
	global_store_dwordx4 v[142:143], v[138:141], off sc0 sc1
	s_waitcnt lgkmcnt(0)
	ds_write_b32 v146, v94
	ds_write_b32 v146, v95 offset:272
	ds_write_b32 v146, v96 offset:544
	ds_write_b32 v147, v97
	ds_write_b32 v146, v90 offset:64
	ds_write_b32 v146, v91 offset:336
	ds_write_b32 v146, v92 offset:608
	ds_write_b32 v147, v93 offset:64
	ds_write_b32 v146, v82 offset:128
	ds_write_b32 v146, v83 offset:400
	ds_write_b32 v146, v84 offset:672
	ds_write_b32 v147, v85 offset:128
	ds_write2_b32 v148, v86, v87 offset1:68
	ds_write_b32 v148, v88 offset:544
	ds_write_b32 v149, v89
	ds_write_b32 v146, v78 offset:4352
	ds_write_b32 v146, v79 offset:4624
	ds_write_b32 v146, v80 offset:4896
	ds_write_b32 v133, v81
	ds_write_b32 v146, v74 offset:4416
	ds_write_b32 v146, v75 offset:4688
	ds_write_b32 v146, v76 offset:4960
	ds_write_b32 v133, v77 offset:64
	ds_write_b32 v146, v70 offset:4480
	ds_write_b32 v146, v71 offset:4752
	ds_write_b32 v146, v72 offset:5024
	ds_write_b32 v133, v73 offset:128
	ds_write2_b32 v150, v66, v67 offset0:64 offset1:132
	ds_write_b32 v148, v68 offset:4896
	ds_write_b32 v131, v69
	s_waitcnt lgkmcnt(0)
	ds_read_b128 v[138:141], v0
	v_add_co_u32_e32 v142, vcc, s2, v136
	s_movk_i32 s2, 0x4000
	s_nop 0
	v_addc_co_u32_e32 v143, vcc, 0, v137, vcc
	v_add_co_u32_e32 v144, vcc, s87, v136
	s_nop 1
	v_addc_co_u32_e32 v145, vcc, 0, v137, vcc
	s_waitcnt lgkmcnt(0)
	global_store_dwordx4 v[144:145], v[138:141], off offset:-4096 sc0 sc1
	ds_read_b128 v[138:141], v0 offset:1088
	s_waitcnt lgkmcnt(0)
	global_store_dwordx4 v[142:143], v[138:141], off offset:1024 sc0 sc1
	ds_read_b128 v[138:141], v0 offset:2176
	s_waitcnt lgkmcnt(0)
	global_store_dwordx4 v[142:143], v[138:141], off offset:2048 sc0 sc1
	ds_read_b128 v[138:141], v0 offset:3264
	s_waitcnt lgkmcnt(0)
	global_store_dwordx4 v[142:143], v[138:141], off offset:3072 sc0 sc1
	ds_read_b128 v[138:141], v0 offset:4352
	v_add_co_u32_e32 v142, vcc, s2, v136
	s_movk_i32 s2, 0x5000
	s_nop 0
	v_addc_co_u32_e32 v143, vcc, 0, v137, vcc
	s_waitcnt lgkmcnt(0)
	global_store_dwordx4 v[144:145], v[138:141], off sc0 sc1
	ds_read_b128 v[138:141], v0 offset:5440
	s_waitcnt lgkmcnt(0)
	global_store_dwordx4 v[144:145], v[138:141], off offset:1024 sc0 sc1
	ds_read_b128 v[138:141], v0 offset:6528
	s_waitcnt lgkmcnt(0)
	global_store_dwordx4 v[144:145], v[138:141], off offset:2048 sc0 sc1
	ds_read_b128 v[138:141], v0 offset:7616
	s_waitcnt lgkmcnt(0)
	global_store_dwordx4 v[144:145], v[138:141], off offset:3072 sc0 sc1
	s_waitcnt lgkmcnt(0)
	ds_write_b32 v146, v58
	ds_write_b32 v146, v59 offset:272
	ds_write_b32 v146, v60 offset:544
	ds_write_b32 v147, v61
	ds_write_b32 v146, v54 offset:64
	ds_write_b32 v146, v55 offset:336
	ds_write_b32 v146, v56 offset:608
	ds_write_b32 v147, v57 offset:64
	ds_write_b32 v146, v46 offset:128
	ds_write_b32 v146, v47 offset:400
	ds_write_b32 v146, v48 offset:672
	ds_write_b32 v147, v49 offset:128
	ds_write2_b32 v148, v50, v51 offset1:68
	ds_write_b32 v148, v52 offset:544
	ds_write_b32 v149, v53
	ds_write_b32 v146, v42 offset:4352
	ds_write_b32 v146, v43 offset:4624
	ds_write_b32 v146, v44 offset:4896
	ds_write_b32 v133, v45
	ds_write_b32 v146, v38 offset:4416
	ds_write_b32 v146, v39 offset:4688
	ds_write_b32 v146, v40 offset:4960
	ds_write_b32 v133, v41 offset:64
	ds_write_b32 v146, v34 offset:4480
	ds_write_b32 v146, v35 offset:4752
	ds_write_b32 v146, v36 offset:5024
	ds_write_b32 v133, v37 offset:128
	ds_write2_b32 v150, v30, v31 offset0:64 offset1:132
	ds_write_b32 v148, v32 offset:4896
	ds_write_b32 v131, v33
	s_waitcnt lgkmcnt(0)
	ds_read_b128 v[138:141], v0
	v_add_co_u32_e32 v144, vcc, s2, v136
	s_nop 1
	v_addc_co_u32_e32 v145, vcc, 0, v137, vcc
	s_waitcnt lgkmcnt(0)
	global_store_dwordx4 v[144:145], v[138:141], off offset:-4096 sc0 sc1
	ds_read_b128 v[138:141], v0 offset:1088
	s_waitcnt lgkmcnt(0)
	global_store_dwordx4 v[142:143], v[138:141], off offset:1024 sc0 sc1
	ds_read_b128 v[138:141], v0 offset:2176
	s_waitcnt lgkmcnt(0)
	global_store_dwordx4 v[142:143], v[138:141], off offset:2048 sc0 sc1
	ds_read_b128 v[138:141], v0 offset:3264
	s_waitcnt lgkmcnt(0)
	global_store_dwordx4 v[142:143], v[138:141], off offset:3072 sc0 sc1
	ds_read_b128 v[138:141], v0 offset:4352
	v_add_co_u32_e32 v142, vcc, s91, v136
	s_waitcnt lgkmcnt(0)
	global_store_dwordx4 v[144:145], v[138:141], off sc0 sc1
	ds_read_b128 v[138:141], v0 offset:5440
	v_addc_co_u32_e32 v143, vcc, 0, v137, vcc
	s_waitcnt lgkmcnt(0)
	global_store_dwordx4 v[144:145], v[138:141], off offset:1024 sc0 sc1
	ds_read_b128 v[138:141], v0 offset:6528
	s_waitcnt lgkmcnt(0)
	global_store_dwordx4 v[144:145], v[138:141], off offset:2048 sc0 sc1
	ds_read_b128 v[138:141], v0 offset:7616
	s_waitcnt lgkmcnt(0)
	global_store_dwordx4 v[144:145], v[138:141], off offset:3072 sc0 sc1
	s_waitcnt lgkmcnt(0)
	ds_write_b32 v146, v22
	ds_write_b32 v146, v23 offset:272
	ds_write_b32 v146, v24 offset:544
	ds_write_b32 v147, v25
	ds_write_b32 v146, v18 offset:64
	ds_write_b32 v146, v19 offset:336
	ds_write_b32 v146, v20 offset:608
	ds_write_b32 v147, v21 offset:64
	ds_write_b32 v146, v10 offset:128
	ds_write_b32 v146, v11 offset:400
	ds_write_b32 v146, v12 offset:672
	ds_write_b32 v147, v13 offset:128
	ds_write2_b32 v148, v14, v15 offset1:68
	ds_write_b32 v148, v16 offset:544
	ds_write_b32 v149, v17
	ds_write_b32 v146, v6 offset:4352
	ds_write_b32 v146, v7 offset:4624
	ds_write_b32 v146, v8 offset:4896
	ds_write_b32 v133, v9
	ds_write_b32 v146, v2 offset:4416
	ds_write_b32 v146, v3 offset:4688
	ds_write_b32 v146, v4 offset:4960
	ds_write_b32 v133, v5 offset:64
	ds_write_b32 v146, v26 offset:4480
	ds_write_b32 v146, v27 offset:4752
	ds_write_b32 v146, v28 offset:5024
	ds_write_b32 v133, v29 offset:128
	ds_write2_b32 v150, v62, v63 offset0:64 offset1:132
	ds_write_b32 v148, v64 offset:4896
	ds_write_b32 v131, v65
	s_waitcnt lgkmcnt(0)
	ds_read_b128 v[138:141], v0
	s_waitcnt lgkmcnt(0)
	global_store_dwordx4 v[142:143], v[138:141], off sc0 sc1
	ds_read_b128 v[138:141], v0 offset:1088
	s_waitcnt lgkmcnt(0)
	global_store_dwordx4 v[142:143], v[138:141], off offset:1024 sc0 sc1
	ds_read_b128 v[138:141], v0 offset:2176
	s_waitcnt lgkmcnt(0)
	global_store_dwordx4 v[142:143], v[138:141], off offset:2048 sc0 sc1
	ds_read_b128 v[138:141], v0 offset:3264
	s_waitcnt lgkmcnt(0)
	global_store_dwordx4 v[142:143], v[138:141], off offset:3072 sc0 sc1
	ds_read_b128 v[138:141], v0 offset:4352
	v_add_co_u32_e32 v142, vcc, 0x7000, v136
	s_nop 1
	v_addc_co_u32_e32 v143, vcc, 0, v137, vcc
	s_waitcnt lgkmcnt(0)
	global_store_dwordx4 v[142:143], v[138:141], off sc0 sc1
	ds_read_b128 v[136:139], v0 offset:5440
	s_waitcnt lgkmcnt(0)
	global_store_dwordx4 v[142:143], v[136:139], off offset:1024 sc0 sc1
	ds_read_b128 v[136:139], v0 offset:6528
	s_waitcnt lgkmcnt(0)
	global_store_dwordx4 v[142:143], v[136:139], off offset:2048 sc0 sc1
	ds_read_b128 v[136:139], v0 offset:7616
	s_waitcnt lgkmcnt(0)
	global_store_dwordx4 v[142:143], v[136:139], off offset:3072 sc0 sc1
	s_waitcnt lgkmcnt(0)

.LBB0_435:
	v_mov_b32_e32 v0, v226
	s_movk_i32 s2, 0x2400
	v_lshrrev_b32_e32 v0, 6, v0
	v_mul_lo_u32 v0, v0, s2
	v_add_u32_e32 v131, 0x10000, v0
	v_or_b32_e32 v138, v131, v215
	v_cvt_pk_bf16_f32 v132, v126, v127
	v_cvt_pk_bf16_f32 v133, v128, v129
	v_add_u32_e32 v156, v138, v218
	ds_write_b64 v156, v[132:133]
	v_cvt_pk_bf16_f32 v132, v122, v123
	v_cvt_pk_bf16_f32 v133, v124, v125
	ds_write_b64 v156, v[132:133] offset:2176
	v_cvt_pk_bf16_f32 v132, v118, v119
	v_cvt_pk_bf16_f32 v133, v120, v121
	ds_write_b64 v156, v[132:133] offset:4352
	v_cvt_pk_bf16_f32 v132, v114, v115
	v_cvt_pk_bf16_f32 v133, v116, v117
	v_add_u32_e32 v157, v138, v220
	ds_write_b64 v157, v[132:133]
	v_cvt_pk_bf16_f32 v132, v110, v111
	v_cvt_pk_bf16_f32 v133, v112, v113
	ds_write_b64 v156, v[132:133] offset:32
	v_cvt_pk_bf16_f32 v132, v106, v107
	v_cvt_pk_bf16_f32 v133, v108, v109
	ds_write_b64 v156, v[132:133] offset:2208
	v_cvt_pk_bf16_f32 v132, v102, v103
	v_cvt_pk_bf16_f32 v133, v104, v105
	ds_write_b64 v156, v[132:133] offset:4384
	v_cvt_pk_bf16_f32 v132, v98, v99
	v_cvt_pk_bf16_f32 v133, v100, v101
	ds_write_b64 v157, v[132:133] offset:32
	v_cvt_pk_bf16_f32 v132, v94, v95
	v_cvt_pk_bf16_f32 v133, v96, v97
	ds_write_b64 v156, v[132:133] offset:64
	v_cvt_pk_bf16_f32 v132, v90, v91
	v_cvt_pk_bf16_f32 v133, v92, v93
	ds_write_b64 v156, v[132:133] offset:2240
	v_cvt_pk_bf16_f32 v132, v82, v83
	v_cvt_pk_bf16_f32 v133, v84, v85
	ds_write_b64 v156, v[132:133] offset:4416
	v_cvt_pk_bf16_f32 v132, v86, v87
	v_cvt_pk_bf16_f32 v133, v88, v89
	ds_write_b64 v157, v[132:133] offset:64
	v_cvt_pk_bf16_f32 v132, v78, v79
	v_cvt_pk_bf16_f32 v133, v80, v81
	ds_write_b64 v156, v[132:133] offset:96
	v_cvt_pk_bf16_f32 v132, v74, v75
	v_cvt_pk_bf16_f32 v133, v76, v77
	ds_write_b64 v156, v[132:133] offset:2272
	v_cvt_pk_bf16_f32 v132, v70, v71
	v_cvt_pk_bf16_f32 v133, v72, v73
	v_lshlrev_b32_e32 v0, 1, v160
	ds_write_b64 v156, v[132:133] offset:4448
	v_cvt_pk_bf16_f32 v132, v66, v67
	v_cvt_pk_bf16_f32 v133, v68, v69
	v_or_b32_e32 v131, v131, v0
	ds_write_b64 v157, v[132:133] offset:96
	v_add_u32_e32 v155, v131, v217
	s_waitcnt lgkmcnt(0)
	v_lshl_add_u64 v[136:137], v[134:135], 0, v[0:1]
	ds_read2_b64 v[132:135], v155 offset1:1
	v_mul_u32_u24_e32 v0, v130, v216
	v_lshlrev_b32_e32 v0, 1, v0
	v_lshl_add_u64 v[138:139], v[136:137], 0, v[0:1]
	v_mul_u32_u24_e32 v0, v130, v221
	s_waitcnt lgkmcnt(0)
	global_store_dwordx4 v[138:139], v[132:135], off sc0 sc1
	ds_read2_b64 v[132:135], v155 offset0:136 offset1:137
	v_lshlrev_b32_e32 v0, 1, v0
	v_lshl_add_u64 v[140:141], v[136:137], 0, v[0:1]
	v_add_u32_e32 v165, 0x880, v155
	v_mul_u32_u24_e32 v0, v130, v222
	s_waitcnt lgkmcnt(0)
	global_store_dwordx4 v[140:141], v[132:135], off sc0 sc1
	ds_read2_b64 v[132:135], v165 offset1:1
	v_lshlrev_b32_e32 v0, 1, v0
	v_lshl_add_u64 v[142:143], v[136:137], 0, v[0:1]
	v_add_u32_e32 v167, 0xcc0, v155
	v_mul_u32_u24_e32 v0, v130, v223
	s_waitcnt lgkmcnt(0)
	global_store_dwordx4 v[142:143], v[132:135], off sc0 sc1
	ds_read2_b64 v[132:135], v167 offset1:1
	v_lshlrev_b32_e32 v0, 1, v0
	v_lshl_add_u64 v[144:145], v[136:137], 0, v[0:1]
	v_add_u32_e32 v169, 0x1100, v155
	v_mul_u32_u24_e32 v0, v130, v224
	s_waitcnt lgkmcnt(0)
	global_store_dwordx4 v[144:145], v[132:135], off sc0 sc1
	ds_read2_b64 v[132:135], v169 offset1:1
	v_lshlrev_b32_e32 v0, 1, v0
	v_lshl_add_u64 v[146:147], v[136:137], 0, v[0:1]
	v_add_u32_e32 v171, 0x1540, v155
	v_mul_u32_u24_e32 v0, v130, v225
	s_waitcnt lgkmcnt(0)
	global_store_dwordx4 v[146:147], v[132:135], off sc0 sc1
	ds_read2_b64 v[132:135], v171 offset1:1
	v_lshlrev_b32_e32 v0, 1, v0
	v_lshl_add_u64 v[148:149], v[136:137], 0, v[0:1]
	v_add_u32_e32 v173, 0x1980, v155
	v_mul_u32_u24_e32 v0, v130, v231
	s_waitcnt lgkmcnt(0)
	global_store_dwordx4 v[148:149], v[132:135], off sc0 sc1
	ds_read2_b64 v[132:135], v173 offset1:1
	v_lshlrev_b32_e32 v0, 1, v0
	v_lshl_add_u64 v[150:151], v[136:137], 0, v[0:1]
	v_add_u32_e32 v175, 0x1dc0, v155
	v_mul_u32_u24_e32 v0, v130, v232
	s_waitcnt lgkmcnt(0)
	global_store_dwordx4 v[150:151], v[132:135], off sc0 sc1
	ds_read2_b64 v[132:135], v175 offset1:1
	v_lshlrev_b32_e32 v0, 1, v0
	v_lshl_add_u64 v[136:137], v[136:137], 0, v[0:1]
	v_cvt_pk_bf16_f32 v130, v58, v59
	v_cvt_pk_bf16_f32 v131, v60, v61
	s_waitcnt lgkmcnt(0)
	global_store_dwordx4 v[136:137], v[132:135], off sc0 sc1
	s_waitcnt lgkmcnt(0)
	ds_write_b64 v156, v[130:131]
	v_cvt_pk_bf16_f32 v130, v54, v55
	v_cvt_pk_bf16_f32 v131, v56, v57
	ds_write_b64 v156, v[130:131] offset:2176
	v_cvt_pk_bf16_f32 v130, v46, v47
	v_cvt_pk_bf16_f32 v131, v48, v49
	ds_write_b64 v156, v[130:131] offset:4352
	v_cvt_pk_bf16_f32 v130, v50, v51
	v_cvt_pk_bf16_f32 v131, v52, v53
	ds_write_b64 v157, v[130:131]
	v_cvt_pk_bf16_f32 v130, v42, v43
	v_cvt_pk_bf16_f32 v131, v44, v45
	ds_write_b64 v156, v[130:131] offset:32
	v_cvt_pk_bf16_f32 v130, v38, v39
	v_cvt_pk_bf16_f32 v131, v40, v41
	ds_write_b64 v156, v[130:131] offset:2208
	v_cvt_pk_bf16_f32 v130, v34, v35
	v_cvt_pk_bf16_f32 v131, v36, v37
	ds_write_b64 v156, v[130:131] offset:4384
	v_cvt_pk_bf16_f32 v130, v30, v31
	v_cvt_pk_bf16_f32 v131, v32, v33
	ds_write_b64 v157, v[130:131] offset:32
	v_cvt_pk_bf16_f32 v130, v22, v23
	v_cvt_pk_bf16_f32 v131, v24, v25
	ds_write_b64 v156, v[130:131] offset:64
	v_cvt_pk_bf16_f32 v130, v18, v19
	v_cvt_pk_bf16_f32 v131, v20, v21
	ds_write_b64 v156, v[130:131] offset:2240
	v_cvt_pk_bf16_f32 v130, v10, v11
	v_cvt_pk_bf16_f32 v131, v12, v13
	ds_write_b64 v156, v[130:131] offset:4416
	v_cvt_pk_bf16_f32 v130, v14, v15
	v_cvt_pk_bf16_f32 v131, v16, v17
	ds_write_b64 v157, v[130:131] offset:64
	v_cvt_pk_bf16_f32 v130, v6, v7
	v_cvt_pk_bf16_f32 v131, v8, v9
	ds_write_b64 v156, v[130:131] offset:96
	v_cvt_pk_bf16_f32 v130, v2, v3
	v_cvt_pk_bf16_f32 v131, v4, v5
	ds_write_b64 v156, v[130:131] offset:2272
	v_cvt_pk_bf16_f32 v130, v26, v27
	v_cvt_pk_bf16_f32 v131, v28, v29
	ds_write_b64 v156, v[130:131] offset:4448
	v_cvt_pk_bf16_f32 v130, v62, v63
	v_cvt_pk_bf16_f32 v131, v64, v65
	ds_write_b64 v157, v[130:131] offset:96
	s_waitcnt lgkmcnt(0)
	ds_read2_b64 v[130:133], v155 offset1:1
	s_cmp_lg_u32 s36, 1
	s_cselect_b64 s[4:5], -1, 0
	s_and_b64 s[2:3], s[4:5], s[8:9]
	s_waitcnt lgkmcnt(0)
	global_store_dwordx4 v[138:139], v[130:133], off offset:128 sc0 sc1
	ds_read2_b64 v[130:133], v155 offset0:136 offset1:137
	s_waitcnt lgkmcnt(0)
	global_store_dwordx4 v[140:141], v[130:133], off offset:128 sc0 sc1
	ds_read2_b64 v[130:133], v165 offset1:1
	s_waitcnt lgkmcnt(0)
	global_store_dwordx4 v[142:143], v[130:133], off offset:128 sc0 sc1
	ds_read2_b64 v[130:133], v167 offset1:1
	s_waitcnt lgkmcnt(0)
	global_store_dwordx4 v[144:145], v[130:133], off offset:128 sc0 sc1
	ds_read2_b64 v[130:133], v169 offset1:1
	s_waitcnt lgkmcnt(0)
	global_store_dwordx4 v[146:147], v[130:133], off offset:128 sc0 sc1
	ds_read2_b64 v[130:133], v171 offset1:1
	s_waitcnt lgkmcnt(0)
	global_store_dwordx4 v[148:149], v[130:133], off offset:128 sc0 sc1
	ds_read2_b64 v[130:133], v173 offset1:1
	s_waitcnt lgkmcnt(0)
	global_store_dwordx4 v[150:151], v[130:133], off offset:128 sc0 sc1
	ds_read2_b64 v[130:133], v175 offset1:1
	s_waitcnt lgkmcnt(0)
	global_store_dwordx4 v[136:137], v[130:133], off offset:128 sc0 sc1
	s_waitcnt lgkmcnt(0)
	s_and_saveexec_b64 s[4:5], s[2:3]
	s_cbranch_execz .LBB0_323
	s_load_dwordx2 s[2:3], s[0:1], 0xe8
	v_lshl_add_u32 v130, v154, 2, s74
	v_ashrrev_i32_e32 v131, 31, v130
	v_lshlrev_b64 v[130:131], 19, v[130:131]
	s_cmp_lg_u32 s36, 5
	s_mov_b64 s[8:9], -1
	s_waitcnt lgkmcnt(0)
	v_lshl_add_u64 v[132:133], s[2:3], 0, v[130:131]
	s_cbranch_scc0 .LBB0_438
	v_lshlrev_b32_e32 v0, 2, v152
	v_and_b32_e32 v0, 0x700, v0
	v_add_lshl_u32 v0, v153, v0, 8
	v_lshl_add_u64 v[130:131], v[132:133], 0, v[0:1]
	s_mov_b64 s[2:3], 0xf000000
	v_lshl_add_u64 v[130:131], v[130:131], 0, s[2:3]
	s_mov_b64 s[8:9], 0

.LBB0_445:
	s_or_b64 exec, exec, s[4:5]
	s_waitcnt vmcnt(0)
	v_mov_b32_e32 v64, v49
	v_mov_b32_e32 v65, v50
	v_mov_b32_e32 v66, v48
	v_mov_b32_e32 v67, v51
	v_pk_add_f32 v[64:65], v[64:65], v[66:67]
	v_mov_b32_e32 v66, v45
	v_mov_b32_e32 v67, v46
	v_mov_b32_e32 v68, v44
	v_mov_b32_e32 v69, v47
	v_pk_add_f32 v[66:67], v[66:67], v[68:69]
	v_add_f32_e32 v0, v64, v65
	v_pk_add_f32 v[66:67], v[66:67], v[66:67] op_sel:[0,1] op_sel_hi:[1,0]
	v_add_f32_e32 v64, 0, v0
	v_add_f32_e32 v68, v40, v41
	v_add_f32_e32 v70, v42, v43
	v_mov_b32_e32 v65, v36
	v_mov_b32_e32 v67, v37
	v_mov_b32_e32 v69, v38
	v_mov_b32_e32 v71, v39
	v_pk_add_f32 v[64:65], v[64:65], v[66:67]
	v_pk_add_f32 v[66:67], v[68:69], v[70:71]
	s_mov_b32 s3, 0x800000
	v_pk_add_f32 v[64:65], v[64:65], v[66:67]
	v_lshl_add_u64 v[2:3], v[2:3], 1, v[54:55]
	v_add_f32_e32 v0, v64, v65
	s_add_i32 s2, s2, s99
	s_cmpk_gt_i32 s2, 0x11ff
	v_add_u32_e32 v56, s12, v56
	s_nop 1
	v_add_f32_dpp v0, v0, v0 quad_perm:[1,0,3,2] row_mask:0xf bank_mask:0xf
	s_nop 1
	v_add_f32_dpp v0, v0, v0 quad_perm:[2,3,0,1] row_mask:0xf bank_mask:0xf
	s_nop 1
	v_add_f32_dpp v0, v0, v0 row_half_mirror row_mask:0xf bank_mask:0xf
	s_nop 1
	v_add_f32_dpp v0, v0, v0 row_mirror row_mask:0xf bank_mask:0xf
	s_nop 1
	v_readlane_b32 s100, v0, 0
	v_readlane_b32 s101, v0, 16
	v_readlane_b32 vcc_lo, v0, 32
	v_readlane_b32 vcc_hi, v0, 48
	s_nop 1
	v_mov_b32_e32 v57, s100
	v_add_f32_e32 v57, s101, v57
	v_add_f32_e32 v57, vcc_lo, v57
	v_add_f32_e32 v57, vcc_hi, v57
	v_fmamk_f32 v49, v57, 0xba800000, v49
	v_fmamk_f32 v48, v57, 0xba800000, v48
	v_fmamk_f32 v51, v57, 0xba800000, v51
	v_fmac_f32_e32 v50, 0xba800000, v57
	v_pk_mul_f32 v[64:65], v[50:51], v[50:51]
	v_pk_mul_f32 v[66:67], v[48:49], v[48:49]
	v_fmamk_f32 v45, v57, 0xba800000, v45
	v_fmamk_f32 v44, v57, 0xba800000, v44
	v_fmamk_f32 v47, v57, 0xba800000, v47
	v_pk_mov_b32 v[68:69], v[66:67], v[64:65] op_sel:[1,0]
	v_mov_b32_e32 v67, v65
	v_fmac_f32_e32 v46, 0xba800000, v57
	v_pk_add_f32 v[64:65], v[68:69], v[66:67]
	v_pk_mul_f32 v[66:67], v[46:47], v[46:47]
	v_pk_mul_f32 v[68:69], v[44:45], v[44:45]
	v_fmamk_f32 v40, v57, 0xba800000, v40
	v_pk_mov_b32 v[70:71], v[68:69], v[66:67] op_sel:[1,0]
	v_mov_b32_e32 v69, v67
	v_fmamk_f32 v41, v57, 0xba800000, v41
	v_fmac_f32_e32 v42, 0xba800000, v57
	v_mul_f32_e32 v0, v40, v40
	v_pk_add_f32 v[66:67], v[70:71], v[68:69]
	v_fmamk_f32 v43, v57, 0xba800000, v43
	v_pk_fma_f32 v[68:69], v[40:41], v[40:41], v[0:1] op_sel_hi:[1,1,0]
	v_mul_f32_e32 v0, v42, v42
	v_pk_add_f32 v[64:65], v[64:65], v[64:65] op_sel_hi:[0,1]
	v_pk_add_f32 v[66:67], v[66:67], v[66:67] op_sel_hi:[0,1]
	v_pk_fma_f32 v[70:71], v[42:43], v[42:43], v[0:1] op_sel_hi:[1,1,0]
	v_fmamk_f32 v39, v57, 0xba800000, v39
	v_fmamk_f32 v38, v57, 0xba800000, v38
	v_fmamk_f32 v37, v57, 0xba800000, v37
	v_fmac_f32_e32 v36, 0xba800000, v57
	v_mul_f32_e32 v68, v36, v36
	v_mul_f32_e32 v70, v37, v37
	v_mul_f32_e32 v64, v38, v38
	v_mul_f32_e32 v66, v39, v39
	v_pk_add_f32 v[68:69], v[68:69], v[70:71]
	v_pk_add_f32 v[64:65], v[64:65], v[66:67]
	v_pk_add_f32 v[66:67], v[16:17], 1.0 op_sel_hi:[1,0]
	v_pk_add_f32 v[64:65], v[68:69], v[64:65]
	s_nop 0
	v_add_f32_e32 v0, v64, v65
	v_pk_add_f32 v[64:65], v[18:19], 1.0 op_sel_hi:[1,0]
	s_nop 1
	v_add_f32_dpp v0, v0, v0 quad_perm:[1,0,3,2] row_mask:0xf bank_mask:0xf
	s_nop 1
	v_add_f32_dpp v0, v0, v0 quad_perm:[2,3,0,1] row_mask:0xf bank_mask:0xf
	s_nop 1
	v_add_f32_dpp v0, v0, v0 row_half_mirror row_mask:0xf bank_mask:0xf
	s_nop 1
	v_add_f32_dpp v0, v0, v0 row_mirror row_mask:0xf bank_mask:0xf
	s_nop 1
	v_readlane_b32 s100, v0, 0
	v_readlane_b32 s101, v0, 16
	v_readlane_b32 vcc_lo, v0, 32
	v_readlane_b32 vcc_hi, v0, 48
	s_nop 1
	v_mov_b32_e32 v0, s100
	v_add_f32_e32 v0, s101, v0
	v_add_f32_e32 v0, vcc_lo, v0
	v_add_f32_e32 v0, vcc_hi, v0
	v_fmamk_f32 v0, v0, 0x3a800000, v227
	v_mul_f32_e32 v57, 0x4b800000, v0
	v_cmp_gt_f32_e32 vcc, s3, v0
	s_nop 1
	v_cndmask_b32_e32 v0, v0, v57, vcc
	v_rsq_f32_e32 v0, v0
	s_nop 0
	v_mul_f32_e32 v57, 0x45800000, v0
	v_cndmask_b32_e32 v0, v0, v57, vcc
	v_pk_mul_f32 v[48:49], v[48:49], v[0:1] op_sel_hi:[1,0]
	v_pk_mul_f32 v[50:51], v[50:51], v[0:1] op_sel_hi:[1,0]
	v_pk_fma_f32 v[48:49], v[66:67], v[48:49], v[4:5]
	v_pk_fma_f32 v[50:51], v[64:65], v[50:51], v[6:7]
	v_cvt_pk_bf16_f32 v48, v48, v49
	v_cvt_pk_bf16_f32 v49, v50, v51
	global_store_dwordx2 v[2:3], v[48:49], off sc0 sc1
	v_pk_mul_f32 v[44:45], v[44:45], v[0:1] op_sel_hi:[1,0]
	v_pk_mul_f32 v[46:47], v[46:47], v[0:1] op_sel_hi:[1,0]
	v_pk_add_f32 v[48:49], v[10:11], 1.0 op_sel_hi:[1,0]
	v_pk_add_f32 v[50:51], v[8:9], 1.0 op_sel_hi:[1,0]
	v_pk_fma_f32 v[46:47], v[48:49], v[46:47], v[22:23]
	v_pk_fma_f32 v[44:45], v[50:51], v[44:45], v[20:21]
	v_pk_mul_f32 v[40:41], v[40:41], v[0:1] op_sel_hi:[1,0]
	v_cvt_pk_bf16_f32 v44, v44, v45
	v_cvt_pk_bf16_f32 v45, v46, v47
	global_store_dwordx2 v[2:3], v[44:45], off offset:512 sc0 sc1
	v_pk_mul_f32 v[42:43], v[42:43], v[0:1] op_sel_hi:[1,0]
	v_pk_add_f32 v[44:45], v[14:15], 1.0 op_sel_hi:[1,0]
	v_pk_add_f32 v[46:47], v[12:13], 1.0 op_sel_hi:[1,0]
	v_pk_fma_f32 v[42:43], v[44:45], v[42:43], v[26:27]
	v_pk_fma_f32 v[40:41], v[46:47], v[40:41], v[24:25]
	v_pk_mul_f32 v[36:37], v[36:37], v[0:1] op_sel_hi:[1,0]
	v_cvt_pk_bf16_f32 v40, v40, v41
	v_cvt_pk_bf16_f32 v41, v42, v43
	global_store_dwordx2 v[2:3], v[40:41], off offset:1024 sc0 sc1
	v_pk_mul_f32 v[38:39], v[38:39], v[0:1] op_sel_hi:[1,0]
	v_pk_add_f32 v[40:41], v[34:35], 1.0 op_sel_hi:[1,0]
	v_pk_add_f32 v[42:43], v[32:33], 1.0 op_sel_hi:[1,0]
	v_pk_fma_f32 v[38:39], v[40:41], v[38:39], v[30:31]
	v_pk_fma_f32 v[36:37], v[42:43], v[36:37], v[28:29]
	s_nop 0
	v_cvt_pk_bf16_f32 v36, v36, v37
	v_cvt_pk_bf16_f32 v37, v38, v39
	global_store_dwordx2 v[2:3], v[36:37], off offset:1536 sc0 sc1
	s_cbranch_scc1 .LBB0_452

.LBB0_463:
	s_cmpk_lg_i32 s28, 0xc0
	s_cbranch_scc0 .LBB0_497
	s_cmpk_gt_u32 s28, 0xc1
	s_cbranch_scc0 .LBB0_490
	s_cmpk_gt_u32 s28, 0x101
	s_cbranch_scc0 .LBB0_487
	s_cmpk_gt_u32 s28, 0xc01
	s_cbranch_scc0 .LBB0_484
	s_cmpk_gt_u32 s28, 0x1201
	s_cbranch_scc0 .LBB0_481
	s_cmpk_gt_u32 s28, 0x1301
	s_cbranch_scc0 .LBB0_478
	s_cmpk_gt_u32 s28, 0x1401
	s_cbranch_scc0 .LBB0_475
	s_cmpk_gt_u32 s28, 0x1501
	s_cbranch_scc0 .LBB0_472
	s_add_i32 s3, s28, 0xffffeafe
	s_load_dwordx2 s[4:5], s[0:1], 0xd0
	s_waitcnt lgkmcnt(0)
	s_load_dwordx2 s[18:19], s[0:1], 0x118
	s_lshl_b32 s2, s3, 3
	s_and_b32 s22, s2, 0x3c0
	s_lshl_b32 s2, s3, 7
	s_lshl_b32 s3, s3, 13
	s_and_b32 s94, s3, 0x7ff00000
	s_and_b32 s2, s2, 0x380
	s_lshl_b64 s[20:21], s[94:95], 2
	s_waitcnt lgkmcnt(0)
	s_add_u32 s3, s4, s20
	s_addc_u32 s5, s5, s21
	s_lshl_b32 s4, s94, 1
	s_add_u32 s18, s18, s4
	v_mov_b32_e32 v20, v226
	s_addc_u32 s19, s19, 0
	s_lshl_b32 s4, s2, 2
	v_ashrrev_i32_e32 v18, 5, v20
	v_add_u32_e32 v21, 0x200, v20
	s_add_u32 s4, s3, s4
	v_lshlrev_b32_e32 v0, 4, v20
	v_add_u32_e32 v2, s22, v18
	v_ashrrev_i32_e32 v22, 5, v21
	v_add_u32_e32 v10, 0x400, v20
	s_addc_u32 s5, s5, 0
	v_and_b32_e32 v0, 0x1f0, v0
	v_ashrrev_i32_e32 v3, 31, v2
	v_add_u32_e32 v6, s22, v22
	v_ashrrev_i32_e32 v23, 5, v10
	v_lshl_add_u64 v[14:15], s[4:5], 0, v[0:1]
	v_lshlrev_b64 v[2:3], 12, v[2:3]
	v_ashrrev_i32_e32 v7, 31, v6
	v_add_u32_e32 v10, s22, v23
	v_lshl_add_u64 v[2:3], v[14:15], 0, v[2:3]
	v_lshlrev_b64 v[6:7], 12, v[6:7]
	v_ashrrev_i32_e32 v11, 31, v10
	v_add_u32_e32 v16, 0x600, v20
	s_waitcnt vmcnt(0)
	s_barrier
	global_load_dwordx4 v[2:5], v[2:3], off
	v_lshl_add_u64 v[6:7], v[14:15], 0, v[6:7]
	v_lshlrev_b64 v[10:11], 12, v[10:11]
	v_ashrrev_i32_e32 v24, 5, v16
	global_load_dwordx4 v[6:9], v[6:7], off
	v_lshl_add_u64 v[10:11], v[14:15], 0, v[10:11]
	v_add_u32_e32 v16, s22, v24
	global_load_dwordx4 v[10:13], v[10:11], off
	v_ashrrev_i32_e32 v17, 31, v16
	v_lshlrev_b64 v[16:17], 12, v[16:17]
	v_lshl_add_u64 v[14:15], v[14:15], 0, v[16:17]
	global_load_dwordx4 v[14:17], v[14:15], off
	s_movk_i32 s3, 0x204
	v_mad_u64_u32 v[18:19], s[4:5], v18, s3, v[0:1]
	s_waitcnt vmcnt(3)
	ds_write2_b32 v18, v2, v3 offset1:1
	ds_write2_b32 v18, v4, v5 offset0:2 offset1:3
	v_mad_u64_u32 v[2:3], s[4:5], v22, s3, v[0:1]
	s_waitcnt vmcnt(2)
	ds_write2_b32 v2, v6, v7 offset1:1
	ds_write2_b32 v2, v8, v9 offset0:2 offset1:3
	v_mad_u64_u32 v[2:3], s[4:5], v23, s3, v[0:1]
	s_waitcnt vmcnt(1)
	ds_write2_b32 v2, v10, v11 offset1:1
	ds_write2_b32 v2, v12, v13 offset0:2 offset1:3
	v_mad_u64_u32 v[2:3], s[4:5], v24, s3, v[0:1]
	v_lshlrev_b32_e32 v0, 3, v20
	s_lshl_b32 s3, s22, 1
	v_and_b32_e32 v4, 56, v0
	s_add_u32 s4, s18, s3
	s_addc_u32 s5, s19, 0
	v_lshlrev_b32_e32 v0, 1, v4
	s_waitcnt vmcnt(0)
	ds_write2_b32 v2, v14, v15 offset1:1
	ds_write2_b32 v2, v16, v17 offset0:2 offset1:3
	v_lshl_add_u64 v[2:3], s[4:5], 0, v[0:1]
	v_mul_u32_u24_e32 v0, 0x204, v4
	v_ashrrev_i32_e32 v12, 3, v20
	v_lshl_add_u32 v10, v12, 2, v0
	v_add_u32_e32 v6, 0x400, v10
	v_add_u32_e32 v8, 0x800, v10
	s_waitcnt lgkmcnt(0)
	s_barrier
	ds_read2_b32 v[4:5], v10 offset1:129
	ds_read2_b32 v[6:7], v6 offset0:2 offset1:131
	ds_read2_b32 v[8:9], v8 offset0:4 offset1:133
	v_add_u32_e32 v10, 0xc00, v10
	ds_read2_b32 v[10:11], v10 offset0:6 offset1:135
	s_waitcnt lgkmcnt(3)
	v_cvt_pk_bf16_f32 v4, v4, v5
	s_waitcnt lgkmcnt(2)
	v_cvt_pk_bf16_f32 v5, v6, v7
	s_waitcnt lgkmcnt(1)
	v_cvt_pk_bf16_f32 v6, v8, v9
	v_add_u32_e32 v8, s2, v12
	v_ashrrev_i32_e32 v9, 31, v8
	v_lshlrev_b64 v[8:9], 11, v[8:9]
	v_ashrrev_i32_e32 v12, 3, v21
	s_waitcnt lgkmcnt(0)
	v_cvt_pk_bf16_f32 v7, v10, v11
	v_lshl_add_u64 v[8:9], v[2:3], 0, v[8:9]
	v_lshl_add_u32 v0, v12, 2, v0
	global_store_dwordx4 v[8:9], v[4:7], off sc0 sc1
	v_add_u32_e32 v8, 0x800, v0
	ds_read2_b32 v[4:5], v0 offset1:129
	v_add_u32_e32 v6, 0x400, v0
	ds_read2_b32 v[6:7], v6 offset0:2 offset1:131
	ds_read2_b32 v[8:9], v8 offset0:4 offset1:133
	v_add_u32_e32 v0, 0xc00, v0
	ds_read2_b32 v[10:11], v0 offset0:6 offset1:135
	s_waitcnt lgkmcnt(3)
	v_cvt_pk_bf16_f32 v4, v4, v5
	s_waitcnt lgkmcnt(2)
	v_cvt_pk_bf16_f32 v5, v6, v7
	s_waitcnt lgkmcnt(1)
	v_cvt_pk_bf16_f32 v6, v8, v9
	v_add_u32_e32 v8, s2, v12
	v_ashrrev_i32_e32 v9, 31, v8
	v_lshlrev_b64 v[8:9], 11, v[8:9]
	s_waitcnt lgkmcnt(0)
	v_cvt_pk_bf16_f32 v7, v10, v11
	v_lshl_add_u64 v[2:3], v[2:3], 0, v[8:9]
	global_store_dwordx4 v[2:3], v[4:7], off sc0 sc1
	s_mov_b64 s[4:5], 0
.LBB0_472:
	s_andn2_b64 vcc, exec, s[4:5]
	s_cbranch_vccnz .LBB0_474
	s_add_i32 s3, s28, 0xffffebfe
	s_load_dwordx2 s[4:5], s[0:1], 0xb8
	s_waitcnt lgkmcnt(0)
	s_load_dwordx2 s[18:19], s[0:1], 0x110
	s_lshl_b32 s2, s3, 3
	s_and_b32 s22, s2, 0x1c0
	s_lshl_b32 s2, s3, 7
	s_lshl_b32 s3, s3, 13
	s_and_b32 s94, s3, 0x7ff80000
	s_and_b32 s2, s2, 0x380
	s_lshl_b64 s[20:21], s[94:95], 2
	s_waitcnt lgkmcnt(0)
	s_add_u32 s3, s4, s20
	s_addc_u32 s5, s5, s21
	s_lshl_b32 s4, s94, 1
	s_add_u32 s18, s18, s4
	v_mov_b32_e32 v20, v226
	s_addc_u32 s19, s19, 0
	s_lshl_b32 s4, s2, 2
	v_ashrrev_i32_e32 v18, 5, v20
	v_add_u32_e32 v21, 0x200, v20
	s_add_u32 s4, s3, s4
	v_lshlrev_b32_e32 v0, 4, v20
	v_add_u32_e32 v2, s22, v18
	v_ashrrev_i32_e32 v22, 5, v21
	v_add_u32_e32 v10, 0x400, v20
	s_addc_u32 s5, s5, 0
	v_and_b32_e32 v0, 0x1f0, v0
	v_ashrrev_i32_e32 v3, 31, v2
	v_add_u32_e32 v6, s22, v22
	v_ashrrev_i32_e32 v23, 5, v10
	v_lshl_add_u64 v[14:15], s[4:5], 0, v[0:1]
	v_lshlrev_b64 v[2:3], 12, v[2:3]
	v_ashrrev_i32_e32 v7, 31, v6
	v_add_u32_e32 v10, s22, v23
	v_lshl_add_u64 v[2:3], v[14:15], 0, v[2:3]
	v_lshlrev_b64 v[6:7], 12, v[6:7]
	v_ashrrev_i32_e32 v11, 31, v10
	v_add_u32_e32 v16, 0x600, v20
	s_waitcnt vmcnt(0)
	s_barrier
	global_load_dwordx4 v[2:5], v[2:3], off
	v_lshl_add_u64 v[6:7], v[14:15], 0, v[6:7]
	v_lshlrev_b64 v[10:11], 12, v[10:11]
	v_ashrrev_i32_e32 v24, 5, v16
	global_load_dwordx4 v[6:9], v[6:7], off
	v_lshl_add_u64 v[10:11], v[14:15], 0, v[10:11]
	v_add_u32_e32 v16, s22, v24
	global_load_dwordx4 v[10:13], v[10:11], off
	v_ashrrev_i32_e32 v17, 31, v16
	v_lshlrev_b64 v[16:17], 12, v[16:17]
	v_lshl_add_u64 v[14:15], v[14:15], 0, v[16:17]
	global_load_dwordx4 v[14:17], v[14:15], off
	s_movk_i32 s3, 0x204
	v_mad_u64_u32 v[18:19], s[4:5], v18, s3, v[0:1]
	s_waitcnt vmcnt(3)
	ds_write2_b32 v18, v2, v3 offset1:1
	ds_write2_b32 v18, v4, v5 offset0:2 offset1:3
	v_mad_u64_u32 v[2:3], s[4:5], v22, s3, v[0:1]
	s_waitcnt vmcnt(2)
	ds_write2_b32 v2, v6, v7 offset1:1
	ds_write2_b32 v2, v8, v9 offset0:2 offset1:3
	v_mad_u64_u32 v[2:3], s[4:5], v23, s3, v[0:1]
	s_waitcnt vmcnt(1)
	ds_write2_b32 v2, v10, v11 offset1:1
	ds_write2_b32 v2, v12, v13 offset0:2 offset1:3
	v_mad_u64_u32 v[2:3], s[4:5], v24, s3, v[0:1]
	v_lshlrev_b32_e32 v0, 3, v20
	s_lshl_b32 s3, s22, 1
	v_and_b32_e32 v4, 56, v0
	s_add_u32 s4, s18, s3
	s_addc_u32 s5, s19, 0
	v_lshlrev_b32_e32 v0, 1, v4
	s_waitcnt vmcnt(0)
	ds_write2_b32 v2, v14, v15 offset1:1
	ds_write2_b32 v2, v16, v17 offset0:2 offset1:3
	v_lshl_add_u64 v[2:3], s[4:5], 0, v[0:1]
	v_mul_u32_u24_e32 v0, 0x204, v4
	v_ashrrev_i32_e32 v12, 3, v20
	v_lshl_add_u32 v10, v12, 2, v0
	v_add_u32_e32 v6, 0x400, v10
	v_add_u32_e32 v8, 0x800, v10
	s_waitcnt lgkmcnt(0)
	s_barrier
	ds_read2_b32 v[4:5], v10 offset1:129
	ds_read2_b32 v[6:7], v6 offset0:2 offset1:131
	ds_read2_b32 v[8:9], v8 offset0:4 offset1:133
	v_add_u32_e32 v10, 0xc00, v10
	ds_read2_b32 v[10:11], v10 offset0:6 offset1:135
	s_waitcnt lgkmcnt(3)
	v_cvt_pk_bf16_f32 v4, v4, v5
	s_waitcnt lgkmcnt(2)
	v_cvt_pk_bf16_f32 v5, v6, v7
	s_waitcnt lgkmcnt(1)
	v_cvt_pk_bf16_f32 v6, v8, v9
	v_add_u32_e32 v8, s2, v12
	v_ashrrev_i32_e32 v9, 31, v8
	v_lshlrev_b64 v[8:9], 10, v[8:9]
	v_ashrrev_i32_e32 v12, 3, v21
	s_waitcnt lgkmcnt(0)
	v_cvt_pk_bf16_f32 v7, v10, v11
	v_lshl_add_u64 v[8:9], v[2:3], 0, v[8:9]
	v_lshl_add_u32 v0, v12, 2, v0
	global_store_dwordx4 v[8:9], v[4:7], off sc0 sc1
	v_add_u32_e32 v8, 0x800, v0
	ds_read2_b32 v[4:5], v0 offset1:129
	v_add_u32_e32 v6, 0x400, v0
	ds_read2_b32 v[6:7], v6 offset0:2 offset1:131
	ds_read2_b32 v[8:9], v8 offset0:4 offset1:133
	v_add_u32_e32 v0, 0xc00, v0
	ds_read2_b32 v[10:11], v0 offset0:6 offset1:135
	s_waitcnt lgkmcnt(3)
	v_cvt_pk_bf16_f32 v4, v4, v5
	s_waitcnt lgkmcnt(2)
	v_cvt_pk_bf16_f32 v5, v6, v7
	s_waitcnt lgkmcnt(1)
	v_cvt_pk_bf16_f32 v6, v8, v9
	v_add_u32_e32 v8, s2, v12
	v_ashrrev_i32_e32 v9, 31, v8
	v_lshlrev_b64 v[8:9], 10, v[8:9]
	s_waitcnt lgkmcnt(0)
	v_cvt_pk_bf16_f32 v7, v10, v11
	v_lshl_add_u64 v[2:3], v[2:3], 0, v[8:9]
	global_store_dwordx4 v[2:3], v[4:7], off sc0 sc1

.LBB0_475:
	s_andn2_b64 vcc, exec, s[4:5]
	s_cbranch_vccnz .LBB0_477
	s_add_i32 s3, s28, 0xffffecfe
	s_load_dwordx2 s[4:5], s[0:1], 0xb0
	s_waitcnt lgkmcnt(0)
	s_load_dwordx2 s[18:19], s[0:1], 0x108
	s_lshl_b32 s2, s3, 3
	s_and_b32 s22, s2, 0x1c0
	s_lshl_b32 s2, s3, 7
	s_lshl_b32 s3, s3, 13
	s_and_b32 s94, s3, 0x7ff80000
	s_and_b32 s2, s2, 0x380
	s_lshl_b64 s[20:21], s[94:95], 2
	s_waitcnt lgkmcnt(0)
	s_add_u32 s3, s4, s20
	s_addc_u32 s5, s5, s21
	s_lshl_b32 s4, s94, 1
	s_add_u32 s18, s18, s4
	v_mov_b32_e32 v20, v226
	s_addc_u32 s19, s19, 0
	s_lshl_b32 s4, s2, 2
	v_ashrrev_i32_e32 v18, 5, v20
	v_add_u32_e32 v21, 0x200, v20
	s_add_u32 s4, s3, s4
	v_lshlrev_b32_e32 v0, 4, v20
	v_add_u32_e32 v2, s22, v18
	v_ashrrev_i32_e32 v22, 5, v21
	v_add_u32_e32 v10, 0x400, v20
	s_addc_u32 s5, s5, 0
	v_and_b32_e32 v0, 0x1f0, v0
	v_ashrrev_i32_e32 v3, 31, v2
	v_add_u32_e32 v6, s22, v22
	v_ashrrev_i32_e32 v23, 5, v10
	v_lshl_add_u64 v[14:15], s[4:5], 0, v[0:1]
	v_lshlrev_b64 v[2:3], 12, v[2:3]
	v_ashrrev_i32_e32 v7, 31, v6
	v_add_u32_e32 v10, s22, v23
	v_lshl_add_u64 v[2:3], v[14:15], 0, v[2:3]
	v_lshlrev_b64 v[6:7], 12, v[6:7]
	v_ashrrev_i32_e32 v11, 31, v10
	v_add_u32_e32 v16, 0x600, v20
	s_waitcnt vmcnt(0)
	s_barrier
	global_load_dwordx4 v[2:5], v[2:3], off
	v_lshl_add_u64 v[6:7], v[14:15], 0, v[6:7]
	v_lshlrev_b64 v[10:11], 12, v[10:11]
	v_ashrrev_i32_e32 v24, 5, v16
	global_load_dwordx4 v[6:9], v[6:7], off
	v_lshl_add_u64 v[10:11], v[14:15], 0, v[10:11]
	v_add_u32_e32 v16, s22, v24
	global_load_dwordx4 v[10:13], v[10:11], off
	v_ashrrev_i32_e32 v17, 31, v16
	v_lshlrev_b64 v[16:17], 12, v[16:17]
	v_lshl_add_u64 v[14:15], v[14:15], 0, v[16:17]
	global_load_dwordx4 v[14:17], v[14:15], off
	s_movk_i32 s3, 0x204
	v_mad_u64_u32 v[18:19], s[4:5], v18, s3, v[0:1]
	s_waitcnt vmcnt(3)
	ds_write2_b32 v18, v2, v3 offset1:1
	ds_write2_b32 v18, v4, v5 offset0:2 offset1:3
	v_mad_u64_u32 v[2:3], s[4:5], v22, s3, v[0:1]
	s_waitcnt vmcnt(2)
	ds_write2_b32 v2, v6, v7 offset1:1
	ds_write2_b32 v2, v8, v9 offset0:2 offset1:3
	v_mad_u64_u32 v[2:3], s[4:5], v23, s3, v[0:1]
	s_waitcnt vmcnt(1)
	ds_write2_b32 v2, v10, v11 offset1:1
	ds_write2_b32 v2, v12, v13 offset0:2 offset1:3
	v_mad_u64_u32 v[2:3], s[4:5], v24, s3, v[0:1]
	v_lshlrev_b32_e32 v0, 3, v20
	s_lshl_b32 s3, s22, 1
	v_and_b32_e32 v4, 56, v0
	s_add_u32 s4, s18, s3
	s_addc_u32 s5, s19, 0
	v_lshlrev_b32_e32 v0, 1, v4
	s_waitcnt vmcnt(0)
	ds_write2_b32 v2, v14, v15 offset1:1
	ds_write2_b32 v2, v16, v17 offset0:2 offset1:3
	v_lshl_add_u64 v[2:3], s[4:5], 0, v[0:1]
	v_mul_u32_u24_e32 v0, 0x204, v4
	v_ashrrev_i32_e32 v12, 3, v20
	v_lshl_add_u32 v10, v12, 2, v0
	v_add_u32_e32 v6, 0x400, v10
	v_add_u32_e32 v8, 0x800, v10
	s_waitcnt lgkmcnt(0)
	s_barrier
	ds_read2_b32 v[4:5], v10 offset1:129
	ds_read2_b32 v[6:7], v6 offset0:2 offset1:131
	ds_read2_b32 v[8:9], v8 offset0:4 offset1:133
	v_add_u32_e32 v10, 0xc00, v10
	ds_read2_b32 v[10:11], v10 offset0:6 offset1:135
	s_waitcnt lgkmcnt(3)
	v_cvt_pk_bf16_f32 v4, v4, v5
	s_waitcnt lgkmcnt(2)
	v_cvt_pk_bf16_f32 v5, v6, v7
	s_waitcnt lgkmcnt(1)
	v_cvt_pk_bf16_f32 v6, v8, v9
	v_add_u32_e32 v8, s2, v12
	v_ashrrev_i32_e32 v9, 31, v8
	v_lshlrev_b64 v[8:9], 10, v[8:9]
	v_ashrrev_i32_e32 v12, 3, v21
	s_waitcnt lgkmcnt(0)
	v_cvt_pk_bf16_f32 v7, v10, v11
	v_lshl_add_u64 v[8:9], v[2:3], 0, v[8:9]
	v_lshl_add_u32 v0, v12, 2, v0
	global_store_dwordx4 v[8:9], v[4:7], off sc0 sc1
	v_add_u32_e32 v8, 0x800, v0
	ds_read2_b32 v[4:5], v0 offset1:129
	v_add_u32_e32 v6, 0x400, v0
	ds_read2_b32 v[6:7], v6 offset0:2 offset1:131
	ds_read2_b32 v[8:9], v8 offset0:4 offset1:133
	v_add_u32_e32 v0, 0xc00, v0
	ds_read2_b32 v[10:11], v0 offset0:6 offset1:135
	s_waitcnt lgkmcnt(3)
	v_cvt_pk_bf16_f32 v4, v4, v5
	s_waitcnt lgkmcnt(2)
	v_cvt_pk_bf16_f32 v5, v6, v7
	s_waitcnt lgkmcnt(1)
	v_cvt_pk_bf16_f32 v6, v8, v9
	v_add_u32_e32 v8, s2, v12
	v_ashrrev_i32_e32 v9, 31, v8
	v_lshlrev_b64 v[8:9], 10, v[8:9]
	s_waitcnt lgkmcnt(0)
	v_cvt_pk_bf16_f32 v7, v10, v11
	v_lshl_add_u64 v[2:3], v[2:3], 0, v[8:9]
	global_store_dwordx4 v[2:3], v[4:7], off sc0 sc1

.LBB0_478:
	s_andn2_b64 vcc, exec, s[4:5]
	s_cbranch_vccnz .LBB0_480
	s_add_i32 s3, s28, 0xffffedfe
	s_load_dwordx2 s[4:5], s[0:1], 0xa8
	s_waitcnt lgkmcnt(0)
	s_load_dwordx2 s[18:19], s[0:1], 0x100
	s_lshl_b32 s2, s3, 3
	s_and_b32 s22, s2, 0x1c0
	s_lshl_b32 s2, s3, 7
	s_lshl_b32 s3, s3, 13
	s_and_b32 s94, s3, 0x7ff80000
	s_and_b32 s2, s2, 0x380
	s_lshl_b64 s[20:21], s[94:95], 2
	s_waitcnt lgkmcnt(0)
	s_add_u32 s3, s4, s20
	s_addc_u32 s5, s5, s21
	s_lshl_b32 s4, s94, 1
	s_add_u32 s18, s18, s4
	v_mov_b32_e32 v20, v226
	s_addc_u32 s19, s19, 0
	s_lshl_b32 s4, s2, 2
	v_ashrrev_i32_e32 v18, 5, v20
	v_add_u32_e32 v21, 0x200, v20
	s_add_u32 s4, s3, s4
	v_lshlrev_b32_e32 v0, 4, v20
	v_add_u32_e32 v2, s22, v18
	v_ashrrev_i32_e32 v22, 5, v21
	v_add_u32_e32 v10, 0x400, v20
	s_addc_u32 s5, s5, 0
	v_and_b32_e32 v0, 0x1f0, v0
	v_ashrrev_i32_e32 v3, 31, v2
	v_add_u32_e32 v6, s22, v22
	v_ashrrev_i32_e32 v23, 5, v10
	v_lshl_add_u64 v[14:15], s[4:5], 0, v[0:1]
	v_lshlrev_b64 v[2:3], 12, v[2:3]
	v_ashrrev_i32_e32 v7, 31, v6
	v_add_u32_e32 v10, s22, v23
	v_lshl_add_u64 v[2:3], v[14:15], 0, v[2:3]
	v_lshlrev_b64 v[6:7], 12, v[6:7]
	v_ashrrev_i32_e32 v11, 31, v10
	v_add_u32_e32 v16, 0x600, v20
	s_waitcnt vmcnt(0)
	s_barrier
	global_load_dwordx4 v[2:5], v[2:3], off
	v_lshl_add_u64 v[6:7], v[14:15], 0, v[6:7]
	v_lshlrev_b64 v[10:11], 12, v[10:11]
	v_ashrrev_i32_e32 v24, 5, v16
	global_load_dwordx4 v[6:9], v[6:7], off
	v_lshl_add_u64 v[10:11], v[14:15], 0, v[10:11]
	v_add_u32_e32 v16, s22, v24
	global_load_dwordx4 v[10:13], v[10:11], off
	v_ashrrev_i32_e32 v17, 31, v16
	v_lshlrev_b64 v[16:17], 12, v[16:17]
	v_lshl_add_u64 v[14:15], v[14:15], 0, v[16:17]
	global_load_dwordx4 v[14:17], v[14:15], off
	s_movk_i32 s3, 0x204
	v_mad_u64_u32 v[18:19], s[4:5], v18, s3, v[0:1]
	s_waitcnt vmcnt(3)
	ds_write2_b32 v18, v2, v3 offset1:1
	ds_write2_b32 v18, v4, v5 offset0:2 offset1:3
	v_mad_u64_u32 v[2:3], s[4:5], v22, s3, v[0:1]
	s_waitcnt vmcnt(2)
	ds_write2_b32 v2, v6, v7 offset1:1
	ds_write2_b32 v2, v8, v9 offset0:2 offset1:3
	v_mad_u64_u32 v[2:3], s[4:5], v23, s3, v[0:1]
	s_waitcnt vmcnt(1)
	ds_write2_b32 v2, v10, v11 offset1:1
	ds_write2_b32 v2, v12, v13 offset0:2 offset1:3
	v_mad_u64_u32 v[2:3], s[4:5], v24, s3, v[0:1]
	v_lshlrev_b32_e32 v0, 3, v20
	s_lshl_b32 s3, s22, 1
	v_and_b32_e32 v4, 56, v0
	s_add_u32 s4, s18, s3
	s_addc_u32 s5, s19, 0
	v_lshlrev_b32_e32 v0, 1, v4
	s_waitcnt vmcnt(0)
	ds_write2_b32 v2, v14, v15 offset1:1
	ds_write2_b32 v2, v16, v17 offset0:2 offset1:3
	v_lshl_add_u64 v[2:3], s[4:5], 0, v[0:1]
	v_mul_u32_u24_e32 v0, 0x204, v4
	v_ashrrev_i32_e32 v12, 3, v20
	v_lshl_add_u32 v10, v12, 2, v0
	v_add_u32_e32 v6, 0x400, v10
	v_add_u32_e32 v8, 0x800, v10
	s_waitcnt lgkmcnt(0)
	s_barrier
	ds_read2_b32 v[4:5], v10 offset1:129
	ds_read2_b32 v[6:7], v6 offset0:2 offset1:131
	ds_read2_b32 v[8:9], v8 offset0:4 offset1:133
	v_add_u32_e32 v10, 0xc00, v10
	ds_read2_b32 v[10:11], v10 offset0:6 offset1:135
	s_waitcnt lgkmcnt(3)
	v_cvt_pk_bf16_f32 v4, v4, v5
	s_waitcnt lgkmcnt(2)
	v_cvt_pk_bf16_f32 v5, v6, v7
	s_waitcnt lgkmcnt(1)
	v_cvt_pk_bf16_f32 v6, v8, v9
	v_add_u32_e32 v8, s2, v12
	v_ashrrev_i32_e32 v9, 31, v8
	v_lshlrev_b64 v[8:9], 10, v[8:9]
	v_ashrrev_i32_e32 v12, 3, v21
	s_waitcnt lgkmcnt(0)
	v_cvt_pk_bf16_f32 v7, v10, v11
	v_lshl_add_u64 v[8:9], v[2:3], 0, v[8:9]
	v_lshl_add_u32 v0, v12, 2, v0
	global_store_dwordx4 v[8:9], v[4:7], off sc0 sc1
	v_add_u32_e32 v8, 0x800, v0
	ds_read2_b32 v[4:5], v0 offset1:129
	v_add_u32_e32 v6, 0x400, v0
	ds_read2_b32 v[6:7], v6 offset0:2 offset1:131
	ds_read2_b32 v[8:9], v8 offset0:4 offset1:133
	v_add_u32_e32 v0, 0xc00, v0
	ds_read2_b32 v[10:11], v0 offset0:6 offset1:135
	s_waitcnt lgkmcnt(3)
	v_cvt_pk_bf16_f32 v4, v4, v5
	s_waitcnt lgkmcnt(2)
	v_cvt_pk_bf16_f32 v5, v6, v7
	s_waitcnt lgkmcnt(1)
	v_cvt_pk_bf16_f32 v6, v8, v9
	v_add_u32_e32 v8, s2, v12
	v_ashrrev_i32_e32 v9, 31, v8
	v_lshlrev_b64 v[8:9], 10, v[8:9]
	s_waitcnt lgkmcnt(0)
	v_cvt_pk_bf16_f32 v7, v10, v11
	v_lshl_add_u64 v[2:3], v[2:3], 0, v[8:9]
	global_store_dwordx4 v[2:3], v[4:7], off sc0 sc1

.LBB0_481:
	s_andn2_b64 vcc, exec, s[4:5]
	s_cbranch_vccnz .LBB0_483
	s_add_i32 s4, s28, 0xfffff3fe
	s_mul_i32 s5, s4, 0xaaab
	s_lshr_b32 s5, s5, 24
	s_waitcnt lgkmcnt(0)
	s_mul_i32 s18, s5, 0xfe80
	s_add_i32 s4, s18, s4
	s_sext_i32_i16 s18, s4
	s_mulk_i32 s18, 0x2aab
	s_lshr_b32 s19, s18, 31
	s_ashr_i32 s18, s18, 18
	s_add_i32 s19, s18, s19
	s_load_dwordx2 s[2:3], s[0:1], 0xc0
	s_load_dwordx2 s[20:21], s[0:1], 0xf8
	s_lshl_b32 s18, s19, 6
	s_mul_i32 s19, s19, 24
	s_sub_i32 s4, s4, s19
	s_sext_i32_i16 s4, s4
	s_mul_i32 s5, s5, 0x300000
	s_lshl_b32 s4, s4, 7
	s_lshl_b32 s19, s5, 2
	s_waitcnt lgkmcnt(0)
	s_add_u32 s19, s2, s19
	s_addc_u32 s22, s3, 0
	s_lshl_b32 s2, s5, 1
	s_add_u32 s20, s20, s2
	s_addc_u32 s21, s21, 0
	s_ashr_i32 s5, s4, 31
	v_mov_b32_e32 v20, v226
	s_lshl_b64 s[2:3], s[4:5], 2
	s_add_u32 s2, s19, s2
	v_lshlrev_b32_e32 v0, 4, v20
	s_addc_u32 s3, s22, s3
	v_and_b32_e32 v0, 0x1f0, v0
	v_ashrrev_i32_e32 v18, 5, v20
	v_add_u32_e32 v21, 0x200, v20
	v_lshl_add_u64 v[14:15], s[2:3], 0, v[0:1]
	v_add_u32_e32 v2, s18, v18
	v_ashrrev_i32_e32 v22, 5, v21
	v_add_u32_e32 v10, 0x400, v20
	v_mad_i64_i32 v[2:3], s[2:3], v2, s87, v[14:15]
	v_add_u32_e32 v6, s18, v22
	v_ashrrev_i32_e32 v23, 5, v10
	s_waitcnt vmcnt(0)
	s_barrier
	global_load_dwordx4 v[2:5], v[2:3], off
	v_mad_i64_i32 v[6:7], s[2:3], v6, s87, v[14:15]
	v_add_u32_e32 v10, s18, v23
	global_load_dwordx4 v[6:9], v[6:7], off
	v_mad_i64_i32 v[10:11], s[2:3], v10, s87, v[14:15]
	global_load_dwordx4 v[10:13], v[10:11], off
	v_add_u32_e32 v16, 0x600, v20
	v_ashrrev_i32_e32 v24, 5, v16
	v_add_u32_e32 v16, s18, v24
	v_mad_i64_i32 v[14:15], s[2:3], v16, s87, v[14:15]
	global_load_dwordx4 v[14:17], v[14:15], off
	s_movk_i32 s5, 0x204
	v_mad_u64_u32 v[18:19], s[2:3], v18, s5, v[0:1]
	s_ashr_i32 s19, s18, 31
	s_waitcnt vmcnt(3)
	ds_write2_b32 v18, v2, v3 offset1:1
	ds_write2_b32 v18, v4, v5 offset0:2 offset1:3
	v_mad_u64_u32 v[2:3], s[2:3], v22, s5, v[0:1]
	s_waitcnt vmcnt(2)
	ds_write2_b32 v2, v6, v7 offset1:1
	ds_write2_b32 v2, v8, v9 offset0:2 offset1:3
	v_mad_u64_u32 v[2:3], s[2:3], v23, s5, v[0:1]
	s_waitcnt vmcnt(1)
	ds_write2_b32 v2, v10, v11 offset1:1
	ds_write2_b32 v2, v12, v13 offset0:2 offset1:3
	v_mad_u64_u32 v[2:3], s[2:3], v24, s5, v[0:1]
	v_lshlrev_b32_e32 v0, 3, v20
	s_lshl_b64 s[2:3], s[18:19], 1
	v_and_b32_e32 v4, 56, v0
	s_add_u32 s2, s20, s2
	s_addc_u32 s3, s21, s3
	v_lshlrev_b32_e32 v0, 1, v4
	s_waitcnt vmcnt(0)
	ds_write2_b32 v2, v14, v15 offset1:1
	ds_write2_b32 v2, v16, v17 offset0:2 offset1:3
	v_lshl_add_u64 v[2:3], s[2:3], 0, v[0:1]
	v_mul_u32_u24_e32 v0, 0x204, v4
	v_ashrrev_i32_e32 v12, 3, v20
	v_lshl_add_u32 v10, v12, 2, v0
	v_add_u32_e32 v6, 0x400, v10
	v_add_u32_e32 v8, 0x800, v10
	s_waitcnt lgkmcnt(0)
	s_barrier
	ds_read2_b32 v[4:5], v10 offset1:129
	ds_read2_b32 v[6:7], v6 offset0:2 offset1:131
	ds_read2_b32 v[8:9], v8 offset0:4 offset1:133
	v_add_u32_e32 v10, 0xc00, v10
	ds_read2_b32 v[10:11], v10 offset0:6 offset1:135
	s_waitcnt lgkmcnt(3)
	v_cvt_pk_bf16_f32 v4, v4, v5
	s_waitcnt lgkmcnt(2)
	v_cvt_pk_bf16_f32 v5, v6, v7
	s_waitcnt lgkmcnt(1)
	v_cvt_pk_bf16_f32 v6, v8, v9
	v_add_u32_e32 v8, s4, v12
	v_ashrrev_i32_e32 v9, 31, v8
	v_lshlrev_b64 v[8:9], 11, v[8:9]
	v_ashrrev_i32_e32 v12, 3, v21
	s_waitcnt lgkmcnt(0)
	v_cvt_pk_bf16_f32 v7, v10, v11
	v_lshl_add_u64 v[8:9], v[2:3], 0, v[8:9]
	v_lshl_add_u32 v0, v12, 2, v0
	global_store_dwordx4 v[8:9], v[4:7], off sc0 sc1
	v_add_u32_e32 v8, 0x800, v0
	ds_read2_b32 v[4:5], v0 offset1:129
	v_add_u32_e32 v6, 0x400, v0
	ds_read2_b32 v[6:7], v6 offset0:2 offset1:131
	ds_read2_b32 v[8:9], v8 offset0:4 offset1:133
	v_add_u32_e32 v0, 0xc00, v0
	ds_read2_b32 v[10:11], v0 offset0:6 offset1:135
	s_waitcnt lgkmcnt(3)
	v_cvt_pk_bf16_f32 v4, v4, v5
	s_waitcnt lgkmcnt(2)
	v_cvt_pk_bf16_f32 v5, v6, v7
	s_waitcnt lgkmcnt(1)
	v_cvt_pk_bf16_f32 v6, v8, v9
	v_add_u32_e32 v8, s4, v12
	v_ashrrev_i32_e32 v9, 31, v8
	v_lshlrev_b64 v[8:9], 11, v[8:9]
	s_waitcnt lgkmcnt(0)
	v_cvt_pk_bf16_f32 v7, v10, v11
	v_lshl_add_u64 v[2:3], v[2:3], 0, v[8:9]
	global_store_dwordx4 v[2:3], v[4:7], off sc0 sc1

.LBB0_484:
	s_andn2_b64 vcc, exec, s[4:5]
	s_cbranch_vccnz .LBB0_486
	s_add_i32 s4, s28, 0xfffffefe
	s_mul_i32 s5, s4, 0xba2f
	s_lshr_b32 s5, s5, 25
	s_waitcnt lgkmcnt(0)
	s_mul_i32 s18, s5, 0xfd40
	s_add_i32 s4, s18, s4
	s_sext_i32_i16 s18, s4
	s_mulk_i32 s18, 0xba3
	s_lshr_b32 s19, s18, 31
	s_ashr_i32 s18, s18, 17
	s_add_i32 s19, s18, s19
	s_load_dwordx2 s[2:3], s[0:1], 0x50
	s_load_dwordx2 s[20:21], s[0:1], 0xf0
	s_lshl_b32 s18, s19, 6
	s_mul_i32 s19, s19, 44
	s_sub_i32 s4, s4, s19
	s_sext_i32_i16 s4, s4
	s_mul_i32 s5, s5, 0x580000
	s_lshl_b32 s4, s4, 7
	s_lshl_b32 s19, s5, 2
	s_waitcnt lgkmcnt(0)
	s_add_u32 s19, s2, s19
	s_addc_u32 s22, s3, 0
	s_lshl_b32 s2, s5, 1
	s_add_u32 s20, s20, s2
	s_addc_u32 s21, s21, 0
	s_ashr_i32 s5, s4, 31
	v_mov_b32_e32 v20, v226
	s_lshl_b64 s[2:3], s[4:5], 2
	s_add_u32 s2, s19, s2
	v_lshlrev_b32_e32 v0, 4, v20
	s_addc_u32 s3, s22, s3
	v_and_b32_e32 v0, 0x1f0, v0
	v_ashrrev_i32_e32 v18, 5, v20
	v_add_u32_e32 v21, 0x200, v20
	v_lshl_add_u64 v[14:15], s[2:3], 0, v[0:1]
	v_add_u32_e32 v2, s18, v18
	s_movk_i32 s5, 0x5800
	v_ashrrev_i32_e32 v22, 5, v21
	v_add_u32_e32 v10, 0x400, v20
	v_mad_i64_i32 v[2:3], s[2:3], v2, s5, v[14:15]
	v_add_u32_e32 v6, s18, v22
	v_ashrrev_i32_e32 v23, 5, v10
	s_waitcnt vmcnt(0)
	s_barrier
	global_load_dwordx4 v[2:5], v[2:3], off
	v_mad_i64_i32 v[6:7], s[2:3], v6, s5, v[14:15]
	v_add_u32_e32 v10, s18, v23
	global_load_dwordx4 v[6:9], v[6:7], off
	v_mad_i64_i32 v[10:11], s[2:3], v10, s5, v[14:15]
	global_load_dwordx4 v[10:13], v[10:11], off
	v_add_u32_e32 v16, 0x600, v20
	v_ashrrev_i32_e32 v24, 5, v16
	v_add_u32_e32 v16, s18, v24
	v_mad_i64_i32 v[14:15], s[2:3], v16, s5, v[14:15]
	global_load_dwordx4 v[14:17], v[14:15], off
	s_movk_i32 s5, 0x204
	v_mad_u64_u32 v[18:19], s[2:3], v18, s5, v[0:1]
	s_ashr_i32 s19, s18, 31
	s_waitcnt vmcnt(3)
	ds_write2_b32 v18, v2, v3 offset1:1
	ds_write2_b32 v18, v4, v5 offset0:2 offset1:3
	v_mad_u64_u32 v[2:3], s[2:3], v22, s5, v[0:1]
	s_waitcnt vmcnt(2)
	ds_write2_b32 v2, v6, v7 offset1:1
	ds_write2_b32 v2, v8, v9 offset0:2 offset1:3
	v_mad_u64_u32 v[2:3], s[2:3], v23, s5, v[0:1]
	s_waitcnt vmcnt(1)
	ds_write2_b32 v2, v10, v11 offset1:1
	ds_write2_b32 v2, v12, v13 offset0:2 offset1:3
	v_mad_u64_u32 v[2:3], s[2:3], v24, s5, v[0:1]
	v_lshlrev_b32_e32 v0, 3, v20
	s_lshl_b64 s[2:3], s[18:19], 1
	v_and_b32_e32 v4, 56, v0
	s_add_u32 s2, s20, s2
	s_addc_u32 s3, s21, s3
	v_lshlrev_b32_e32 v0, 1, v4
	s_waitcnt vmcnt(0)
	ds_write2_b32 v2, v14, v15 offset1:1
	ds_write2_b32 v2, v16, v17 offset0:2 offset1:3
	v_lshl_add_u64 v[2:3], s[2:3], 0, v[0:1]
	v_mul_u32_u24_e32 v0, 0x204, v4
	v_ashrrev_i32_e32 v12, 3, v20
	v_lshl_add_u32 v10, v12, 2, v0
	v_add_u32_e32 v6, 0x400, v10
	v_add_u32_e32 v8, 0x800, v10
	s_waitcnt lgkmcnt(0)
	s_barrier
	ds_read2_b32 v[4:5], v10 offset1:129
	ds_read2_b32 v[6:7], v6 offset0:2 offset1:131
	ds_read2_b32 v[8:9], v8 offset0:4 offset1:133
	v_add_u32_e32 v10, 0xc00, v10
	ds_read2_b32 v[10:11], v10 offset0:6 offset1:135
	s_waitcnt lgkmcnt(3)
	v_cvt_pk_bf16_f32 v4, v4, v5
	s_waitcnt lgkmcnt(2)
	v_cvt_pk_bf16_f32 v5, v6, v7
	s_waitcnt lgkmcnt(1)
	v_cvt_pk_bf16_f32 v6, v8, v9
	v_add_u32_e32 v8, s4, v12
	v_ashrrev_i32_e32 v9, 31, v8
	v_lshlrev_b64 v[8:9], 11, v[8:9]
	v_ashrrev_i32_e32 v12, 3, v21
	s_waitcnt lgkmcnt(0)
	v_cvt_pk_bf16_f32 v7, v10, v11
	v_lshl_add_u64 v[8:9], v[2:3], 0, v[8:9]
	v_lshl_add_u32 v0, v12, 2, v0
	global_store_dwordx4 v[8:9], v[4:7], off sc0 sc1
	v_add_u32_e32 v8, 0x800, v0
	ds_read2_b32 v[4:5], v0 offset1:129
	v_add_u32_e32 v6, 0x400, v0
	ds_read2_b32 v[6:7], v6 offset0:2 offset1:131
	ds_read2_b32 v[8:9], v8 offset0:4 offset1:133
	v_add_u32_e32 v0, 0xc00, v0
	ds_read2_b32 v[10:11], v0 offset0:6 offset1:135
	s_waitcnt lgkmcnt(3)
	v_cvt_pk_bf16_f32 v4, v4, v5
	s_waitcnt lgkmcnt(2)
	v_cvt_pk_bf16_f32 v5, v6, v7
	s_waitcnt lgkmcnt(1)
	v_cvt_pk_bf16_f32 v6, v8, v9
	v_add_u32_e32 v8, s4, v12
	v_ashrrev_i32_e32 v9, 31, v8
	v_lshlrev_b64 v[8:9], 11, v[8:9]
	s_waitcnt lgkmcnt(0)
	v_cvt_pk_bf16_f32 v7, v10, v11
	v_lshl_add_u64 v[2:3], v[2:3], 0, v[8:9]
	global_store_dwordx4 v[2:3], v[4:7], off sc0 sc1

.LBB0_487:
	s_andn2_b64 vcc, exec, s[4:5]
	s_cbranch_vccnz .LBB0_489
	s_load_dwordx2 s[2:3], s[0:1], 0x68
	s_add_i32 s94, s28, 0xffffff3e
	s_lshl_b64 s[4:5], s[94:95], 14
	v_mov_b32_e32 v0, v226
	s_waitcnt lgkmcnt(0)
	s_add_u32 s2, s2, s4
	s_addc_u32 s3, s3, s5
	s_load_dwordx2 s[4:5], s[0:1], 0x120
	s_lshl_b64 s[18:19], s[94:95], 13
	v_lshlrev_b32_e32 v10, 3, v0
	v_ashrrev_i32_e32 v11, 31, v10
	v_lshl_add_u64 v[6:7], v[10:11], 2, s[2:3]
	global_load_dwordx4 v[2:5], v[6:7], off offset:16
	s_nop 0
	global_load_dwordx4 v[6:9], v[6:7], off
	s_waitcnt lgkmcnt(0)
	s_add_u32 s4, s4, s18
	s_addc_u32 s5, s5, s19
	s_waitcnt vmcnt(0)
	v_cvt_pk_bf16_f32 v6, v6, v7
	v_cvt_pk_bf16_f32 v7, v8, v9
	v_cvt_pk_bf16_f32 v8, v2, v3
	v_cvt_pk_bf16_f32 v9, v4, v5
	v_lshl_add_u64 v[2:3], v[10:11], 1, s[4:5]
	global_store_dwordx4 v[2:3], v[6:9], off sc0 sc1

.LBB0_493:
	v_lshl_add_u64 v[16:17], v[6:7], 0, s[18:19]
	v_lshl_add_u64 v[24:25], v[10:11], 0, s[18:19]
	v_lshl_add_u64 v[32:33], v[8:9], 0, s[18:19]
	v_lshl_add_u64 v[36:37], v[4:5], 0, s[18:19]
	global_load_dwordx4 v[12:15], v[16:17], off offset:16
	s_nop 0
	global_load_dwordx4 v[16:19], v[16:17], off
	s_nop 0
	global_load_dwordx4 v[20:23], v[24:25], off offset:16
	s_nop 0
	global_load_dwordx4 v[24:27], v[24:25], off
	s_nop 0
	global_load_dwordx4 v[28:31], v[32:33], off offset:16
	s_nop 0
	global_load_dwordx4 v[32:35], v[32:33], off
	s_nop 0
	global_load_dwordx4 v[58:61], v[36:37], off offset:16
	global_load_dwordx4 v[62:65], v[36:37], off
	s_add_u32 s18, s18, 32
	s_addc_u32 s19, s19, 0
	s_cmpk_eq_i32 s18, 0x100
	s_waitcnt vmcnt(0)
	v_mov_b32_e32 v37, v16
	v_mov_b32_e32 v55, v24
	v_mov_b32_e32 v36, v32
	v_mov_b32_e32 v54, v62
	v_pk_fma_f32 v[2:3], v[36:37], v[54:55], v[2:3]
	v_mov_b32_e32 v16, v33
	v_mov_b32_e32 v24, v63
	v_pk_fma_f32 v[2:3], v[16:17], v[24:25], v[2:3]
	v_mov_b32_e32 v16, v34
	v_mov_b32_e32 v17, v18
	v_mov_b32_e32 v24, v64
	v_mov_b32_e32 v25, v26
	v_pk_fma_f32 v[2:3], v[16:17], v[24:25], v[2:3]
	v_mov_b32_e32 v18, v35
	v_mov_b32_e32 v26, v65
	v_pk_fma_f32 v[2:3], v[18:19], v[26:27], v[2:3]
	v_mov_b32_e32 v16, v28
	v_mov_b32_e32 v17, v12
	v_mov_b32_e32 v18, v58
	v_mov_b32_e32 v19, v20
	v_pk_fma_f32 v[2:3], v[16:17], v[18:19], v[2:3]
	v_mov_b32_e32 v12, v29
	v_mov_b32_e32 v20, v59
	v_pk_fma_f32 v[2:3], v[12:13], v[20:21], v[2:3]
	v_mov_b32_e32 v12, v30
	v_mov_b32_e32 v13, v14
	v_mov_b32_e32 v16, v60
	v_mov_b32_e32 v17, v22
	v_pk_fma_f32 v[2:3], v[12:13], v[16:17], v[2:3]
	v_mov_b32_e32 v14, v31
	v_mov_b32_e32 v22, v61
	v_pk_fma_f32 v[2:3], v[14:15], v[22:23], v[2:3]
	s_cbranch_scc0 .LBB0_493
	v_mul_f32_e32 v0, 0x3fb8aa3b, v3
	v_rndne_f32_e32 v4, v0
	s_mov_b32 s2, 0x3fb8aa3b
	v_sub_f32_e32 v5, v0, v4
	v_fma_f32 v0, v3, s2, -v0
	v_fmac_f32_e32 v0, 0x32a5705f, v3
	v_add_f32_e32 v0, v5, v0
	v_exp_f32_e32 v0, v0
	v_cvt_i32_f32_e32 v4, v4
	s_mov_b32 s3, 0xc2ce8ed0
	v_cmp_ngt_f32_e32 vcc, s3, v3
	s_mov_b32 s18, 0x42b17218
	v_ldexp_f32 v0, v0, v4
	v_cndmask_b32_e32 v0, 0, v0, vcc
	v_cmp_nlt_f32_e32 vcc, s18, v3
	v_mul_f32_e32 v3, 0x3fb8aa3b, v2
	v_rndne_f32_e32 v4, v3
	v_sub_f32_e32 v5, v3, v4
	v_fma_f32 v3, v2, s2, -v3
	v_fmac_f32_e32 v3, 0x32a5705f, v2
	v_add_f32_e32 v3, v5, v3
	v_exp_f32_e32 v3, v3
	v_cvt_i32_f32_e32 v4, v4
	v_cndmask_b32_e32 v0, v230, v0, vcc
	v_cmp_ngt_f32_e32 vcc, s3, v2
	s_load_dwordx2 s[2:3], s[0:1], 0x198
	v_ldexp_f32 v3, v3, v4
	v_cndmask_b32_e32 v3, 0, v3, vcc
	v_cmp_nlt_f32_e32 vcc, s18, v2
	s_nop 1
	v_cndmask_b32_e32 v2, v230, v3, vcc
	v_sub_f32_e32 v0, v0, v2
	global_load_dword v2, v[40:41], off offset:424
	s_waitcnt vmcnt(0)
	v_add_f32_e32 v0, v0, v2
	s_waitcnt lgkmcnt(0)
	v_lshl_add_u64 v[2:3], v[38:39], 2, s[2:3]
	global_store_dword v[2:3], v0, off sc0 sc1

.LBB0_502:
	v_ashrrev_i32_e32 v4, 4, v2
	v_ashrrev_i32_e32 v5, 4, v3
	v_cvt_f32_i32_e32 v5, v5
	v_cvt_f32_i32_e32 v4, v4
	v_lshlrev_b32_e32 v6, 1, v3
	v_ashrrev_i32_e32 v7, 31, v6
	v_lshl_add_u64 v[6:7], v[6:7], 2, s[18:19]
	v_pk_mul_f32 v[4:5], v[42:43], v[4:5]
	v_add_u32_e32 v0, -2, v0
	v_mul_f32_e32 v10, 0.15915494, v4
	v_mul_f32_e32 v8, 0.15915494, v5
	v_cos_f32_e32 v11, v10
	v_cos_f32_e32 v9, v8
	v_lshlrev_b32_e32 v4, 1, v2
	v_ashrrev_i32_e32 v5, 31, v4
	v_lshl_add_u64 v[4:5], v[4:5], 2, s[18:19]
	global_store_dword v[4:5], v11, off sc0 sc1
	global_store_dword v[6:7], v9, off sc0 sc1
	v_sin_f32_e32 v9, v10
	v_sin_f32_e32 v8, v8
	v_cmp_eq_u32_e32 vcc, 0, v0
	v_add_u32_e32 v3, 0x400, v3
	v_add_u32_e32 v2, 0x400, v2
	s_or_b64 s[24:25], vcc, s[24:25]
	global_store_dword v[4:5], v9, off offset:4 sc0 sc1
	global_store_dword v[6:7], v8, off offset:4 sc0 sc1
	s_andn2_b64 exec, exec, s[24:25]
	s_cbranch_execnz .LBB0_502
	s_or_b64 exec, exec, s[24:25]
	s_mov_b64 s[24:25], 0
	s_and_saveexec_b64 s[26:27], s[14:15]
	s_mov_b64 s[24:25], exec
	v_lshlrev_b32_e32 v2, 1, v56
	s_or_b64 exec, exec, s[26:27]
	s_orn2_b64 s[24:25], s[24:25], exec
	v_mov_b32_e32 v0, v56

.LBB0_509:
	v_ashrrev_i32_e32 v4, 4, v0
	v_cvt_f32_i32_e32 v6, v4
	s_movk_i32 s2, 0x1ff
	v_add_u32_e32 v8, 0x200, v0
	v_cmp_lt_i32_e32 vcc, s2, v0
	v_mul_f32_e32 v0, v42, v6
	v_mul_f32_e32 v0, 0.15915494, v0
	v_cos_f32_e32 v6, v0
	v_sin_f32_e32 v7, v0
	v_ashrrev_i32_e32 v3, 31, v2
	s_waitcnt lgkmcnt(0)
	v_lshl_add_u64 v[4:5], v[2:3], 2, s[18:19]
	v_add_u32_e32 v2, 0x400, v2
	s_or_b64 s[20:21], vcc, s[20:21]
	v_mov_b32_e32 v0, v8
	global_store_dwordx2 v[4:5], v[6:7], off sc0 sc1
	s_andn2_b64 exec, exec, s[20:21]
	s_cbranch_execnz .LBB0_509

.LBB0_527:
	v_add_u32_e32 v12, s3, v7
	ds_read2st64_b32 v[10:11], v12 offset1:9
	s_addk_i32 s3, 0x4800
	s_cmp_eq_u32 s3, 0x1b000
	s_waitcnt lgkmcnt(0)
	v_add_f32_e32 v8, v8, v10
	v_add_f32_e32 v10, v8, v11
	ds_read2st64_b32 v[8:9], v12 offset0:18 offset1:27
	s_waitcnt lgkmcnt(0)
	v_add_f32_e32 v8, v10, v8
	v_add_f32_e32 v10, v8, v9
	ds_read2st64_b32 v[8:9], v12 offset0:36 offset1:45
	s_waitcnt lgkmcnt(0)
	v_add_f32_e32 v8, v10, v8
	v_add_f32_e32 v10, v8, v9
	ds_read2st64_b32 v[8:9], v12 offset0:54 offset1:63
	s_waitcnt lgkmcnt(0)
	v_add_f32_e32 v8, v10, v8
	v_add_f32_e32 v8, v8, v9
	s_cbranch_scc0 .LBB0_527
	global_load_dword v7, v[2:3], off
	v_add_u32_e32 v6, s2, v6
	v_cmp_lt_i32_e32 vcc, 63, v57
	s_or_b64 s[4:5], vcc, s[4:5]
	s_waitcnt vmcnt(0)
	v_add_f32_e32 v8, v8, v7
	v_mad_i64_i32 v[6:7], s[18:19], v6, s87, v[4:5]
	global_store_dword v[6:7], v8, off sc0 sc1
	v_add_u32_e32 v6, 0x200, v57
	v_mov_b32_e32 v57, v6
	s_andn2_b64 exec, exec, s[4:5]
	s_cbranch_execnz .LBB0_526
	s_branch .LBB0_459
